# v3 + removed the redundant s_waitcnt lgkmcnt(0) that follows each compute-segment barrier in the K-loops
# speedup vs baseline: 1.0123x; 1.0031x over previous
; #define PG8_STAGE(bufoff, gbase, voff) do { _Pragma("unroll") for (int _i = 0; _i < 2; ++_i) \
;         __builtin_amdgcn_global_load_lds((const unsigned*)((const char*)(gbase) + (voff)[_i]), (PG8_LAS unsigned*)(lds + (bufoff) + ldsw + _i * 8192), 16, 0, 0); } while (0)
; #define PG8_LDA(dst, b, h) do { _Pragma("unroll") for (int m = 0; m < 4; ++m) _Pragma("unroll") for (int k = 0; k < 2; ++k) dst[m][k] = *(const PG8_LAS bf16x8*)(lds + PG8_SA(b, h) + aoff + m * 2048 + k * 1024); } while (0)
; #define PG8_LDB(dst, b, h) do { _Pragma("unroll") for (int n = 0; n < 2; ++n) _Pragma("unroll") for (int k = 0; k < 2; ++k) dst[n][k] = *(const PG8_LAS bf16x8*)(lds + PG8_SB(b, h) + boff + n * 2048 + k * 1024); } while (0)
; #define PG8_MMA(ai, bj, At, Bt) do { __builtin_amdgcn_s_setprio(1); _Pragma("unroll") for (int m = 0; m < 4; ++m) _Pragma("unroll") for (int n = 0; n < 2; ++n) _Pragma("unroll") for (int k = 0; k < 2; ++k) \
;         acc[ai][bj][m][n] = __builtin_amdgcn_mfma_f32_16x16x32_f16(Bt[n][k], At[m][k], acc[ai][bj][m][n], 0, 0, 0); __builtin_amdgcn_s_setprio(0); } while (0)
; #define PG8_WAIT_V(n) asm volatile("s_waitcnt vmcnt(" #n ")" ::: "memory")
; #define PG8_WAIT_L(n) asm volatile("s_waitcnt lgkmcnt(" #n ")" ::: "memory")
; #define PG8_BAR __builtin_amdgcn_s_barrier()
; #define PG8_SCHED __builtin_amdgcn_sched_barrier(0)
; template <class Epi, class Sched, bool ALIGN_EPI = false, bool SP2 = false>
; __device__ __forceinline__ void gemm_phase(PG8_LAS unsigned char* lds, const Gemm g, const Sched& S, const Epi& E) {
;     ...
;             PG8_LDB(B0, 0, 0); PG8_LDB(B1, 0, 1); PG8_SCHED; PG8_LDA(At, 0, 0); PG8_STAGE(PG8_SA(1, 1), a1 + hstep, voffA);
;             PG8_WAIT_V(8); PG8_WAIT_L(0); PG8_BAR; PG8_MMA(0, 0, At, B0); PG8_MMA(0, 1, At, B1); PG8_BAR; PG8_SCHED;
;             PG8_LDA(At, 0, 1); PG8_STAGE(PG8_SB(0, 0), b2, voffB); PG8_STAGE(PG8_SB(0, 1), b2 + hstep, voffB); PG8_STAGE(PG8_SA(0, 0), a2, voffA);
;             PG8_WAIT_V(8); PG8_WAIT_L(0); PG8_BAR; PG8_MMA(1, 0, At, B0); PG8_MMA(1, 1, At, B1); PG8_BAR; PG8_SCHED;
.LBB0_146:
	ds_read_b128 v[150:153], v147
	ds_read_b128 v[154:157], v147 offset:1024
	ds_read_b128 v[158:161], v147 offset:2048
	ds_read_b128 v[162:165], v147 offset:3072
	ds_read_b128 v[166:169], v148
	ds_read_b128 v[170:173], v148 offset:1024
	ds_read_b128 v[174:177], v148 offset:2048
	ds_read_b128 v[178:181], v148 offset:3072
	s_add_u32 s24, s22, 0xfff80080
	s_addc_u32 s25, s23, -1
	s_cmp_eq_u32 s62, 28
	s_cselect_b32 s27, s17, s25
	s_cselect_b32 s26, s54, s24
	s_cselect_b32 s25, s15, s61
	s_cselect_b32 s24, s55, s60
	s_add_i32 m0, s13, 0xc000
	ds_read_b128 v[182:185], v149
	ds_read_b128 v[186:189], v149 offset:1024
	ds_read_b128 v[190:193], v149 offset:2048
	ds_read_b128 v[194:197], v149 offset:3072
	ds_read_b128 v[198:201], v149 offset:4096
	ds_read_b128 v[206:209], v149 offset:5120
	ds_read_b128 v[210:213], v149 offset:6144
	ds_read_b128 v[214:217], v149 offset:7168
	global_load_lds_dwordx4 v138, s[22:23]
	s_add_i32 m0, s13, 0xe000
	s_nop 0
	global_load_lds_dwordx4 v136, s[22:23]
	s_waitcnt vmcnt(8)
	s_waitcnt lgkmcnt(0)
	s_barrier
	v_mfma_f32_16x16x32_f16 v[120:123], v[158:161], v[182:185], v[120:123]
	v_mfma_f32_16x16x32_f16 v[124:127], v[150:153], v[182:185], v[124:127]
	v_mfma_f32_16x16x32_f16 v[112:115], v[158:161], v[190:193], v[112:115]
	v_mfma_f32_16x16x32_f16 v[116:119], v[150:153], v[190:193], v[116:119]
	v_mfma_f32_16x16x32_f16 v[96:99], v[158:161], v[198:201], v[96:99]
	v_mfma_f32_16x16x32_f16 v[100:103], v[150:153], v[198:201], v[100:103]
	v_mfma_f32_16x16x32_f16 v[80:83], v[158:161], v[210:213], v[80:83]
	v_mfma_f32_16x16x32_f16 v[84:87], v[150:153], v[210:213], v[84:87]
	v_mfma_f32_16x16x32_f16 v[120:123], v[162:165], v[186:189], v[120:123]
	v_mfma_f32_16x16x32_f16 v[124:127], v[154:157], v[186:189], v[124:127]
	v_mfma_f32_16x16x32_f16 v[112:115], v[162:165], v[194:197], v[112:115]
	v_mfma_f32_16x16x32_f16 v[116:119], v[154:157], v[194:197], v[116:119]
	v_mfma_f32_16x16x32_f16 v[96:99], v[162:165], v[206:209], v[96:99]
	v_mfma_f32_16x16x32_f16 v[100:103], v[154:157], v[206:209], v[100:103]
	v_mfma_f32_16x16x32_f16 v[80:83], v[162:165], v[214:217], v[80:83]
	v_mfma_f32_16x16x32_f16 v[84:87], v[154:157], v[214:217], v[84:87]
	v_mfma_f32_16x16x32_f16 v[104:107], v[174:177], v[182:185], v[104:107]
	v_mfma_f32_16x16x32_f16 v[108:111], v[166:169], v[182:185], v[108:111]
	v_mfma_f32_16x16x32_f16 v[88:91], v[174:177], v[190:193], v[88:91]
	v_mfma_f32_16x16x32_f16 v[92:95], v[166:169], v[190:193], v[92:95]
	v_mfma_f32_16x16x32_f16 v[72:75], v[174:177], v[198:201], v[72:75]
	v_mfma_f32_16x16x32_f16 v[76:79], v[166:169], v[198:201], v[76:79]
	v_mfma_f32_16x16x32_f16 v[64:67], v[174:177], v[210:213], v[64:67]
	v_mfma_f32_16x16x32_f16 v[68:71], v[166:169], v[210:213], v[68:71]
	v_mfma_f32_16x16x32_f16 v[104:107], v[178:181], v[186:189], v[104:107]
	v_mfma_f32_16x16x32_f16 v[108:111], v[170:173], v[186:189], v[108:111]
	v_mfma_f32_16x16x32_f16 v[88:91], v[178:181], v[194:197], v[88:91]
	v_mfma_f32_16x16x32_f16 v[92:95], v[170:173], v[194:197], v[92:95]
	v_mfma_f32_16x16x32_f16 v[72:75], v[178:181], v[206:209], v[72:75]
	v_mfma_f32_16x16x32_f16 v[76:79], v[170:173], v[206:209], v[76:79]
	v_mfma_f32_16x16x32_f16 v[64:67], v[178:181], v[214:217], v[64:67]
	v_mfma_f32_16x16x32_f16 v[68:71], v[170:173], v[214:217], v[68:71]
	s_barrier
	s_add_i32 s63, s44, s34
	s_add_u32 s98, s24, s8
	s_addc_u32 s99, s25, s9
	s_mov_b32 m0, s63
	ds_read_b128 v[182:185], v149 offset:16384
	ds_read_b128 v[186:189], v149 offset:17408
	ds_read_b128 v[190:193], v149 offset:18432
	ds_read_b128 v[194:197], v149 offset:19456
	ds_read_b128 v[198:201], v149 offset:20480
	ds_read_b128 v[206:209], v149 offset:21504
	ds_read_b128 v[210:213], v149 offset:22528
	ds_read_b128 v[214:217], v149 offset:23552
	global_load_lds_dwordx4 v132, s[24:25]
	s_add_i32 m0, s63, 0x2000
	s_add_u32 s66, s24, 0x80000
	s_addc_u32 s67, s25, 0
	s_add_i32 s63, s45, s34
	global_load_lds_dwordx4 v128, s[24:25]
	s_mov_b32 m0, s63
	s_nop 0
	global_load_lds_dwordx4 v132, s[66:67]
	s_add_i32 m0, s63, 0x2000
	s_nop 0
	global_load_lds_dwordx4 v128, s[66:67]
	s_add_u32 s100, s26, s8
	s_addc_u32 s101, s27, s9
	s_mov_b32 m0, s13
	s_nop 0
	global_load_lds_dwordx4 v134, s[26:27]
	s_mov_b32 m0, s37
	s_nop 0
	global_load_lds_dwordx4 v130, s[26:27]
	s_waitcnt vmcnt(8)
	s_waitcnt lgkmcnt(0)
	s_barrier
	v_mfma_f32_16x16x32_f16 v[56:59], v[158:161], v[182:185], v[56:59]
	v_mfma_f32_16x16x32_f16 v[60:63], v[150:153], v[182:185], v[60:63]
	v_mfma_f32_16x16x32_f16 v[48:51], v[158:161], v[190:193], v[48:51]
	v_mfma_f32_16x16x32_f16 v[52:55], v[150:153], v[190:193], v[52:55]
	v_mfma_f32_16x16x32_f16 v[32:35], v[158:161], v[198:201], v[32:35]
	v_mfma_f32_16x16x32_f16 v[36:39], v[150:153], v[198:201], v[36:39]
	v_mfma_f32_16x16x32_f16 v[16:19], v[158:161], v[210:213], v[16:19]
	v_mfma_f32_16x16x32_f16 v[20:23], v[150:153], v[210:213], v[20:23]
	v_mfma_f32_16x16x32_f16 v[56:59], v[162:165], v[186:189], v[56:59]
	v_mfma_f32_16x16x32_f16 v[60:63], v[154:157], v[186:189], v[60:63]
	v_mfma_f32_16x16x32_f16 v[48:51], v[162:165], v[194:197], v[48:51]
	v_mfma_f32_16x16x32_f16 v[52:55], v[154:157], v[194:197], v[52:55]
	v_mfma_f32_16x16x32_f16 v[32:35], v[162:165], v[206:209], v[32:35]
	v_mfma_f32_16x16x32_f16 v[36:39], v[154:157], v[206:209], v[36:39]
	v_mfma_f32_16x16x32_f16 v[16:19], v[162:165], v[214:217], v[16:19]
	v_mfma_f32_16x16x32_f16 v[20:23], v[154:157], v[214:217], v[20:23]
	v_mfma_f32_16x16x32_f16 v[40:43], v[174:177], v[182:185], v[40:43]
	v_mfma_f32_16x16x32_f16 v[44:47], v[166:169], v[182:185], v[44:47]
	v_mfma_f32_16x16x32_f16 v[24:27], v[174:177], v[190:193], v[24:27]
	v_mfma_f32_16x16x32_f16 v[28:31], v[166:169], v[190:193], v[28:31]
	v_mfma_f32_16x16x32_f16 v[8:11], v[174:177], v[198:201], v[8:11]
	v_mfma_f32_16x16x32_f16 v[12:15], v[166:169], v[198:201], v[12:15]
	v_mfma_f32_16x16x32_f16 v[0:3], v[174:177], v[210:213], v[0:3]
	v_mfma_f32_16x16x32_f16 v[4:7], v[166:169], v[210:213], v[4:7]
	v_mfma_f32_16x16x32_f16 v[40:43], v[178:181], v[186:189], v[40:43]
	v_mfma_f32_16x16x32_f16 v[44:47], v[170:173], v[186:189], v[44:47]
	v_mfma_f32_16x16x32_f16 v[24:27], v[178:181], v[194:197], v[24:27]
	v_mfma_f32_16x16x32_f16 v[28:31], v[170:173], v[194:197], v[28:31]
	v_mfma_f32_16x16x32_f16 v[8:11], v[178:181], v[206:209], v[8:11]
	v_mfma_f32_16x16x32_f16 v[12:15], v[170:173], v[206:209], v[12:15]
	v_mfma_f32_16x16x32_f16 v[0:3], v[178:181], v[214:217], v[0:3]
	v_mfma_f32_16x16x32_f16 v[4:7], v[170:173], v[214:217], v[4:7]
	s_barrier
; #define PG8_STAGE(bufoff, gbase, voff) do { _Pragma("unroll") for (int _i = 0; _i < 2; ++_i) \
;         __builtin_amdgcn_global_load_lds((const unsigned*)((const char*)(gbase) + (voff)[_i]), (PG8_LAS unsigned*)(lds + (bufoff) + ldsw + _i * 8192), 16, 0, 0); } while (0)
; #define PG8_LDA(dst, b, h) do { _Pragma("unroll") for (int m = 0; m < 4; ++m) _Pragma("unroll") for (int k = 0; k < 2; ++k) dst[m][k] = *(const PG8_LAS bf16x8*)(lds + PG8_SA(b, h) + aoff + m * 2048 + k * 1024); } while (0)
; #define PG8_LDB(dst, b, h) do { _Pragma("unroll") for (int n = 0; n < 2; ++n) _Pragma("unroll") for (int k = 0; k < 2; ++k) dst[n][k] = *(const PG8_LAS bf16x8*)(lds + PG8_SB(b, h) + boff + n * 2048 + k * 1024); } while (0)
; #define PG8_MMA(ai, bj, At, Bt) do { __builtin_amdgcn_s_setprio(1); _Pragma("unroll") for (int m = 0; m < 4; ++m) _Pragma("unroll") for (int n = 0; n < 2; ++n) _Pragma("unroll") for (int k = 0; k < 2; ++k) \
;         acc[ai][bj][m][n] = __builtin_amdgcn_mfma_f32_16x16x32_f16(Bt[n][k], At[m][k], acc[ai][bj][m][n], 0, 0, 0); __builtin_amdgcn_s_setprio(0); } while (0)
; #define PG8_WAIT_V(n) asm volatile("s_waitcnt vmcnt(" #n ")" ::: "memory")
; #define PG8_WAIT_L(n) asm volatile("s_waitcnt lgkmcnt(" #n ")" ::: "memory")
; #define PG8_BAR __builtin_amdgcn_s_barrier()
; #define PG8_SCHED __builtin_amdgcn_sched_barrier(0)
; template <class Epi, class Sched, bool ALIGN_EPI = false, bool SP2 = false>
; __device__ __forceinline__ void gemm_phase(PG8_LAS unsigned char* lds, const Gemm g, const Sched& S, const Epi& E) {
;     ...
;             PG8_LDB(B0, 1, 0); PG8_LDB(B1, 1, 1); PG8_SCHED; PG8_LDA(At, 1, 0); PG8_STAGE(PG8_SA(0, 1), a2 + hstep, voffA);
;             PG8_WAIT_V(8); PG8_WAIT_L(0); PG8_BAR; PG8_MMA(0, 0, At, B0); PG8_MMA(0, 1, At, B1); PG8_BAR; PG8_SCHED;
;             PG8_LDA(At, 1, 1); PG8_STAGE(PG8_SB(1, 0), b3, voffB); PG8_STAGE(PG8_SB(1, 1), b3 + hstep, voffB); PG8_STAGE(PG8_SA(1, 0), a3, voffA);
;             PG8_WAIT_V(8); PG8_WAIT_L(0); PG8_BAR; PG8_MMA(1, 0, At, B0); PG8_MMA(1, 1, At, B1); PG8_BAR; PG8_SCHED;
;     ...
;         if constexpr (ALIGN_EPI) { if (wr == 0) PG8_BAR; }
	s_add_i32 s63, 0, 0x18000
	s_add_i32 s66, 0, 0x1c000
	v_add_u32_e32 v162, s63, v145
	v_add_u32_e32 v178, s66, v145
	ds_read_b128 v[150:153], v162
	ds_read_b128 v[154:157], v162 offset:1024
	ds_read_b128 v[158:161], v162 offset:2048
	ds_read_b128 v[162:165], v162 offset:3072
	ds_read_b128 v[166:169], v178
	ds_read_b128 v[170:173], v178 offset:1024
	ds_read_b128 v[174:177], v178 offset:2048
	ds_read_b128 v[178:181], v178 offset:3072
	s_add_u32 s26, s26, 0x80000
	s_addc_u32 s27, s27, 0
	s_mov_b32 m0, s38
	ds_read_b128 v[182:185], v149 offset:32768
	ds_read_b128 v[186:189], v149 offset:33792
	ds_read_b128 v[190:193], v149 offset:34816
	ds_read_b128 v[194:197], v149 offset:35840
	ds_read_b128 v[198:201], v149 offset:36864
	ds_read_b128 v[206:209], v149 offset:37888
	ds_read_b128 v[210:213], v149 offset:38912
	ds_read_b128 v[214:217], v149 offset:39936
	global_load_lds_dwordx4 v134, s[26:27]
	s_mov_b32 m0, s39
	s_nop 0
	global_load_lds_dwordx4 v130, s[26:27]
	s_waitcnt vmcnt(8)
	s_waitcnt lgkmcnt(0)
	s_barrier
	v_mfma_f32_16x16x32_f16 v[120:123], v[158:161], v[182:185], v[120:123]
	v_mfma_f32_16x16x32_f16 v[124:127], v[150:153], v[182:185], v[124:127]
	v_mfma_f32_16x16x32_f16 v[112:115], v[158:161], v[190:193], v[112:115]
	v_mfma_f32_16x16x32_f16 v[116:119], v[150:153], v[190:193], v[116:119]
	v_mfma_f32_16x16x32_f16 v[96:99], v[158:161], v[198:201], v[96:99]
	v_mfma_f32_16x16x32_f16 v[100:103], v[150:153], v[198:201], v[100:103]
	v_mfma_f32_16x16x32_f16 v[80:83], v[158:161], v[210:213], v[80:83]
	v_mfma_f32_16x16x32_f16 v[84:87], v[150:153], v[210:213], v[84:87]
	v_mfma_f32_16x16x32_f16 v[120:123], v[162:165], v[186:189], v[120:123]
	v_mfma_f32_16x16x32_f16 v[124:127], v[154:157], v[186:189], v[124:127]
	v_mfma_f32_16x16x32_f16 v[112:115], v[162:165], v[194:197], v[112:115]
	v_mfma_f32_16x16x32_f16 v[116:119], v[154:157], v[194:197], v[116:119]
	v_mfma_f32_16x16x32_f16 v[96:99], v[162:165], v[206:209], v[96:99]
	v_mfma_f32_16x16x32_f16 v[100:103], v[154:157], v[206:209], v[100:103]
	v_mfma_f32_16x16x32_f16 v[80:83], v[162:165], v[214:217], v[80:83]
	v_mfma_f32_16x16x32_f16 v[84:87], v[154:157], v[214:217], v[84:87]
	v_mfma_f32_16x16x32_f16 v[104:107], v[174:177], v[182:185], v[104:107]
	v_mfma_f32_16x16x32_f16 v[108:111], v[166:169], v[182:185], v[108:111]
	v_mfma_f32_16x16x32_f16 v[88:91], v[174:177], v[190:193], v[88:91]
	v_mfma_f32_16x16x32_f16 v[92:95], v[166:169], v[190:193], v[92:95]
	v_mfma_f32_16x16x32_f16 v[72:75], v[174:177], v[198:201], v[72:75]
	v_mfma_f32_16x16x32_f16 v[76:79], v[166:169], v[198:201], v[76:79]
	v_mfma_f32_16x16x32_f16 v[64:67], v[174:177], v[210:213], v[64:67]
	v_mfma_f32_16x16x32_f16 v[68:71], v[166:169], v[210:213], v[68:71]
	v_mfma_f32_16x16x32_f16 v[104:107], v[178:181], v[186:189], v[104:107]
	v_mfma_f32_16x16x32_f16 v[108:111], v[170:173], v[186:189], v[108:111]
	v_mfma_f32_16x16x32_f16 v[88:91], v[178:181], v[194:197], v[88:91]
	v_mfma_f32_16x16x32_f16 v[92:95], v[170:173], v[194:197], v[92:95]
	v_mfma_f32_16x16x32_f16 v[72:75], v[178:181], v[206:209], v[72:75]
	v_mfma_f32_16x16x32_f16 v[76:79], v[170:173], v[206:209], v[76:79]
	v_mfma_f32_16x16x32_f16 v[64:67], v[178:181], v[214:217], v[64:67]
	v_mfma_f32_16x16x32_f16 v[68:71], v[170:173], v[214:217], v[68:71]
	s_barrier
	s_add_i32 s26, s63, s34
	s_mov_b32 m0, s26
	ds_read_b128 v[182:185], v149 offset:49152
	ds_read_b128 v[186:189], v149 offset:50176
	ds_read_b128 v[190:193], v149 offset:51200
	ds_read_b128 v[194:197], v149 offset:52224
	ds_read_b128 v[198:201], v149 offset:53248
	ds_read_b128 v[206:209], v149 offset:54272
	ds_read_b128 v[210:213], v149 offset:55296
	ds_read_b128 v[214:217], v149 offset:56320
	global_load_lds_dwordx4 v132, s[98:99]
	s_add_i32 m0, s26, 0x2000
	s_add_u32 s24, s24, 0x80080
	s_addc_u32 s25, s25, 0
	s_add_i32 s26, s66, s34
	global_load_lds_dwordx4 v128, s[98:99]
	s_mov_b32 m0, s26
	s_nop 0
	global_load_lds_dwordx4 v132, s[24:25]
	s_add_i32 m0, s26, 0x2000
	s_nop 0
	global_load_lds_dwordx4 v128, s[24:25]
	s_mov_b32 m0, s41
	s_nop 0
	global_load_lds_dwordx4 v134, s[100:101]
	s_mov_b32 m0, s42
	s_nop 0
	global_load_lds_dwordx4 v130, s[100:101]
	s_waitcnt vmcnt(8)
	s_waitcnt lgkmcnt(0)
	s_barrier
	v_mfma_f32_16x16x32_f16 v[56:59], v[158:161], v[182:185], v[56:59]
	v_mfma_f32_16x16x32_f16 v[60:63], v[150:153], v[182:185], v[60:63]
	v_mfma_f32_16x16x32_f16 v[48:51], v[158:161], v[190:193], v[48:51]
	v_mfma_f32_16x16x32_f16 v[52:55], v[150:153], v[190:193], v[52:55]
	v_mfma_f32_16x16x32_f16 v[32:35], v[158:161], v[198:201], v[32:35]
	v_mfma_f32_16x16x32_f16 v[36:39], v[150:153], v[198:201], v[36:39]
	v_mfma_f32_16x16x32_f16 v[16:19], v[158:161], v[210:213], v[16:19]
	v_mfma_f32_16x16x32_f16 v[20:23], v[150:153], v[210:213], v[20:23]
	v_mfma_f32_16x16x32_f16 v[56:59], v[162:165], v[186:189], v[56:59]
	v_mfma_f32_16x16x32_f16 v[60:63], v[154:157], v[186:189], v[60:63]
	v_mfma_f32_16x16x32_f16 v[48:51], v[162:165], v[194:197], v[48:51]
	v_mfma_f32_16x16x32_f16 v[52:55], v[154:157], v[194:197], v[52:55]
	v_mfma_f32_16x16x32_f16 v[32:35], v[162:165], v[206:209], v[32:35]
	v_mfma_f32_16x16x32_f16 v[36:39], v[154:157], v[206:209], v[36:39]
	v_mfma_f32_16x16x32_f16 v[16:19], v[162:165], v[214:217], v[16:19]
	v_mfma_f32_16x16x32_f16 v[20:23], v[154:157], v[214:217], v[20:23]
	v_mfma_f32_16x16x32_f16 v[40:43], v[174:177], v[182:185], v[40:43]
	v_mfma_f32_16x16x32_f16 v[44:47], v[166:169], v[182:185], v[44:47]
	v_mfma_f32_16x16x32_f16 v[24:27], v[174:177], v[190:193], v[24:27]
	v_mfma_f32_16x16x32_f16 v[28:31], v[166:169], v[190:193], v[28:31]
	v_mfma_f32_16x16x32_f16 v[8:11], v[174:177], v[198:201], v[8:11]
	v_mfma_f32_16x16x32_f16 v[12:15], v[166:169], v[198:201], v[12:15]
	v_mfma_f32_16x16x32_f16 v[0:3], v[174:177], v[210:213], v[0:3]
	v_mfma_f32_16x16x32_f16 v[4:7], v[166:169], v[210:213], v[4:7]
	v_mfma_f32_16x16x32_f16 v[40:43], v[178:181], v[186:189], v[40:43]
	v_mfma_f32_16x16x32_f16 v[44:47], v[170:173], v[186:189], v[44:47]
	v_mfma_f32_16x16x32_f16 v[24:27], v[178:181], v[194:197], v[24:27]
	v_mfma_f32_16x16x32_f16 v[28:31], v[170:173], v[194:197], v[28:31]
	v_mfma_f32_16x16x32_f16 v[8:11], v[178:181], v[206:209], v[8:11]
	v_mfma_f32_16x16x32_f16 v[12:15], v[170:173], v[206:209], v[12:15]
	v_mfma_f32_16x16x32_f16 v[0:3], v[178:181], v[214:217], v[0:3]
	v_mfma_f32_16x16x32_f16 v[4:7], v[170:173], v[214:217], v[4:7]
	s_barrier
	s_add_i32 s62, s62, 2
	s_add_u32 s60, s60, 0x100
	s_addc_u32 s61, s61, 0
	s_add_u32 s22, s22, 0x100
	s_addc_u32 s23, s23, 0
	s_cmp_gt_u32 s62, 29
	s_cbranch_scc0 .LBB0_146
	s_and_b64 vcc, exec, s[10:11]
	s_cbranch_vccz .LBB0_149
	s_barrier

; #define PG8_STAGE(bufoff, gbase, voff) do { _Pragma("unroll") for (int _i = 0; _i < 2; ++_i) \
;         __builtin_amdgcn_global_load_lds((const unsigned*)((const char*)(gbase) + (voff)[_i]), (PG8_LAS unsigned*)(lds + (bufoff) + ldsw + _i * 8192), 16, 0, 0); } while (0)
; #define PG8_LDA(dst, b, h) do { _Pragma("unroll") for (int m = 0; m < 4; ++m) _Pragma("unroll") for (int k = 0; k < 2; ++k) dst[m][k] = *(const PG8_LAS bf16x8*)(lds + PG8_SA(b, h) + aoff + m * 2048 + k * 1024); } while (0)
; #define PG8_LDB(dst, b, h) do { _Pragma("unroll") for (int n = 0; n < 2; ++n) _Pragma("unroll") for (int k = 0; k < 2; ++k) dst[n][k] = *(const PG8_LAS bf16x8*)(lds + PG8_SB(b, h) + boff + n * 2048 + k * 1024); } while (0)
; #define PG8_MMA(ai, bj, At, Bt) do { __builtin_amdgcn_s_setprio(1); _Pragma("unroll") for (int m = 0; m < 4; ++m) _Pragma("unroll") for (int n = 0; n < 2; ++n) _Pragma("unroll") for (int k = 0; k < 2; ++k) \
;         acc[ai][bj][m][n] = __builtin_amdgcn_mfma_f32_16x16x32_f16(Bt[n][k], At[m][k], acc[ai][bj][m][n], 0, 0, 0); __builtin_amdgcn_s_setprio(0); } while (0)
; #define PG8_WAIT_V(n) asm volatile("s_waitcnt vmcnt(" #n ")" ::: "memory")
; #define PG8_WAIT_L(n) asm volatile("s_waitcnt lgkmcnt(" #n ")" ::: "memory")
; #define PG8_BAR __builtin_amdgcn_s_barrier()
; #define PG8_SCHED __builtin_amdgcn_sched_barrier(0)
; template <class Epi, class Sched, bool ALIGN_EPI = false, bool SP2 = false>
; __device__ __forceinline__ void gemm_phase(PG8_LAS unsigned char* lds, const Gemm g, const Sched& S, const Epi& E) {
;     ...
;             PG8_LDB(B0, 0, 0); PG8_LDB(B1, 0, 1); PG8_SCHED; PG8_LDA(At, 0, 0); PG8_STAGE(PG8_SA(1, 1), a1 + hstep, voffA);
;             PG8_WAIT_V(8); PG8_WAIT_L(0); PG8_BAR; PG8_MMA(0, 0, At, B0); PG8_MMA(0, 1, At, B1); PG8_BAR; PG8_SCHED;
;             PG8_LDA(At, 0, 1); PG8_STAGE(PG8_SB(0, 0), b2, voffB); PG8_STAGE(PG8_SB(0, 1), b2 + hstep, voffB); PG8_STAGE(PG8_SA(0, 0), a2, voffA);
;             PG8_WAIT_V(8); PG8_WAIT_L(0); PG8_BAR; PG8_MMA(1, 0, At, B0); PG8_MMA(1, 1, At, B1); PG8_BAR; PG8_SCHED;
.LBB0_485:
	ds_read_b128 v[128:131], v163
	ds_read_b128 v[132:135], v163 offset:1024
	ds_read_b128 v[152:155], v163 offset:2048
	ds_read_b128 v[156:159], v163 offset:3072
	ds_read_b128 v[166:169], v164
	ds_read_b128 v[170:173], v164 offset:1024
	ds_read_b128 v[174:177], v164 offset:2048
	ds_read_b128 v[178:181], v164 offset:3072
	s_add_u32 s26, s24, 0x100
	s_addc_u32 s27, s25, 0
	s_cmp_eq_u32 s65, 20
	s_cselect_b32 s31, s1, s27
	s_cselect_b32 s30, s0, s26
	s_cselect_b32 s29, s23, s64
	s_cselect_b32 s28, s22, s63
	s_add_i32 m0, s37, 0xc000
	ds_read_b128 v[182:185], v165
	ds_read_b128 v[186:189], v165 offset:1024
	ds_read_b128 v[190:193], v165 offset:2048
	ds_read_b128 v[194:197], v165 offset:3072
	ds_read_b128 v[198:201], v165 offset:4096
	ds_read_b128 v[208:211], v165 offset:5120
	ds_read_b128 v[212:215], v165 offset:6144
	ds_read_b128 v[216:219], v165 offset:7168
	global_load_lds_dwordx4 v146, s[24:25]
	s_add_i32 m0, s37, 0xe000
	s_nop 0
	global_load_lds_dwordx4 v144, s[24:25]
	s_waitcnt vmcnt(8)
	s_waitcnt lgkmcnt(0)
	s_barrier
	v_mfma_f32_16x16x32_f16 v[120:123], v[152:155], v[182:185], v[120:123]
	v_mfma_f32_16x16x32_f16 v[124:127], v[128:131], v[182:185], v[124:127]
	v_mfma_f32_16x16x32_f16 v[104:107], v[152:155], v[190:193], v[104:107]
	v_mfma_f32_16x16x32_f16 v[108:111], v[128:131], v[190:193], v[108:111]
	v_mfma_f32_16x16x32_f16 v[88:91], v[152:155], v[198:201], v[88:91]
	v_mfma_f32_16x16x32_f16 v[92:95], v[128:131], v[198:201], v[92:95]
	v_mfma_f32_16x16x32_f16 v[72:75], v[152:155], v[212:215], v[72:75]
	v_mfma_f32_16x16x32_f16 v[76:79], v[128:131], v[212:215], v[76:79]
	v_mfma_f32_16x16x32_f16 v[120:123], v[156:159], v[186:189], v[120:123]
	v_mfma_f32_16x16x32_f16 v[124:127], v[132:135], v[186:189], v[124:127]
	v_mfma_f32_16x16x32_f16 v[104:107], v[156:159], v[194:197], v[104:107]
	v_mfma_f32_16x16x32_f16 v[108:111], v[132:135], v[194:197], v[108:111]
	v_mfma_f32_16x16x32_f16 v[88:91], v[156:159], v[208:211], v[88:91]
	v_mfma_f32_16x16x32_f16 v[92:95], v[132:135], v[208:211], v[92:95]
	v_mfma_f32_16x16x32_f16 v[72:75], v[156:159], v[216:219], v[72:75]
	v_mfma_f32_16x16x32_f16 v[76:79], v[132:135], v[216:219], v[76:79]
	v_mfma_f32_16x16x32_f16 v[112:115], v[174:177], v[182:185], v[112:115]
	v_mfma_f32_16x16x32_f16 v[116:119], v[166:169], v[182:185], v[116:119]
	v_mfma_f32_16x16x32_f16 v[96:99], v[174:177], v[190:193], v[96:99]
	v_mfma_f32_16x16x32_f16 v[100:103], v[166:169], v[190:193], v[100:103]
	v_mfma_f32_16x16x32_f16 v[80:83], v[174:177], v[198:201], v[80:83]
	v_mfma_f32_16x16x32_f16 v[84:87], v[166:169], v[198:201], v[84:87]
	v_mfma_f32_16x16x32_f16 v[64:67], v[174:177], v[212:215], v[64:67]
	v_mfma_f32_16x16x32_f16 v[68:71], v[166:169], v[212:215], v[68:71]
	v_mfma_f32_16x16x32_f16 v[112:115], v[178:181], v[186:189], v[112:115]
	v_mfma_f32_16x16x32_f16 v[116:119], v[170:173], v[186:189], v[116:119]
	v_mfma_f32_16x16x32_f16 v[96:99], v[178:181], v[194:197], v[96:99]
	v_mfma_f32_16x16x32_f16 v[100:103], v[170:173], v[194:197], v[100:103]
	v_mfma_f32_16x16x32_f16 v[80:83], v[178:181], v[208:211], v[80:83]
	v_mfma_f32_16x16x32_f16 v[84:87], v[170:173], v[208:211], v[84:87]
	v_mfma_f32_16x16x32_f16 v[64:67], v[178:181], v[216:219], v[64:67]
	v_mfma_f32_16x16x32_f16 v[68:71], v[170:173], v[216:219], v[68:71]
	s_barrier
	s_add_i32 s24, s45, s36
	s_add_u32 s98, s28, s16
	s_addc_u32 s99, s29, s17
	s_mov_b32 m0, s24
	ds_read_b128 v[182:185], v165 offset:16384
	ds_read_b128 v[186:189], v165 offset:17408
	ds_read_b128 v[190:193], v165 offset:18432
	ds_read_b128 v[194:197], v165 offset:19456
	ds_read_b128 v[198:201], v165 offset:20480
	ds_read_b128 v[208:211], v165 offset:21504
	ds_read_b128 v[212:215], v165 offset:22528
	ds_read_b128 v[216:219], v165 offset:23552
	global_load_lds_dwordx4 v138, s[28:29]
	s_add_i32 m0, s24, 0x2000
	s_add_u32 s24, s28, 0x60000
	s_addc_u32 s25, s29, 0
	s_add_i32 s66, s52, s36
	global_load_lds_dwordx4 v142, s[28:29]
	s_mov_b32 m0, s66
	s_nop 0
	global_load_lds_dwordx4 v138, s[24:25]
	s_add_i32 m0, s66, 0x2000
	s_nop 0
	global_load_lds_dwordx4 v142, s[24:25]
	s_add_u32 s100, s30, s16
	s_addc_u32 s101, s31, s17
	s_mov_b32 m0, s37
	s_nop 0
	global_load_lds_dwordx4 v136, s[30:31]
	s_mov_b32 m0, s38
	s_nop 0
	global_load_lds_dwordx4 v140, s[30:31]
	s_waitcnt vmcnt(8)
	s_waitcnt lgkmcnt(0)
	s_barrier
	v_mfma_f32_16x16x32_f16 v[56:59], v[152:155], v[182:185], v[56:59]
	v_mfma_f32_16x16x32_f16 v[60:63], v[128:131], v[182:185], v[60:63]
	v_mfma_f32_16x16x32_f16 v[40:43], v[152:155], v[190:193], v[40:43]
	v_mfma_f32_16x16x32_f16 v[44:47], v[128:131], v[190:193], v[44:47]
	v_mfma_f32_16x16x32_f16 v[24:27], v[152:155], v[198:201], v[24:27]
	v_mfma_f32_16x16x32_f16 v[28:31], v[128:131], v[198:201], v[28:31]
	v_mfma_f32_16x16x32_f16 v[8:11], v[152:155], v[212:215], v[8:11]
	v_mfma_f32_16x16x32_f16 v[12:15], v[128:131], v[212:215], v[12:15]
	v_mfma_f32_16x16x32_f16 v[56:59], v[156:159], v[186:189], v[56:59]
	v_mfma_f32_16x16x32_f16 v[60:63], v[132:135], v[186:189], v[60:63]
	v_mfma_f32_16x16x32_f16 v[40:43], v[156:159], v[194:197], v[40:43]
	v_mfma_f32_16x16x32_f16 v[44:47], v[132:135], v[194:197], v[44:47]
	v_mfma_f32_16x16x32_f16 v[24:27], v[156:159], v[208:211], v[24:27]
	v_mfma_f32_16x16x32_f16 v[28:31], v[132:135], v[208:211], v[28:31]
	v_mfma_f32_16x16x32_f16 v[8:11], v[156:159], v[216:219], v[8:11]
	v_mfma_f32_16x16x32_f16 v[12:15], v[132:135], v[216:219], v[12:15]
	v_mfma_f32_16x16x32_f16 v[48:51], v[174:177], v[182:185], v[48:51]
	v_mfma_f32_16x16x32_f16 v[52:55], v[166:169], v[182:185], v[52:55]
	v_mfma_f32_16x16x32_f16 v[32:35], v[174:177], v[190:193], v[32:35]
	v_mfma_f32_16x16x32_f16 v[36:39], v[166:169], v[190:193], v[36:39]
	v_mfma_f32_16x16x32_f16 v[16:19], v[174:177], v[198:201], v[16:19]
	v_mfma_f32_16x16x32_f16 v[20:23], v[166:169], v[198:201], v[20:23]
	v_mfma_f32_16x16x32_f16 v[0:3], v[174:177], v[212:215], v[0:3]
	v_mfma_f32_16x16x32_f16 v[4:7], v[166:169], v[212:215], v[4:7]
	v_mfma_f32_16x16x32_f16 v[48:51], v[178:181], v[186:189], v[48:51]
	v_mfma_f32_16x16x32_f16 v[52:55], v[170:173], v[186:189], v[52:55]
	v_mfma_f32_16x16x32_f16 v[32:35], v[178:181], v[194:197], v[32:35]
	v_mfma_f32_16x16x32_f16 v[36:39], v[170:173], v[194:197], v[36:39]
	v_mfma_f32_16x16x32_f16 v[16:19], v[178:181], v[208:211], v[16:19]
	v_mfma_f32_16x16x32_f16 v[20:23], v[170:173], v[208:211], v[20:23]
	v_mfma_f32_16x16x32_f16 v[0:3], v[178:181], v[216:219], v[0:3]
	v_mfma_f32_16x16x32_f16 v[4:7], v[170:173], v[216:219], v[4:7]
	s_barrier
; #define PG8_STAGE(bufoff, gbase, voff) do { _Pragma("unroll") for (int _i = 0; _i < 2; ++_i) \
;         __builtin_amdgcn_global_load_lds((const unsigned*)((const char*)(gbase) + (voff)[_i]), (PG8_LAS unsigned*)(lds + (bufoff) + ldsw + _i * 8192), 16, 0, 0); } while (0)
; #define PG8_LDA(dst, b, h) do { _Pragma("unroll") for (int m = 0; m < 4; ++m) _Pragma("unroll") for (int k = 0; k < 2; ++k) dst[m][k] = *(const PG8_LAS bf16x8*)(lds + PG8_SA(b, h) + aoff + m * 2048 + k * 1024); } while (0)
; #define PG8_LDB(dst, b, h) do { _Pragma("unroll") for (int n = 0; n < 2; ++n) _Pragma("unroll") for (int k = 0; k < 2; ++k) dst[n][k] = *(const PG8_LAS bf16x8*)(lds + PG8_SB(b, h) + boff + n * 2048 + k * 1024); } while (0)
; #define PG8_MMA(ai, bj, At, Bt) do { __builtin_amdgcn_s_setprio(1); _Pragma("unroll") for (int m = 0; m < 4; ++m) _Pragma("unroll") for (int n = 0; n < 2; ++n) _Pragma("unroll") for (int k = 0; k < 2; ++k) \
;         acc[ai][bj][m][n] = __builtin_amdgcn_mfma_f32_16x16x32_f16(Bt[n][k], At[m][k], acc[ai][bj][m][n], 0, 0, 0); __builtin_amdgcn_s_setprio(0); } while (0)
; #define PG8_WAIT_V(n) asm volatile("s_waitcnt vmcnt(" #n ")" ::: "memory")
; #define PG8_WAIT_L(n) asm volatile("s_waitcnt lgkmcnt(" #n ")" ::: "memory")
; #define PG8_BAR __builtin_amdgcn_s_barrier()
; #define PG8_SCHED __builtin_amdgcn_sched_barrier(0)
; template <class Epi, class Sched, bool ALIGN_EPI = false, bool SP2 = false>
; __device__ __forceinline__ void gemm_phase(PG8_LAS unsigned char* lds, const Gemm g, const Sched& S, const Epi& E) {
;     ...
;             PG8_LDB(B0, 1, 0); PG8_LDB(B1, 1, 1); PG8_SCHED; PG8_LDA(At, 1, 0); PG8_STAGE(PG8_SA(0, 1), a2 + hstep, voffA);
;             PG8_WAIT_V(8); PG8_WAIT_L(0); PG8_BAR; PG8_MMA(0, 0, At, B0); PG8_MMA(0, 1, At, B1); PG8_BAR; PG8_SCHED;
;             PG8_LDA(At, 1, 1); PG8_STAGE(PG8_SB(1, 0), b3, voffB); PG8_STAGE(PG8_SB(1, 1), b3 + hstep, voffB); PG8_STAGE(PG8_SA(1, 0), a3, voffA);
;             PG8_WAIT_V(8); PG8_WAIT_L(0); PG8_BAR; PG8_MMA(1, 0, At, B0); PG8_MMA(1, 1, At, B1); PG8_BAR; PG8_SCHED;
;     ...
;         if constexpr (ALIGN_EPI) { if (wr == 0) PG8_BAR; }
	s_add_i32 s66, 0, 0x18000
	s_add_i32 s67, 0, 0x1c000
	v_add_u32_e32 v156, s66, v161
	v_add_u32_e32 v178, s67, v161
	ds_read_b128 v[128:131], v156
	ds_read_b128 v[132:135], v156 offset:1024
	ds_read_b128 v[152:155], v156 offset:2048
	ds_read_b128 v[156:159], v156 offset:3072
	ds_read_b128 v[166:169], v178
	ds_read_b128 v[170:173], v178 offset:1024
	ds_read_b128 v[174:177], v178 offset:2048
	ds_read_b128 v[178:181], v178 offset:3072
	s_add_u32 s24, s30, 0x60000
	s_addc_u32 s25, s31, 0
	s_mov_b32 m0, s39
	ds_read_b128 v[182:185], v165 offset:32768
	ds_read_b128 v[186:189], v165 offset:33792
	ds_read_b128 v[190:193], v165 offset:34816
	ds_read_b128 v[194:197], v165 offset:35840
	ds_read_b128 v[198:201], v165 offset:36864
	ds_read_b128 v[208:211], v165 offset:37888
	ds_read_b128 v[212:215], v165 offset:38912
	ds_read_b128 v[216:219], v165 offset:39936
	global_load_lds_dwordx4 v136, s[24:25]
	s_mov_b32 m0, s40
	s_nop 0
	global_load_lds_dwordx4 v140, s[24:25]
	s_waitcnt vmcnt(8)
	s_waitcnt lgkmcnt(0)
	s_barrier
	v_mfma_f32_16x16x32_f16 v[120:123], v[152:155], v[182:185], v[120:123]
	v_mfma_f32_16x16x32_f16 v[124:127], v[128:131], v[182:185], v[124:127]
	v_mfma_f32_16x16x32_f16 v[104:107], v[152:155], v[190:193], v[104:107]
	v_mfma_f32_16x16x32_f16 v[108:111], v[128:131], v[190:193], v[108:111]
	v_mfma_f32_16x16x32_f16 v[88:91], v[152:155], v[198:201], v[88:91]
	v_mfma_f32_16x16x32_f16 v[92:95], v[128:131], v[198:201], v[92:95]
	v_mfma_f32_16x16x32_f16 v[72:75], v[152:155], v[212:215], v[72:75]
	v_mfma_f32_16x16x32_f16 v[76:79], v[128:131], v[212:215], v[76:79]
	v_mfma_f32_16x16x32_f16 v[120:123], v[156:159], v[186:189], v[120:123]
	v_mfma_f32_16x16x32_f16 v[124:127], v[132:135], v[186:189], v[124:127]
	v_mfma_f32_16x16x32_f16 v[104:107], v[156:159], v[194:197], v[104:107]
	v_mfma_f32_16x16x32_f16 v[108:111], v[132:135], v[194:197], v[108:111]
	v_mfma_f32_16x16x32_f16 v[88:91], v[156:159], v[208:211], v[88:91]
	v_mfma_f32_16x16x32_f16 v[92:95], v[132:135], v[208:211], v[92:95]
	v_mfma_f32_16x16x32_f16 v[72:75], v[156:159], v[216:219], v[72:75]
	v_mfma_f32_16x16x32_f16 v[76:79], v[132:135], v[216:219], v[76:79]
	v_mfma_f32_16x16x32_f16 v[112:115], v[174:177], v[182:185], v[112:115]
	v_mfma_f32_16x16x32_f16 v[116:119], v[166:169], v[182:185], v[116:119]
	v_mfma_f32_16x16x32_f16 v[96:99], v[174:177], v[190:193], v[96:99]
	v_mfma_f32_16x16x32_f16 v[100:103], v[166:169], v[190:193], v[100:103]
	v_mfma_f32_16x16x32_f16 v[80:83], v[174:177], v[198:201], v[80:83]
	v_mfma_f32_16x16x32_f16 v[84:87], v[166:169], v[198:201], v[84:87]
	v_mfma_f32_16x16x32_f16 v[64:67], v[174:177], v[212:215], v[64:67]
	v_mfma_f32_16x16x32_f16 v[68:71], v[166:169], v[212:215], v[68:71]
	v_mfma_f32_16x16x32_f16 v[112:115], v[178:181], v[186:189], v[112:115]
	v_mfma_f32_16x16x32_f16 v[116:119], v[170:173], v[186:189], v[116:119]
	v_mfma_f32_16x16x32_f16 v[96:99], v[178:181], v[194:197], v[96:99]
	v_mfma_f32_16x16x32_f16 v[100:103], v[170:173], v[194:197], v[100:103]
	v_mfma_f32_16x16x32_f16 v[80:83], v[178:181], v[208:211], v[80:83]
	v_mfma_f32_16x16x32_f16 v[84:87], v[170:173], v[208:211], v[84:87]
	v_mfma_f32_16x16x32_f16 v[64:67], v[178:181], v[216:219], v[64:67]
	v_mfma_f32_16x16x32_f16 v[68:71], v[170:173], v[216:219], v[68:71]
	s_barrier
	s_add_i32 s24, s66, s36
	s_mov_b32 m0, s24
	ds_read_b128 v[182:185], v165 offset:49152
	ds_read_b128 v[186:189], v165 offset:50176
	ds_read_b128 v[190:193], v165 offset:51200
	ds_read_b128 v[194:197], v165 offset:52224
	ds_read_b128 v[198:201], v165 offset:53248
	ds_read_b128 v[208:211], v165 offset:54272
	ds_read_b128 v[212:215], v165 offset:55296
	ds_read_b128 v[216:219], v165 offset:56320
	global_load_lds_dwordx4 v138, s[98:99]
	s_add_i32 m0, s24, 0x2000
	s_add_u32 s24, s28, 0x60080
	s_addc_u32 s25, s29, 0
	s_add_i32 s28, s67, s36
	global_load_lds_dwordx4 v142, s[98:99]
	s_mov_b32 m0, s28
	s_nop 0
	global_load_lds_dwordx4 v138, s[24:25]
	s_add_i32 m0, s28, 0x2000
	s_nop 0
	global_load_lds_dwordx4 v142, s[24:25]
	s_mov_b32 m0, s42
	s_nop 0
	global_load_lds_dwordx4 v136, s[100:101]
	s_mov_b32 m0, s43
	s_nop 0
	global_load_lds_dwordx4 v140, s[100:101]
	s_waitcnt vmcnt(8)
	s_waitcnt lgkmcnt(0)
	s_barrier
	v_mfma_f32_16x16x32_f16 v[56:59], v[152:155], v[182:185], v[56:59]
	v_mfma_f32_16x16x32_f16 v[60:63], v[128:131], v[182:185], v[60:63]
	v_mfma_f32_16x16x32_f16 v[40:43], v[152:155], v[190:193], v[40:43]
	v_mfma_f32_16x16x32_f16 v[44:47], v[128:131], v[190:193], v[44:47]
	v_mfma_f32_16x16x32_f16 v[24:27], v[152:155], v[198:201], v[24:27]
	v_mfma_f32_16x16x32_f16 v[28:31], v[128:131], v[198:201], v[28:31]
	v_mfma_f32_16x16x32_f16 v[8:11], v[152:155], v[212:215], v[8:11]
	v_mfma_f32_16x16x32_f16 v[12:15], v[128:131], v[212:215], v[12:15]
	v_mfma_f32_16x16x32_f16 v[56:59], v[156:159], v[186:189], v[56:59]
	v_mfma_f32_16x16x32_f16 v[60:63], v[132:135], v[186:189], v[60:63]
	v_mfma_f32_16x16x32_f16 v[40:43], v[156:159], v[194:197], v[40:43]
	v_mfma_f32_16x16x32_f16 v[44:47], v[132:135], v[194:197], v[44:47]
	v_mfma_f32_16x16x32_f16 v[24:27], v[156:159], v[208:211], v[24:27]
	v_mfma_f32_16x16x32_f16 v[28:31], v[132:135], v[208:211], v[28:31]
	v_mfma_f32_16x16x32_f16 v[8:11], v[156:159], v[216:219], v[8:11]
	v_mfma_f32_16x16x32_f16 v[12:15], v[132:135], v[216:219], v[12:15]
	v_mfma_f32_16x16x32_f16 v[48:51], v[174:177], v[182:185], v[48:51]
	v_mfma_f32_16x16x32_f16 v[52:55], v[166:169], v[182:185], v[52:55]
	v_mfma_f32_16x16x32_f16 v[32:35], v[174:177], v[190:193], v[32:35]
	v_mfma_f32_16x16x32_f16 v[36:39], v[166:169], v[190:193], v[36:39]
	v_mfma_f32_16x16x32_f16 v[16:19], v[174:177], v[198:201], v[16:19]
	v_mfma_f32_16x16x32_f16 v[20:23], v[166:169], v[198:201], v[20:23]
	v_mfma_f32_16x16x32_f16 v[0:3], v[174:177], v[212:215], v[0:3]
	v_mfma_f32_16x16x32_f16 v[4:7], v[166:169], v[212:215], v[4:7]
	v_mfma_f32_16x16x32_f16 v[48:51], v[178:181], v[186:189], v[48:51]
	v_mfma_f32_16x16x32_f16 v[52:55], v[170:173], v[186:189], v[52:55]
	v_mfma_f32_16x16x32_f16 v[32:35], v[178:181], v[194:197], v[32:35]
	v_mfma_f32_16x16x32_f16 v[36:39], v[170:173], v[194:197], v[36:39]
	v_mfma_f32_16x16x32_f16 v[16:19], v[178:181], v[208:211], v[16:19]
	v_mfma_f32_16x16x32_f16 v[20:23], v[170:173], v[208:211], v[20:23]
	v_mfma_f32_16x16x32_f16 v[0:3], v[178:181], v[216:219], v[0:3]
	v_mfma_f32_16x16x32_f16 v[4:7], v[170:173], v[216:219], v[4:7]
	s_barrier
	s_add_i32 s65, s65, 2
	s_add_u32 s63, s63, 0x100
	s_addc_u32 s64, s64, 0
	s_cmp_gt_u32 s65, 21
	s_mov_b64 s[24:25], s[26:27]
	s_cbranch_scc0 .LBB0_485
	s_and_b64 vcc, exec, s[18:19]
	s_cbranch_vccz .LBB0_488
	s_barrier

; #define PG8_STAGE(bufoff, gbase, voff) do { _Pragma("unroll") for (int _i = 0; _i < 2; ++_i) \
;         __builtin_amdgcn_global_load_lds((const unsigned*)((const char*)(gbase) + (voff)[_i]), (PG8_LAS unsigned*)(lds + (bufoff) + ldsw + _i * 8192), 16, 0, 0); } while (0)
; #define PG8_LDA(dst, b, h) do { _Pragma("unroll") for (int m = 0; m < 4; ++m) _Pragma("unroll") for (int k = 0; k < 2; ++k) dst[m][k] = *(const PG8_LAS bf16x8*)(lds + PG8_SA(b, h) + aoff + m * 2048 + k * 1024); } while (0)
; #define PG8_LDB(dst, b, h) do { _Pragma("unroll") for (int n = 0; n < 2; ++n) _Pragma("unroll") for (int k = 0; k < 2; ++k) dst[n][k] = *(const PG8_LAS bf16x8*)(lds + PG8_SB(b, h) + boff + n * 2048 + k * 1024); } while (0)
; #define PG8_MMA(ai, bj, At, Bt) do { __builtin_amdgcn_s_setprio(1); _Pragma("unroll") for (int m = 0; m < 4; ++m) _Pragma("unroll") for (int n = 0; n < 2; ++n) _Pragma("unroll") for (int k = 0; k < 2; ++k) \
;         acc[ai][bj][m][n] = __builtin_amdgcn_mfma_f32_16x16x32_f16(Bt[n][k], At[m][k], acc[ai][bj][m][n], 0, 0, 0); __builtin_amdgcn_s_setprio(0); } while (0)
; #define PG8_WAIT_V(n) asm volatile("s_waitcnt vmcnt(" #n ")" ::: "memory")
; #define PG8_WAIT_L(n) asm volatile("s_waitcnt lgkmcnt(" #n ")" ::: "memory")
; #define PG8_BAR __builtin_amdgcn_s_barrier()
; #define PG8_SCHED __builtin_amdgcn_sched_barrier(0)
; template <class Epi, class Sched, bool ALIGN_EPI = false, bool SP2 = false>
; __device__ __forceinline__ void gemm_phase(PG8_LAS unsigned char* lds, const Gemm g, const Sched& S, const Epi& E) {
;     ...
;             PG8_LDB(B0, 0, 0); PG8_LDB(B1, 0, 1); PG8_SCHED; PG8_LDA(At, 0, 0); PG8_STAGE(PG8_SA(1, 1), a1 + hstep, voffA);
;             PG8_WAIT_V(8); PG8_WAIT_L(0); PG8_BAR; PG8_MMA(0, 0, At, B0); PG8_MMA(0, 1, At, B1); PG8_BAR; PG8_SCHED;
;             PG8_LDA(At, 0, 1); PG8_STAGE(PG8_SB(0, 0), b2, voffB); PG8_STAGE(PG8_SB(0, 1), b2 + hstep, voffB); PG8_STAGE(PG8_SA(0, 0), a2, voffA);
;             PG8_WAIT_V(8); PG8_WAIT_L(0); PG8_BAR; PG8_MMA(1, 0, At, B0); PG8_MMA(1, 1, At, B1); PG8_BAR; PG8_SCHED;
.LBB0_577:
	ds_read_b128 v[128:131], v198
	ds_read_b128 v[132:135], v198 offset:1024
	ds_read_b128 v[136:139], v198 offset:2048
	ds_read_b128 v[140:143], v198 offset:3072
	ds_read_b128 v[144:147], v199
	ds_read_b128 v[148:151], v199 offset:1024
	ds_read_b128 v[152:155], v199 offset:2048
	ds_read_b128 v[156:159], v199 offset:3072
	s_add_u32 s42, s40, 0xfff80080
	s_addc_u32 s43, s41, -1
	s_cmp_eq_u32 s91, 28
	s_cselect_b32 s45, s31, s43
	s_cselect_b32 s44, s87, s42
	s_cselect_b32 s43, s29, s90
	s_cselect_b32 s42, s88, s89
	s_add_i32 m0, s39, 0xc000
	ds_read_b128 v[176:179], v200
	ds_read_b128 v[180:183], v200 offset:1024
	ds_read_b128 v[184:187], v200 offset:2048
	ds_read_b128 v[188:191], v200 offset:3072
	ds_read_b128 v[208:211], v200 offset:4096
	ds_read_b128 v[212:215], v200 offset:5120
	ds_read_b128 v[216:219], v200 offset:6144
	ds_read_b128 v[220:223], v200 offset:7168
	global_load_lds_dwordx4 v170, s[40:41]
	s_add_i32 m0, s39, 0xe000
	s_nop 0
	global_load_lds_dwordx4 v168, s[40:41]
	s_waitcnt vmcnt(8)
	s_waitcnt lgkmcnt(0)
	s_barrier
	v_mfma_f32_16x16x32_f16 v[120:123], v[136:139], v[176:179], v[120:123]
	v_mfma_f32_16x16x32_f16 v[124:127], v[128:131], v[176:179], v[124:127]
	v_mfma_f32_16x16x32_f16 v[104:107], v[136:139], v[184:187], v[104:107]
	v_mfma_f32_16x16x32_f16 v[108:111], v[128:131], v[184:187], v[108:111]
	v_mfma_f32_16x16x32_f16 v[88:91], v[136:139], v[208:211], v[88:91]
	v_mfma_f32_16x16x32_f16 v[92:95], v[128:131], v[208:211], v[92:95]
	v_mfma_f32_16x16x32_f16 v[72:75], v[136:139], v[216:219], v[72:75]
	v_mfma_f32_16x16x32_f16 v[76:79], v[128:131], v[216:219], v[76:79]
	v_mfma_f32_16x16x32_f16 v[120:123], v[140:143], v[180:183], v[120:123]
	v_mfma_f32_16x16x32_f16 v[124:127], v[132:135], v[180:183], v[124:127]
	v_mfma_f32_16x16x32_f16 v[104:107], v[140:143], v[188:191], v[104:107]
	v_mfma_f32_16x16x32_f16 v[108:111], v[132:135], v[188:191], v[108:111]
	v_mfma_f32_16x16x32_f16 v[88:91], v[140:143], v[212:215], v[88:91]
	v_mfma_f32_16x16x32_f16 v[92:95], v[132:135], v[212:215], v[92:95]
	v_mfma_f32_16x16x32_f16 v[72:75], v[140:143], v[220:223], v[72:75]
	v_mfma_f32_16x16x32_f16 v[76:79], v[132:135], v[220:223], v[76:79]
	v_mfma_f32_16x16x32_f16 v[112:115], v[152:155], v[176:179], v[112:115]
	v_mfma_f32_16x16x32_f16 v[116:119], v[144:147], v[176:179], v[116:119]
	v_mfma_f32_16x16x32_f16 v[96:99], v[152:155], v[184:187], v[96:99]
	v_mfma_f32_16x16x32_f16 v[100:103], v[144:147], v[184:187], v[100:103]
	v_mfma_f32_16x16x32_f16 v[80:83], v[152:155], v[208:211], v[80:83]
	v_mfma_f32_16x16x32_f16 v[84:87], v[144:147], v[208:211], v[84:87]
	v_mfma_f32_16x16x32_f16 v[64:67], v[152:155], v[216:219], v[64:67]
	v_mfma_f32_16x16x32_f16 v[68:71], v[144:147], v[216:219], v[68:71]
	v_mfma_f32_16x16x32_f16 v[112:115], v[156:159], v[180:183], v[112:115]
	v_mfma_f32_16x16x32_f16 v[116:119], v[148:151], v[180:183], v[116:119]
	v_mfma_f32_16x16x32_f16 v[96:99], v[156:159], v[188:191], v[96:99]
	v_mfma_f32_16x16x32_f16 v[100:103], v[148:151], v[188:191], v[100:103]
	v_mfma_f32_16x16x32_f16 v[80:83], v[156:159], v[212:215], v[80:83]
	v_mfma_f32_16x16x32_f16 v[84:87], v[148:151], v[212:215], v[84:87]
	v_mfma_f32_16x16x32_f16 v[64:67], v[156:159], v[220:223], v[64:67]
	v_mfma_f32_16x16x32_f16 v[68:71], v[148:151], v[220:223], v[68:71]
	s_barrier
	s_add_i32 s92, s74, s63
	s_add_u32 s98, s42, s16
	s_addc_u32 s99, s43, s17
	s_mov_b32 m0, s92
	ds_read_b128 v[176:179], v200 offset:16384
	ds_read_b128 v[180:183], v200 offset:17408
	ds_read_b128 v[184:187], v200 offset:18432
	ds_read_b128 v[188:191], v200 offset:19456
	ds_read_b128 v[208:211], v200 offset:20480
	ds_read_b128 v[212:215], v200 offset:21504
	ds_read_b128 v[216:219], v200 offset:22528
	ds_read_b128 v[220:223], v200 offset:23552
	global_load_lds_dwordx4 v162, s[42:43]
	s_add_i32 m0, s92, 0x2000
	s_add_u32 s92, s42, 0x80000
	s_addc_u32 s93, s43, 0
	s_add_i32 s94, s75, s63
	global_load_lds_dwordx4 v166, s[42:43]
	s_mov_b32 m0, s94
	s_nop 0
	global_load_lds_dwordx4 v162, s[92:93]
	s_add_i32 m0, s94, 0x2000
	s_nop 0
	global_load_lds_dwordx4 v166, s[92:93]
	s_add_u32 s100, s44, s16
	s_addc_u32 s101, s45, s17
	s_mov_b32 m0, s39
	s_nop 0
	global_load_lds_dwordx4 v160, s[44:45]
	s_mov_b32 m0, s64
	s_nop 0
	global_load_lds_dwordx4 v164, s[44:45]
	s_waitcnt vmcnt(8)
	s_waitcnt lgkmcnt(0)
	s_barrier
	v_mfma_f32_16x16x32_f16 v[56:59], v[136:139], v[176:179], v[56:59]
	v_mfma_f32_16x16x32_f16 v[60:63], v[128:131], v[176:179], v[60:63]
	v_mfma_f32_16x16x32_f16 v[40:43], v[136:139], v[184:187], v[40:43]
	v_mfma_f32_16x16x32_f16 v[44:47], v[128:131], v[184:187], v[44:47]
	v_mfma_f32_16x16x32_f16 v[24:27], v[136:139], v[208:211], v[24:27]
	v_mfma_f32_16x16x32_f16 v[28:31], v[128:131], v[208:211], v[28:31]
	v_mfma_f32_16x16x32_f16 v[8:11], v[136:139], v[216:219], v[8:11]
	v_mfma_f32_16x16x32_f16 v[12:15], v[128:131], v[216:219], v[12:15]
	v_mfma_f32_16x16x32_f16 v[56:59], v[140:143], v[180:183], v[56:59]
	v_mfma_f32_16x16x32_f16 v[60:63], v[132:135], v[180:183], v[60:63]
	v_mfma_f32_16x16x32_f16 v[40:43], v[140:143], v[188:191], v[40:43]
	v_mfma_f32_16x16x32_f16 v[44:47], v[132:135], v[188:191], v[44:47]
	v_mfma_f32_16x16x32_f16 v[24:27], v[140:143], v[212:215], v[24:27]
	v_mfma_f32_16x16x32_f16 v[28:31], v[132:135], v[212:215], v[28:31]
	v_mfma_f32_16x16x32_f16 v[8:11], v[140:143], v[220:223], v[8:11]
	v_mfma_f32_16x16x32_f16 v[12:15], v[132:135], v[220:223], v[12:15]
	v_mfma_f32_16x16x32_f16 v[48:51], v[152:155], v[176:179], v[48:51]
	v_mfma_f32_16x16x32_f16 v[52:55], v[144:147], v[176:179], v[52:55]
	v_mfma_f32_16x16x32_f16 v[32:35], v[152:155], v[184:187], v[32:35]
	v_mfma_f32_16x16x32_f16 v[36:39], v[144:147], v[184:187], v[36:39]
	v_mfma_f32_16x16x32_f16 v[16:19], v[152:155], v[208:211], v[16:19]
	v_mfma_f32_16x16x32_f16 v[20:23], v[144:147], v[208:211], v[20:23]
	v_mfma_f32_16x16x32_f16 v[0:3], v[152:155], v[216:219], v[0:3]
	v_mfma_f32_16x16x32_f16 v[4:7], v[144:147], v[216:219], v[4:7]
	v_mfma_f32_16x16x32_f16 v[48:51], v[156:159], v[180:183], v[48:51]
	v_mfma_f32_16x16x32_f16 v[52:55], v[148:151], v[180:183], v[52:55]
	v_mfma_f32_16x16x32_f16 v[32:35], v[156:159], v[188:191], v[32:35]
	v_mfma_f32_16x16x32_f16 v[36:39], v[148:151], v[188:191], v[36:39]
	v_mfma_f32_16x16x32_f16 v[16:19], v[156:159], v[212:215], v[16:19]
	v_mfma_f32_16x16x32_f16 v[20:23], v[148:151], v[212:215], v[20:23]
	v_mfma_f32_16x16x32_f16 v[0:3], v[156:159], v[220:223], v[0:3]
	v_mfma_f32_16x16x32_f16 v[4:7], v[148:151], v[220:223], v[4:7]
	s_barrier
; #define PG8_STAGE(bufoff, gbase, voff) do { _Pragma("unroll") for (int _i = 0; _i < 2; ++_i) \
;         __builtin_amdgcn_global_load_lds((const unsigned*)((const char*)(gbase) + (voff)[_i]), (PG8_LAS unsigned*)(lds + (bufoff) + ldsw + _i * 8192), 16, 0, 0); } while (0)
; #define PG8_LDA(dst, b, h) do { _Pragma("unroll") for (int m = 0; m < 4; ++m) _Pragma("unroll") for (int k = 0; k < 2; ++k) dst[m][k] = *(const PG8_LAS bf16x8*)(lds + PG8_SA(b, h) + aoff + m * 2048 + k * 1024); } while (0)
; #define PG8_LDB(dst, b, h) do { _Pragma("unroll") for (int n = 0; n < 2; ++n) _Pragma("unroll") for (int k = 0; k < 2; ++k) dst[n][k] = *(const PG8_LAS bf16x8*)(lds + PG8_SB(b, h) + boff + n * 2048 + k * 1024); } while (0)
; #define PG8_MMA(ai, bj, At, Bt) do { __builtin_amdgcn_s_setprio(1); _Pragma("unroll") for (int m = 0; m < 4; ++m) _Pragma("unroll") for (int n = 0; n < 2; ++n) _Pragma("unroll") for (int k = 0; k < 2; ++k) \
;         acc[ai][bj][m][n] = __builtin_amdgcn_mfma_f32_16x16x32_f16(Bt[n][k], At[m][k], acc[ai][bj][m][n], 0, 0, 0); __builtin_amdgcn_s_setprio(0); } while (0)
; #define PG8_WAIT_V(n) asm volatile("s_waitcnt vmcnt(" #n ")" ::: "memory")
; #define PG8_WAIT_L(n) asm volatile("s_waitcnt lgkmcnt(" #n ")" ::: "memory")
; #define PG8_BAR __builtin_amdgcn_s_barrier()
; #define PG8_SCHED __builtin_amdgcn_sched_barrier(0)
; template <class Epi, class Sched, bool ALIGN_EPI = false, bool SP2 = false>
; __device__ __forceinline__ void gemm_phase(PG8_LAS unsigned char* lds, const Gemm g, const Sched& S, const Epi& E) {
;     ...
;             PG8_LDB(B0, 1, 0); PG8_LDB(B1, 1, 1); PG8_SCHED; PG8_LDA(At, 1, 0); PG8_STAGE(PG8_SA(0, 1), a2 + hstep, voffA);
;             PG8_WAIT_V(8); PG8_WAIT_L(0); PG8_BAR; PG8_MMA(0, 0, At, B0); PG8_MMA(0, 1, At, B1); PG8_BAR; PG8_SCHED;
;             PG8_LDA(At, 1, 1); PG8_STAGE(PG8_SB(1, 0), b3, voffB); PG8_STAGE(PG8_SB(1, 1), b3 + hstep, voffB); PG8_STAGE(PG8_SA(1, 0), a3, voffA);
;             PG8_WAIT_V(8); PG8_WAIT_L(0); PG8_BAR; PG8_MMA(1, 0, At, B0); PG8_MMA(1, 1, At, B1); PG8_BAR; PG8_SCHED;
;     ...
;         if constexpr (ALIGN_EPI) { if (wr == 0) PG8_BAR; }
	s_add_i32 s92, 0, 0x18000
	s_add_i32 s93, 0, 0x1c000
	v_add_u32_e32 v140, s92, v196
	v_add_u32_e32 v156, s93, v196
	ds_read_b128 v[128:131], v140
	ds_read_b128 v[132:135], v140 offset:1024
	ds_read_b128 v[136:139], v140 offset:2048
	ds_read_b128 v[140:143], v140 offset:3072
	ds_read_b128 v[144:147], v156
	ds_read_b128 v[148:151], v156 offset:1024
	ds_read_b128 v[152:155], v156 offset:2048
	ds_read_b128 v[156:159], v156 offset:3072
	s_add_u32 s44, s44, 0x80000
	s_addc_u32 s45, s45, 0
	s_mov_b32 m0, s65
	ds_read_b128 v[176:179], v200 offset:32768
	ds_read_b128 v[180:183], v200 offset:33792
	ds_read_b128 v[184:187], v200 offset:34816
	ds_read_b128 v[188:191], v200 offset:35840
	ds_read_b128 v[208:211], v200 offset:36864
	ds_read_b128 v[212:215], v200 offset:37888
	ds_read_b128 v[216:219], v200 offset:38912
	ds_read_b128 v[220:223], v200 offset:39936
	global_load_lds_dwordx4 v160, s[44:45]
	s_mov_b32 m0, s66
	s_nop 0
	global_load_lds_dwordx4 v164, s[44:45]
	s_waitcnt vmcnt(8)
	s_waitcnt lgkmcnt(0)
	s_barrier
	v_mfma_f32_16x16x32_f16 v[120:123], v[136:139], v[176:179], v[120:123]
	v_mfma_f32_16x16x32_f16 v[124:127], v[128:131], v[176:179], v[124:127]
	v_mfma_f32_16x16x32_f16 v[104:107], v[136:139], v[184:187], v[104:107]
	v_mfma_f32_16x16x32_f16 v[108:111], v[128:131], v[184:187], v[108:111]
	v_mfma_f32_16x16x32_f16 v[88:91], v[136:139], v[208:211], v[88:91]
	v_mfma_f32_16x16x32_f16 v[92:95], v[128:131], v[208:211], v[92:95]
	v_mfma_f32_16x16x32_f16 v[72:75], v[136:139], v[216:219], v[72:75]
	v_mfma_f32_16x16x32_f16 v[76:79], v[128:131], v[216:219], v[76:79]
	v_mfma_f32_16x16x32_f16 v[120:123], v[140:143], v[180:183], v[120:123]
	v_mfma_f32_16x16x32_f16 v[124:127], v[132:135], v[180:183], v[124:127]
	v_mfma_f32_16x16x32_f16 v[104:107], v[140:143], v[188:191], v[104:107]
	v_mfma_f32_16x16x32_f16 v[108:111], v[132:135], v[188:191], v[108:111]
	v_mfma_f32_16x16x32_f16 v[88:91], v[140:143], v[212:215], v[88:91]
	v_mfma_f32_16x16x32_f16 v[92:95], v[132:135], v[212:215], v[92:95]
	v_mfma_f32_16x16x32_f16 v[72:75], v[140:143], v[220:223], v[72:75]
	v_mfma_f32_16x16x32_f16 v[76:79], v[132:135], v[220:223], v[76:79]
	v_mfma_f32_16x16x32_f16 v[112:115], v[152:155], v[176:179], v[112:115]
	v_mfma_f32_16x16x32_f16 v[116:119], v[144:147], v[176:179], v[116:119]
	v_mfma_f32_16x16x32_f16 v[96:99], v[152:155], v[184:187], v[96:99]
	v_mfma_f32_16x16x32_f16 v[100:103], v[144:147], v[184:187], v[100:103]
	v_mfma_f32_16x16x32_f16 v[80:83], v[152:155], v[208:211], v[80:83]
	v_mfma_f32_16x16x32_f16 v[84:87], v[144:147], v[208:211], v[84:87]
	v_mfma_f32_16x16x32_f16 v[64:67], v[152:155], v[216:219], v[64:67]
	v_mfma_f32_16x16x32_f16 v[68:71], v[144:147], v[216:219], v[68:71]
	v_mfma_f32_16x16x32_f16 v[112:115], v[156:159], v[180:183], v[112:115]
	v_mfma_f32_16x16x32_f16 v[116:119], v[148:151], v[180:183], v[116:119]
	v_mfma_f32_16x16x32_f16 v[96:99], v[156:159], v[188:191], v[96:99]
	v_mfma_f32_16x16x32_f16 v[100:103], v[148:151], v[188:191], v[100:103]
	v_mfma_f32_16x16x32_f16 v[80:83], v[156:159], v[212:215], v[80:83]
	v_mfma_f32_16x16x32_f16 v[84:87], v[148:151], v[212:215], v[84:87]
	v_mfma_f32_16x16x32_f16 v[64:67], v[156:159], v[220:223], v[64:67]
	v_mfma_f32_16x16x32_f16 v[68:71], v[148:151], v[220:223], v[68:71]
	s_barrier
	s_add_i32 s44, s92, s63
	s_mov_b32 m0, s44
	ds_read_b128 v[176:179], v200 offset:49152
	ds_read_b128 v[180:183], v200 offset:50176
	ds_read_b128 v[184:187], v200 offset:51200
	ds_read_b128 v[188:191], v200 offset:52224
	ds_read_b128 v[208:211], v200 offset:53248
	ds_read_b128 v[212:215], v200 offset:54272
	ds_read_b128 v[216:219], v200 offset:55296
	ds_read_b128 v[220:223], v200 offset:56320
	global_load_lds_dwordx4 v162, s[98:99]
	s_add_i32 m0, s44, 0x2000
	s_add_u32 s42, s42, 0x80080
	s_addc_u32 s43, s43, 0
	s_add_i32 s44, s93, s63
	global_load_lds_dwordx4 v166, s[98:99]
	s_mov_b32 m0, s44
	s_nop 0
	global_load_lds_dwordx4 v162, s[42:43]
	s_add_i32 m0, s44, 0x2000
	s_nop 0
	global_load_lds_dwordx4 v166, s[42:43]
	s_mov_b32 m0, s68
	s_nop 0
	global_load_lds_dwordx4 v160, s[100:101]
	s_mov_b32 m0, s69
	s_nop 0
	global_load_lds_dwordx4 v164, s[100:101]
	s_waitcnt vmcnt(8)
	s_waitcnt lgkmcnt(0)
	s_barrier
	v_mfma_f32_16x16x32_f16 v[56:59], v[136:139], v[176:179], v[56:59]
	v_mfma_f32_16x16x32_f16 v[60:63], v[128:131], v[176:179], v[60:63]
	v_mfma_f32_16x16x32_f16 v[40:43], v[136:139], v[184:187], v[40:43]
	v_mfma_f32_16x16x32_f16 v[44:47], v[128:131], v[184:187], v[44:47]
	v_mfma_f32_16x16x32_f16 v[24:27], v[136:139], v[208:211], v[24:27]
	v_mfma_f32_16x16x32_f16 v[28:31], v[128:131], v[208:211], v[28:31]
	v_mfma_f32_16x16x32_f16 v[8:11], v[136:139], v[216:219], v[8:11]
	v_mfma_f32_16x16x32_f16 v[12:15], v[128:131], v[216:219], v[12:15]
	v_mfma_f32_16x16x32_f16 v[56:59], v[140:143], v[180:183], v[56:59]
	v_mfma_f32_16x16x32_f16 v[60:63], v[132:135], v[180:183], v[60:63]
	v_mfma_f32_16x16x32_f16 v[40:43], v[140:143], v[188:191], v[40:43]
	v_mfma_f32_16x16x32_f16 v[44:47], v[132:135], v[188:191], v[44:47]
	v_mfma_f32_16x16x32_f16 v[24:27], v[140:143], v[212:215], v[24:27]
	v_mfma_f32_16x16x32_f16 v[28:31], v[132:135], v[212:215], v[28:31]
	v_mfma_f32_16x16x32_f16 v[8:11], v[140:143], v[220:223], v[8:11]
	v_mfma_f32_16x16x32_f16 v[12:15], v[132:135], v[220:223], v[12:15]
	v_mfma_f32_16x16x32_f16 v[48:51], v[152:155], v[176:179], v[48:51]
	v_mfma_f32_16x16x32_f16 v[52:55], v[144:147], v[176:179], v[52:55]
	v_mfma_f32_16x16x32_f16 v[32:35], v[152:155], v[184:187], v[32:35]
	v_mfma_f32_16x16x32_f16 v[36:39], v[144:147], v[184:187], v[36:39]
	v_mfma_f32_16x16x32_f16 v[16:19], v[152:155], v[208:211], v[16:19]
	v_mfma_f32_16x16x32_f16 v[20:23], v[144:147], v[208:211], v[20:23]
	v_mfma_f32_16x16x32_f16 v[0:3], v[152:155], v[216:219], v[0:3]
	v_mfma_f32_16x16x32_f16 v[4:7], v[144:147], v[216:219], v[4:7]
	v_mfma_f32_16x16x32_f16 v[48:51], v[156:159], v[180:183], v[48:51]
	v_mfma_f32_16x16x32_f16 v[52:55], v[148:151], v[180:183], v[52:55]
	v_mfma_f32_16x16x32_f16 v[32:35], v[156:159], v[188:191], v[32:35]
	v_mfma_f32_16x16x32_f16 v[36:39], v[148:151], v[188:191], v[36:39]
	v_mfma_f32_16x16x32_f16 v[16:19], v[156:159], v[212:215], v[16:19]
	v_mfma_f32_16x16x32_f16 v[20:23], v[148:151], v[212:215], v[20:23]
	v_mfma_f32_16x16x32_f16 v[0:3], v[156:159], v[220:223], v[0:3]
	v_mfma_f32_16x16x32_f16 v[4:7], v[148:151], v[220:223], v[4:7]
	s_barrier
	s_add_i32 s91, s91, 2
	s_add_u32 s89, s89, 0x100
	s_addc_u32 s90, s90, 0
	s_add_u32 s40, s40, 0x100
	s_addc_u32 s41, s41, 0
	s_cmp_gt_u32 s91, 29
	s_cbranch_scc0 .LBB0_577
	s_and_b64 vcc, exec, s[18:19]
	s_cbranch_vccz .LBB0_580
	s_barrier

; #define PG8_STAGE(bufoff, gbase, voff) do { _Pragma("unroll") for (int _i = 0; _i < 2; ++_i) \
;         __builtin_amdgcn_global_load_lds((const unsigned*)((const char*)(gbase) + (voff)[_i]), (PG8_LAS unsigned*)(lds + (bufoff) + ldsw + _i * 8192), 16, 0, 0); } while (0)
; #define PG8_LDA(dst, b, h) do { _Pragma("unroll") for (int m = 0; m < 4; ++m) _Pragma("unroll") for (int k = 0; k < 2; ++k) dst[m][k] = *(const PG8_LAS bf16x8*)(lds + PG8_SA(b, h) + aoff + m * 2048 + k * 1024); } while (0)
; #define PG8_LDB(dst, b, h) do { _Pragma("unroll") for (int n = 0; n < 2; ++n) _Pragma("unroll") for (int k = 0; k < 2; ++k) dst[n][k] = *(const PG8_LAS bf16x8*)(lds + PG8_SB(b, h) + boff + n * 2048 + k * 1024); } while (0)
; #define PG8_MMA(ai, bj, At, Bt) do { __builtin_amdgcn_s_setprio(1); _Pragma("unroll") for (int m = 0; m < 4; ++m) _Pragma("unroll") for (int n = 0; n < 2; ++n) _Pragma("unroll") for (int k = 0; k < 2; ++k) \
;         acc[ai][bj][m][n] = __builtin_amdgcn_mfma_f32_16x16x32_f16(Bt[n][k], At[m][k], acc[ai][bj][m][n], 0, 0, 0); __builtin_amdgcn_s_setprio(0); } while (0)
; #define PG8_WAIT_V(n) asm volatile("s_waitcnt vmcnt(" #n ")" ::: "memory")
; #define PG8_WAIT_L(n) asm volatile("s_waitcnt lgkmcnt(" #n ")" ::: "memory")
; #define PG8_BAR __builtin_amdgcn_s_barrier()
; #define PG8_SCHED __builtin_amdgcn_sched_barrier(0)
; template <class Epi, class Sched, bool ALIGN_EPI = false, bool SP2 = false>
; __device__ __forceinline__ void gemm_phase(PG8_LAS unsigned char* lds, const Gemm g, const Sched& S, const Epi& E) {
;     ...
;             PG8_LDB(B0, 0, 0); PG8_LDB(B1, 0, 1); PG8_SCHED; PG8_LDA(At, 0, 0); PG8_STAGE(PG8_SA(1, 1), a1 + hstep, voffA);
;             PG8_WAIT_V(8); PG8_WAIT_L(0); PG8_BAR; PG8_MMA(0, 0, At, B0); PG8_MMA(0, 1, At, B1); PG8_BAR; PG8_SCHED;
;             PG8_LDA(At, 0, 1); PG8_STAGE(PG8_SB(0, 0), b2, voffB); PG8_STAGE(PG8_SB(0, 1), b2 + hstep, voffB); PG8_STAGE(PG8_SA(0, 0), a2, voffA);
;             PG8_WAIT_V(8); PG8_WAIT_L(0); PG8_BAR; PG8_MMA(1, 0, At, B0); PG8_MMA(1, 1, At, B1); PG8_BAR; PG8_SCHED;
.LBB0_655:
	ds_read_b128 v[128:131], v211
	ds_read_b128 v[132:135], v211 offset:1024
	ds_read_b128 v[136:139], v211 offset:2048
	ds_read_b128 v[140:143], v211 offset:3072
	ds_read_b128 v[144:147], v212
	ds_read_b128 v[148:151], v212 offset:1024
	ds_read_b128 v[152:155], v212 offset:2048
	ds_read_b128 v[156:159], v212 offset:3072
	s_add_u32 s42, s40, 0xffe00080
	s_addc_u32 s43, s41, -1
	s_cmpk_eq_i32 s86, 0x7c
	s_cselect_b32 s45, s29, s43
	s_cselect_b32 s44, s37, s42
	s_cselect_b32 s43, s27, s83
	s_cselect_b32 s42, s81, s82
	s_add_i32 m0, s39, 0xc000
	ds_read_b128 v[160:163], v213
	ds_read_b128 v[164:167], v213 offset:1024
	ds_read_b128 v[184:187], v213 offset:2048
	ds_read_b128 v[188:191], v213 offset:3072
	ds_read_b128 v[192:195], v213 offset:4096
	ds_read_b128 v[196:199], v213 offset:5120
	ds_read_b128 v[200:203], v213 offset:6144
	ds_read_b128 v[214:217], v213 offset:7168
	global_load_lds_dwordx4 v178, s[40:41]
	s_add_i32 m0, s39, 0xe000
	s_nop 0
	global_load_lds_dwordx4 v176, s[40:41]
	s_waitcnt vmcnt(8)
	s_waitcnt lgkmcnt(0)
	s_barrier
	v_mfma_f32_16x16x32_f16 v[120:123], v[136:139], v[160:163], v[120:123]
	v_mfma_f32_16x16x32_f16 v[124:127], v[128:131], v[160:163], v[124:127]
	v_mfma_f32_16x16x32_f16 v[104:107], v[136:139], v[184:187], v[104:107]
	v_mfma_f32_16x16x32_f16 v[108:111], v[128:131], v[184:187], v[108:111]
	v_mfma_f32_16x16x32_f16 v[88:91], v[136:139], v[192:195], v[88:91]
	v_mfma_f32_16x16x32_f16 v[92:95], v[128:131], v[192:195], v[92:95]
	v_mfma_f32_16x16x32_f16 v[72:75], v[136:139], v[200:203], v[72:75]
	v_mfma_f32_16x16x32_f16 v[76:79], v[128:131], v[200:203], v[76:79]
	v_mfma_f32_16x16x32_f16 v[120:123], v[140:143], v[164:167], v[120:123]
	v_mfma_f32_16x16x32_f16 v[124:127], v[132:135], v[164:167], v[124:127]
	v_mfma_f32_16x16x32_f16 v[104:107], v[140:143], v[188:191], v[104:107]
	v_mfma_f32_16x16x32_f16 v[108:111], v[132:135], v[188:191], v[108:111]
	v_mfma_f32_16x16x32_f16 v[88:91], v[140:143], v[196:199], v[88:91]
	v_mfma_f32_16x16x32_f16 v[92:95], v[132:135], v[196:199], v[92:95]
	v_mfma_f32_16x16x32_f16 v[72:75], v[140:143], v[214:217], v[72:75]
	v_mfma_f32_16x16x32_f16 v[76:79], v[132:135], v[214:217], v[76:79]
	v_mfma_f32_16x16x32_f16 v[112:115], v[152:155], v[160:163], v[112:115]
	v_mfma_f32_16x16x32_f16 v[116:119], v[144:147], v[160:163], v[116:119]
	v_mfma_f32_16x16x32_f16 v[96:99], v[152:155], v[184:187], v[96:99]
	v_mfma_f32_16x16x32_f16 v[100:103], v[144:147], v[184:187], v[100:103]
	v_mfma_f32_16x16x32_f16 v[80:83], v[152:155], v[192:195], v[80:83]
	v_mfma_f32_16x16x32_f16 v[84:87], v[144:147], v[192:195], v[84:87]
	v_mfma_f32_16x16x32_f16 v[64:67], v[152:155], v[200:203], v[64:67]
	v_mfma_f32_16x16x32_f16 v[68:71], v[144:147], v[200:203], v[68:71]
	v_mfma_f32_16x16x32_f16 v[112:115], v[156:159], v[164:167], v[112:115]
	v_mfma_f32_16x16x32_f16 v[116:119], v[148:151], v[164:167], v[116:119]
	v_mfma_f32_16x16x32_f16 v[96:99], v[156:159], v[188:191], v[96:99]
	v_mfma_f32_16x16x32_f16 v[100:103], v[148:151], v[188:191], v[100:103]
	v_mfma_f32_16x16x32_f16 v[80:83], v[156:159], v[196:199], v[80:83]
	v_mfma_f32_16x16x32_f16 v[84:87], v[148:151], v[196:199], v[84:87]
	v_mfma_f32_16x16x32_f16 v[64:67], v[156:159], v[214:217], v[64:67]
	v_mfma_f32_16x16x32_f16 v[68:71], v[148:151], v[214:217], v[68:71]
	s_barrier
	s_add_i32 s87, s69, s61
	s_add_u32 s98, s42, s18
	s_addc_u32 s99, s43, s19
	s_mov_b32 m0, s87
	ds_read_b128 v[160:163], v213 offset:16384
	ds_read_b128 v[164:167], v213 offset:17408
	ds_read_b128 v[184:187], v213 offset:18432
	ds_read_b128 v[188:191], v213 offset:19456
	ds_read_b128 v[192:195], v213 offset:20480
	ds_read_b128 v[196:199], v213 offset:21504
	ds_read_b128 v[200:203], v213 offset:22528
	ds_read_b128 v[214:217], v213 offset:23552
	global_load_lds_dwordx4 v170, s[42:43]
	s_add_i32 m0, s87, 0x2000
	s_add_u32 s88, s42, 0x200000
	s_addc_u32 s89, s43, 0
	s_add_i32 s87, s74, s61
	global_load_lds_dwordx4 v174, s[42:43]
	s_mov_b32 m0, s87
	s_nop 0
	global_load_lds_dwordx4 v170, s[88:89]
	s_add_i32 m0, s87, 0x2000
	s_nop 0
	global_load_lds_dwordx4 v174, s[88:89]
	s_add_u32 s100, s44, s18
	s_addc_u32 s101, s45, s19
	s_mov_b32 m0, s39
	s_nop 0
	global_load_lds_dwordx4 v168, s[44:45]
	s_mov_b32 m0, s62
	s_nop 0
	global_load_lds_dwordx4 v172, s[44:45]
	s_waitcnt vmcnt(8)
	s_waitcnt lgkmcnt(0)
	s_barrier
	v_mfma_f32_16x16x32_f16 v[56:59], v[136:139], v[160:163], v[56:59]
	v_mfma_f32_16x16x32_f16 v[60:63], v[128:131], v[160:163], v[60:63]
	v_mfma_f32_16x16x32_f16 v[40:43], v[136:139], v[184:187], v[40:43]
	v_mfma_f32_16x16x32_f16 v[44:47], v[128:131], v[184:187], v[44:47]
	v_mfma_f32_16x16x32_f16 v[24:27], v[136:139], v[192:195], v[24:27]
	v_mfma_f32_16x16x32_f16 v[28:31], v[128:131], v[192:195], v[28:31]
	v_mfma_f32_16x16x32_f16 v[8:11], v[136:139], v[200:203], v[8:11]
	v_mfma_f32_16x16x32_f16 v[12:15], v[128:131], v[200:203], v[12:15]
	v_mfma_f32_16x16x32_f16 v[56:59], v[140:143], v[164:167], v[56:59]
	v_mfma_f32_16x16x32_f16 v[60:63], v[132:135], v[164:167], v[60:63]
	v_mfma_f32_16x16x32_f16 v[40:43], v[140:143], v[188:191], v[40:43]
	v_mfma_f32_16x16x32_f16 v[44:47], v[132:135], v[188:191], v[44:47]
	v_mfma_f32_16x16x32_f16 v[24:27], v[140:143], v[196:199], v[24:27]
	v_mfma_f32_16x16x32_f16 v[28:31], v[132:135], v[196:199], v[28:31]
	v_mfma_f32_16x16x32_f16 v[8:11], v[140:143], v[214:217], v[8:11]
	v_mfma_f32_16x16x32_f16 v[12:15], v[132:135], v[214:217], v[12:15]
	v_mfma_f32_16x16x32_f16 v[48:51], v[152:155], v[160:163], v[48:51]
	v_mfma_f32_16x16x32_f16 v[52:55], v[144:147], v[160:163], v[52:55]
	v_mfma_f32_16x16x32_f16 v[32:35], v[152:155], v[184:187], v[32:35]
	v_mfma_f32_16x16x32_f16 v[36:39], v[144:147], v[184:187], v[36:39]
	v_mfma_f32_16x16x32_f16 v[16:19], v[152:155], v[192:195], v[16:19]
	v_mfma_f32_16x16x32_f16 v[20:23], v[144:147], v[192:195], v[20:23]
	v_mfma_f32_16x16x32_f16 v[0:3], v[152:155], v[200:203], v[0:3]
	v_mfma_f32_16x16x32_f16 v[4:7], v[144:147], v[200:203], v[4:7]
	v_mfma_f32_16x16x32_f16 v[48:51], v[156:159], v[164:167], v[48:51]
	v_mfma_f32_16x16x32_f16 v[52:55], v[148:151], v[164:167], v[52:55]
	v_mfma_f32_16x16x32_f16 v[32:35], v[156:159], v[188:191], v[32:35]
	v_mfma_f32_16x16x32_f16 v[36:39], v[148:151], v[188:191], v[36:39]
	v_mfma_f32_16x16x32_f16 v[16:19], v[156:159], v[196:199], v[16:19]
	v_mfma_f32_16x16x32_f16 v[20:23], v[148:151], v[196:199], v[20:23]
	v_mfma_f32_16x16x32_f16 v[0:3], v[156:159], v[214:217], v[0:3]
	v_mfma_f32_16x16x32_f16 v[4:7], v[148:151], v[214:217], v[4:7]
	s_barrier
; #define PG8_STAGE(bufoff, gbase, voff) do { _Pragma("unroll") for (int _i = 0; _i < 2; ++_i) \
;         __builtin_amdgcn_global_load_lds((const unsigned*)((const char*)(gbase) + (voff)[_i]), (PG8_LAS unsigned*)(lds + (bufoff) + ldsw + _i * 8192), 16, 0, 0); } while (0)
; #define PG8_LDA(dst, b, h) do { _Pragma("unroll") for (int m = 0; m < 4; ++m) _Pragma("unroll") for (int k = 0; k < 2; ++k) dst[m][k] = *(const PG8_LAS bf16x8*)(lds + PG8_SA(b, h) + aoff + m * 2048 + k * 1024); } while (0)
; #define PG8_LDB(dst, b, h) do { _Pragma("unroll") for (int n = 0; n < 2; ++n) _Pragma("unroll") for (int k = 0; k < 2; ++k) dst[n][k] = *(const PG8_LAS bf16x8*)(lds + PG8_SB(b, h) + boff + n * 2048 + k * 1024); } while (0)
; #define PG8_MMA(ai, bj, At, Bt) do { __builtin_amdgcn_s_setprio(1); _Pragma("unroll") for (int m = 0; m < 4; ++m) _Pragma("unroll") for (int n = 0; n < 2; ++n) _Pragma("unroll") for (int k = 0; k < 2; ++k) \
;         acc[ai][bj][m][n] = __builtin_amdgcn_mfma_f32_16x16x32_f16(Bt[n][k], At[m][k], acc[ai][bj][m][n], 0, 0, 0); __builtin_amdgcn_s_setprio(0); } while (0)
; #define PG8_WAIT_V(n) asm volatile("s_waitcnt vmcnt(" #n ")" ::: "memory")
; #define PG8_WAIT_L(n) asm volatile("s_waitcnt lgkmcnt(" #n ")" ::: "memory")
; #define PG8_BAR __builtin_amdgcn_s_barrier()
; #define PG8_SCHED __builtin_amdgcn_sched_barrier(0)
; template <class Epi, class Sched, bool ALIGN_EPI = false, bool SP2 = false>
; __device__ __forceinline__ void gemm_phase(PG8_LAS unsigned char* lds, const Gemm g, const Sched& S, const Epi& E) {
;     ...
;             PG8_LDB(B0, 1, 0); PG8_LDB(B1, 1, 1); PG8_SCHED; PG8_LDA(At, 1, 0); PG8_STAGE(PG8_SA(0, 1), a2 + hstep, voffA);
;             PG8_WAIT_V(8); PG8_WAIT_L(0); PG8_BAR; PG8_MMA(0, 0, At, B0); PG8_MMA(0, 1, At, B1); PG8_BAR; PG8_SCHED;
;             PG8_LDA(At, 1, 1); PG8_STAGE(PG8_SB(1, 0), b3, voffB); PG8_STAGE(PG8_SB(1, 1), b3 + hstep, voffB); PG8_STAGE(PG8_SA(1, 0), a3, voffA);
;             PG8_WAIT_V(8); PG8_WAIT_L(0); PG8_BAR; PG8_MMA(1, 0, At, B0); PG8_MMA(1, 1, At, B1); PG8_BAR; PG8_SCHED;
;     ...
;         if constexpr (ALIGN_EPI) { if (wr == 0) PG8_BAR; }
	s_add_i32 s87, 0, 0x18000
	s_add_i32 s88, 0, 0x1c000
	v_add_u32_e32 v140, s87, v209
	v_add_u32_e32 v156, s88, v209
	ds_read_b128 v[128:131], v140
	ds_read_b128 v[132:135], v140 offset:1024
	ds_read_b128 v[136:139], v140 offset:2048
	ds_read_b128 v[140:143], v140 offset:3072
	ds_read_b128 v[144:147], v156
	ds_read_b128 v[148:151], v156 offset:1024
	ds_read_b128 v[152:155], v156 offset:2048
	ds_read_b128 v[156:159], v156 offset:3072
	s_add_u32 s44, s44, 0x200000
	s_addc_u32 s45, s45, 0
	s_mov_b32 m0, s63
	ds_read_b128 v[160:163], v213 offset:32768
	ds_read_b128 v[164:167], v213 offset:33792
	ds_read_b128 v[184:187], v213 offset:34816
	ds_read_b128 v[188:191], v213 offset:35840
	ds_read_b128 v[192:195], v213 offset:36864
	ds_read_b128 v[196:199], v213 offset:37888
	ds_read_b128 v[200:203], v213 offset:38912
	ds_read_b128 v[214:217], v213 offset:39936
	global_load_lds_dwordx4 v168, s[44:45]
	s_mov_b32 m0, s64
	s_nop 0
	global_load_lds_dwordx4 v172, s[44:45]
	s_waitcnt vmcnt(8)
	s_waitcnt lgkmcnt(0)
	s_barrier
	v_mfma_f32_16x16x32_f16 v[120:123], v[136:139], v[160:163], v[120:123]
	v_mfma_f32_16x16x32_f16 v[124:127], v[128:131], v[160:163], v[124:127]
	v_mfma_f32_16x16x32_f16 v[104:107], v[136:139], v[184:187], v[104:107]
	v_mfma_f32_16x16x32_f16 v[108:111], v[128:131], v[184:187], v[108:111]
	v_mfma_f32_16x16x32_f16 v[88:91], v[136:139], v[192:195], v[88:91]
	v_mfma_f32_16x16x32_f16 v[92:95], v[128:131], v[192:195], v[92:95]
	v_mfma_f32_16x16x32_f16 v[72:75], v[136:139], v[200:203], v[72:75]
	v_mfma_f32_16x16x32_f16 v[76:79], v[128:131], v[200:203], v[76:79]
	v_mfma_f32_16x16x32_f16 v[120:123], v[140:143], v[164:167], v[120:123]
	v_mfma_f32_16x16x32_f16 v[124:127], v[132:135], v[164:167], v[124:127]
	v_mfma_f32_16x16x32_f16 v[104:107], v[140:143], v[188:191], v[104:107]
	v_mfma_f32_16x16x32_f16 v[108:111], v[132:135], v[188:191], v[108:111]
	v_mfma_f32_16x16x32_f16 v[88:91], v[140:143], v[196:199], v[88:91]
	v_mfma_f32_16x16x32_f16 v[92:95], v[132:135], v[196:199], v[92:95]
	v_mfma_f32_16x16x32_f16 v[72:75], v[140:143], v[214:217], v[72:75]
	v_mfma_f32_16x16x32_f16 v[76:79], v[132:135], v[214:217], v[76:79]
	v_mfma_f32_16x16x32_f16 v[112:115], v[152:155], v[160:163], v[112:115]
	v_mfma_f32_16x16x32_f16 v[116:119], v[144:147], v[160:163], v[116:119]
	v_mfma_f32_16x16x32_f16 v[96:99], v[152:155], v[184:187], v[96:99]
	v_mfma_f32_16x16x32_f16 v[100:103], v[144:147], v[184:187], v[100:103]
	v_mfma_f32_16x16x32_f16 v[80:83], v[152:155], v[192:195], v[80:83]
	v_mfma_f32_16x16x32_f16 v[84:87], v[144:147], v[192:195], v[84:87]
	v_mfma_f32_16x16x32_f16 v[64:67], v[152:155], v[200:203], v[64:67]
	v_mfma_f32_16x16x32_f16 v[68:71], v[144:147], v[200:203], v[68:71]
	v_mfma_f32_16x16x32_f16 v[112:115], v[156:159], v[164:167], v[112:115]
	v_mfma_f32_16x16x32_f16 v[116:119], v[148:151], v[164:167], v[116:119]
	v_mfma_f32_16x16x32_f16 v[96:99], v[156:159], v[188:191], v[96:99]
	v_mfma_f32_16x16x32_f16 v[100:103], v[148:151], v[188:191], v[100:103]
	v_mfma_f32_16x16x32_f16 v[80:83], v[156:159], v[196:199], v[80:83]
	v_mfma_f32_16x16x32_f16 v[84:87], v[148:151], v[196:199], v[84:87]
	v_mfma_f32_16x16x32_f16 v[64:67], v[156:159], v[214:217], v[64:67]
	v_mfma_f32_16x16x32_f16 v[68:71], v[148:151], v[214:217], v[68:71]
	s_barrier
	s_add_i32 s44, s87, s61
	s_mov_b32 m0, s44
	ds_read_b128 v[160:163], v213 offset:49152
	ds_read_b128 v[164:167], v213 offset:50176
	ds_read_b128 v[184:187], v213 offset:51200
	ds_read_b128 v[188:191], v213 offset:52224
	ds_read_b128 v[192:195], v213 offset:53248
	ds_read_b128 v[196:199], v213 offset:54272
	ds_read_b128 v[200:203], v213 offset:55296
	ds_read_b128 v[214:217], v213 offset:56320
	global_load_lds_dwordx4 v170, s[98:99]
	s_add_i32 m0, s44, 0x2000
	s_add_u32 s42, s42, 0x200080
	s_addc_u32 s43, s43, 0
	s_add_i32 s44, s88, s61
	global_load_lds_dwordx4 v174, s[98:99]
	s_mov_b32 m0, s44
	s_nop 0
	global_load_lds_dwordx4 v170, s[42:43]
	s_add_i32 m0, s44, 0x2000
	s_nop 0
	global_load_lds_dwordx4 v174, s[42:43]
	s_mov_b32 m0, s66
	s_nop 0
	global_load_lds_dwordx4 v168, s[100:101]
	s_mov_b32 m0, s67
	s_nop 0
	global_load_lds_dwordx4 v172, s[100:101]
	s_waitcnt vmcnt(8)
	s_waitcnt lgkmcnt(0)
	s_barrier
	v_mfma_f32_16x16x32_f16 v[56:59], v[136:139], v[160:163], v[56:59]
	v_mfma_f32_16x16x32_f16 v[60:63], v[128:131], v[160:163], v[60:63]
	v_mfma_f32_16x16x32_f16 v[40:43], v[136:139], v[184:187], v[40:43]
	v_mfma_f32_16x16x32_f16 v[44:47], v[128:131], v[184:187], v[44:47]
	v_mfma_f32_16x16x32_f16 v[24:27], v[136:139], v[192:195], v[24:27]
	v_mfma_f32_16x16x32_f16 v[28:31], v[128:131], v[192:195], v[28:31]
	v_mfma_f32_16x16x32_f16 v[8:11], v[136:139], v[200:203], v[8:11]
	v_mfma_f32_16x16x32_f16 v[12:15], v[128:131], v[200:203], v[12:15]
	v_mfma_f32_16x16x32_f16 v[56:59], v[140:143], v[164:167], v[56:59]
	v_mfma_f32_16x16x32_f16 v[60:63], v[132:135], v[164:167], v[60:63]
	v_mfma_f32_16x16x32_f16 v[40:43], v[140:143], v[188:191], v[40:43]
	v_mfma_f32_16x16x32_f16 v[44:47], v[132:135], v[188:191], v[44:47]
	v_mfma_f32_16x16x32_f16 v[24:27], v[140:143], v[196:199], v[24:27]
	v_mfma_f32_16x16x32_f16 v[28:31], v[132:135], v[196:199], v[28:31]
	v_mfma_f32_16x16x32_f16 v[8:11], v[140:143], v[214:217], v[8:11]
	v_mfma_f32_16x16x32_f16 v[12:15], v[132:135], v[214:217], v[12:15]
	v_mfma_f32_16x16x32_f16 v[48:51], v[152:155], v[160:163], v[48:51]
	v_mfma_f32_16x16x32_f16 v[52:55], v[144:147], v[160:163], v[52:55]
	v_mfma_f32_16x16x32_f16 v[32:35], v[152:155], v[184:187], v[32:35]
	v_mfma_f32_16x16x32_f16 v[36:39], v[144:147], v[184:187], v[36:39]
	v_mfma_f32_16x16x32_f16 v[16:19], v[152:155], v[192:195], v[16:19]
	v_mfma_f32_16x16x32_f16 v[20:23], v[144:147], v[192:195], v[20:23]
	v_mfma_f32_16x16x32_f16 v[0:3], v[152:155], v[200:203], v[0:3]
	v_mfma_f32_16x16x32_f16 v[4:7], v[144:147], v[200:203], v[4:7]
	v_mfma_f32_16x16x32_f16 v[48:51], v[156:159], v[164:167], v[48:51]
	v_mfma_f32_16x16x32_f16 v[52:55], v[148:151], v[164:167], v[52:55]
	v_mfma_f32_16x16x32_f16 v[32:35], v[156:159], v[188:191], v[32:35]
	v_mfma_f32_16x16x32_f16 v[36:39], v[148:151], v[188:191], v[36:39]
	v_mfma_f32_16x16x32_f16 v[16:19], v[156:159], v[196:199], v[16:19]
	v_mfma_f32_16x16x32_f16 v[20:23], v[148:151], v[196:199], v[20:23]
	v_mfma_f32_16x16x32_f16 v[0:3], v[156:159], v[214:217], v[0:3]
	v_mfma_f32_16x16x32_f16 v[4:7], v[148:151], v[214:217], v[4:7]
	s_barrier
	s_add_i32 s86, s86, 2
	s_add_u32 s82, s82, 0x100
	s_addc_u32 s83, s83, 0
	s_add_u32 s40, s40, 0x100
	s_addc_u32 s41, s41, 0
	s_cmpk_gt_u32 s86, 0x7d
	s_cbranch_scc0 .LBB0_655
	s_and_b64 vcc, exec, s[20:21]
	s_cbranch_vccz .LBB0_658
	s_barrier

; #define PG8_STAGE(bufoff, gbase, voff) do { _Pragma("unroll") for (int _i = 0; _i < 2; ++_i) \
;         __builtin_amdgcn_global_load_lds((const unsigned*)((const char*)(gbase) + (voff)[_i]), (PG8_LAS unsigned*)(lds + (bufoff) + ldsw + _i * 8192), 16, 0, 0); } while (0)
; #define PG8_LDA(dst, b, h) do { _Pragma("unroll") for (int m = 0; m < 4; ++m) _Pragma("unroll") for (int k = 0; k < 2; ++k) dst[m][k] = *(const PG8_LAS bf16x8*)(lds + PG8_SA(b, h) + aoff + m * 2048 + k * 1024); } while (0)
; #define PG8_LDB(dst, b, h) do { _Pragma("unroll") for (int n = 0; n < 2; ++n) _Pragma("unroll") for (int k = 0; k < 2; ++k) dst[n][k] = *(const PG8_LAS bf16x8*)(lds + PG8_SB(b, h) + boff + n * 2048 + k * 1024); } while (0)
; #define PG8_MMA(ai, bj, At, Bt) do { __builtin_amdgcn_s_setprio(1); _Pragma("unroll") for (int m = 0; m < 4; ++m) _Pragma("unroll") for (int n = 0; n < 2; ++n) _Pragma("unroll") for (int k = 0; k < 2; ++k) \
;         acc[ai][bj][m][n] = __builtin_amdgcn_mfma_f32_16x16x32_f16(Bt[n][k], At[m][k], acc[ai][bj][m][n], 0, 0, 0); __builtin_amdgcn_s_setprio(0); } while (0)
; #define PG8_WAIT_V(n) asm volatile("s_waitcnt vmcnt(" #n ")" ::: "memory")
; #define PG8_WAIT_L(n) asm volatile("s_waitcnt lgkmcnt(" #n ")" ::: "memory")
; #define PG8_BAR __builtin_amdgcn_s_barrier()
; #define PG8_SCHED __builtin_amdgcn_sched_barrier(0)
; template <class Epi, class Sched, bool ALIGN_EPI = false, bool SP2 = false>
; __device__ __forceinline__ void gemm_phase(PG8_LAS unsigned char* lds, const Gemm g, const Sched& S, const Epi& E) {
;     ...
;             PG8_LDB(B0, 0, 0); PG8_LDB(B1, 0, 1); PG8_SCHED; PG8_LDA(At, 0, 0); PG8_STAGE(PG8_SA(1, 1), a1 + hstep, voffA);
;             PG8_WAIT_V(8); PG8_WAIT_L(0); PG8_BAR; PG8_MMA(0, 0, At, B0); PG8_MMA(0, 1, At, B1); PG8_BAR; PG8_SCHED;
;             PG8_LDA(At, 0, 1); PG8_STAGE(PG8_SB(0, 0), b2, voffB); PG8_STAGE(PG8_SB(0, 1), b2 + hstep, voffB); PG8_STAGE(PG8_SA(0, 0), a2, voffA);
;             PG8_WAIT_V(8); PG8_WAIT_L(0); PG8_BAR; PG8_MMA(1, 0, At, B0); PG8_MMA(1, 1, At, B1); PG8_BAR; PG8_SCHED;
.LBB0_747:
	ds_read_b128 v[128:131], v191
	ds_read_b128 v[132:135], v191 offset:1024
	ds_read_b128 v[136:139], v191 offset:2048
	ds_read_b128 v[140:143], v191 offset:3072
	ds_read_b128 v[144:147], v192
	ds_read_b128 v[148:151], v192 offset:1024
	ds_read_b128 v[152:155], v192 offset:2048
	ds_read_b128 v[156:159], v192 offset:3072
	s_add_u32 s48, s44, 0xfff80080
	s_addc_u32 s49, s45, -1
	s_cmp_eq_u32 s90, 28
	s_cselect_b32 s51, s37, s49
	s_cselect_b32 s50, s86, s48
	s_cselect_b32 s49, s35, s89
	s_cselect_b32 s48, s87, s88
	s_add_i32 m0, s43, 0xc000
	ds_read_b128 v[176:179], v193
	ds_read_b128 v[180:183], v193 offset:1024
	ds_read_b128 v[184:187], v193 offset:2048
	ds_read_b128 v[194:197], v193 offset:3072
	ds_read_b128 v[198:201], v193 offset:4096
	ds_read_b128 v[208:211], v193 offset:5120
	ds_read_b128 v[212:215], v193 offset:6144
	ds_read_b128 v[216:219], v193 offset:7168
	global_load_lds_dwordx4 v170, s[44:45]
	s_add_i32 m0, s43, 0xe000
	s_nop 0
	global_load_lds_dwordx4 v168, s[44:45]
	s_waitcnt vmcnt(8)
	s_waitcnt lgkmcnt(0)
	s_barrier
	v_mfma_f32_16x16x32_f16 v[120:123], v[136:139], v[176:179], v[120:123]
	v_mfma_f32_16x16x32_f16 v[124:127], v[128:131], v[176:179], v[124:127]
	v_mfma_f32_16x16x32_f16 v[104:107], v[136:139], v[184:187], v[104:107]
	v_mfma_f32_16x16x32_f16 v[112:115], v[128:131], v[184:187], v[112:115]
	v_mfma_f32_16x16x32_f16 v[88:91], v[136:139], v[198:201], v[88:91]
	v_mfma_f32_16x16x32_f16 v[96:99], v[128:131], v[198:201], v[96:99]
	v_mfma_f32_16x16x32_f16 v[72:75], v[136:139], v[212:215], v[72:75]
	v_mfma_f32_16x16x32_f16 v[80:83], v[128:131], v[212:215], v[80:83]
	v_mfma_f32_16x16x32_f16 v[120:123], v[140:143], v[180:183], v[120:123]
	v_mfma_f32_16x16x32_f16 v[124:127], v[132:135], v[180:183], v[124:127]
	v_mfma_f32_16x16x32_f16 v[104:107], v[140:143], v[194:197], v[104:107]
	v_mfma_f32_16x16x32_f16 v[112:115], v[132:135], v[194:197], v[112:115]
	v_mfma_f32_16x16x32_f16 v[88:91], v[140:143], v[208:211], v[88:91]
	v_mfma_f32_16x16x32_f16 v[96:99], v[132:135], v[208:211], v[96:99]
	v_mfma_f32_16x16x32_f16 v[72:75], v[140:143], v[216:219], v[72:75]
	v_mfma_f32_16x16x32_f16 v[80:83], v[132:135], v[216:219], v[80:83]
	v_mfma_f32_16x16x32_f16 v[108:111], v[152:155], v[176:179], v[108:111]
	v_mfma_f32_16x16x32_f16 v[116:119], v[144:147], v[176:179], v[116:119]
	v_mfma_f32_16x16x32_f16 v[92:95], v[152:155], v[184:187], v[92:95]
	v_mfma_f32_16x16x32_f16 v[100:103], v[144:147], v[184:187], v[100:103]
	v_mfma_f32_16x16x32_f16 v[76:79], v[152:155], v[198:201], v[76:79]
	v_mfma_f32_16x16x32_f16 v[84:87], v[144:147], v[198:201], v[84:87]
	v_mfma_f32_16x16x32_f16 v[64:67], v[152:155], v[212:215], v[64:67]
	v_mfma_f32_16x16x32_f16 v[68:71], v[144:147], v[212:215], v[68:71]
	v_mfma_f32_16x16x32_f16 v[108:111], v[156:159], v[180:183], v[108:111]
	v_mfma_f32_16x16x32_f16 v[116:119], v[148:151], v[180:183], v[116:119]
	v_mfma_f32_16x16x32_f16 v[92:95], v[156:159], v[194:197], v[92:95]
	v_mfma_f32_16x16x32_f16 v[100:103], v[148:151], v[194:197], v[100:103]
	v_mfma_f32_16x16x32_f16 v[76:79], v[156:159], v[208:211], v[76:79]
	v_mfma_f32_16x16x32_f16 v[84:87], v[148:151], v[208:211], v[84:87]
	v_mfma_f32_16x16x32_f16 v[64:67], v[156:159], v[216:219], v[64:67]
	v_mfma_f32_16x16x32_f16 v[68:71], v[148:151], v[216:219], v[68:71]
	s_barrier
	s_add_i32 s91, s68, s61
	s_add_u32 s98, s48, s18
	s_addc_u32 s99, s49, s19
	s_mov_b32 m0, s91
	ds_read_b128 v[176:179], v193 offset:16384
	ds_read_b128 v[180:183], v193 offset:17408
	ds_read_b128 v[184:187], v193 offset:18432
	ds_read_b128 v[194:197], v193 offset:19456
	ds_read_b128 v[198:201], v193 offset:20480
	ds_read_b128 v[208:211], v193 offset:21504
	ds_read_b128 v[212:215], v193 offset:22528
	ds_read_b128 v[216:219], v193 offset:23552
	global_load_lds_dwordx4 v162, s[48:49]
	s_add_i32 m0, s91, 0x2000
	s_add_u32 s92, s48, 0x80000
	s_addc_u32 s93, s49, 0
	s_add_i32 s91, s69, s61
	global_load_lds_dwordx4 v166, s[48:49]
	s_mov_b32 m0, s91
	s_nop 0
	global_load_lds_dwordx4 v162, s[92:93]
	s_add_i32 m0, s91, 0x2000
	s_nop 0
	global_load_lds_dwordx4 v166, s[92:93]
	s_add_u32 s100, s50, s18
	s_addc_u32 s101, s51, s19
	s_mov_b32 m0, s43
	s_nop 0
	global_load_lds_dwordx4 v160, s[50:51]
	s_mov_b32 m0, s62
	s_nop 0
	global_load_lds_dwordx4 v164, s[50:51]
	s_waitcnt vmcnt(8)
	s_waitcnt lgkmcnt(0)
	s_barrier
	v_mfma_f32_16x16x32_f16 v[56:59], v[136:139], v[176:179], v[56:59]
	v_mfma_f32_16x16x32_f16 v[60:63], v[128:131], v[176:179], v[60:63]
	v_mfma_f32_16x16x32_f16 v[44:47], v[136:139], v[184:187], v[44:47]
	v_mfma_f32_16x16x32_f16 v[52:55], v[128:131], v[184:187], v[52:55]
	v_mfma_f32_16x16x32_f16 v[28:31], v[136:139], v[198:201], v[28:31]
	v_mfma_f32_16x16x32_f16 v[36:39], v[128:131], v[198:201], v[36:39]
	v_mfma_f32_16x16x32_f16 v[12:15], v[136:139], v[212:215], v[12:15]
	v_mfma_f32_16x16x32_f16 v[20:23], v[128:131], v[212:215], v[20:23]
	v_mfma_f32_16x16x32_f16 v[56:59], v[140:143], v[180:183], v[56:59]
	v_mfma_f32_16x16x32_f16 v[60:63], v[132:135], v[180:183], v[60:63]
	v_mfma_f32_16x16x32_f16 v[44:47], v[140:143], v[194:197], v[44:47]
	v_mfma_f32_16x16x32_f16 v[52:55], v[132:135], v[194:197], v[52:55]
	v_mfma_f32_16x16x32_f16 v[28:31], v[140:143], v[208:211], v[28:31]
	v_mfma_f32_16x16x32_f16 v[36:39], v[132:135], v[208:211], v[36:39]
	v_mfma_f32_16x16x32_f16 v[12:15], v[140:143], v[216:219], v[12:15]
	v_mfma_f32_16x16x32_f16 v[20:23], v[132:135], v[216:219], v[20:23]
	v_mfma_f32_16x16x32_f16 v[40:43], v[152:155], v[176:179], v[40:43]
	v_mfma_f32_16x16x32_f16 v[48:51], v[144:147], v[176:179], v[48:51]
	v_mfma_f32_16x16x32_f16 v[24:27], v[152:155], v[184:187], v[24:27]
	v_mfma_f32_16x16x32_f16 v[32:35], v[144:147], v[184:187], v[32:35]
	v_mfma_f32_16x16x32_f16 v[8:11], v[152:155], v[198:201], v[8:11]
	v_mfma_f32_16x16x32_f16 v[16:19], v[144:147], v[198:201], v[16:19]
	v_mfma_f32_16x16x32_f16 v[0:3], v[152:155], v[212:215], v[0:3]
	v_mfma_f32_16x16x32_f16 v[4:7], v[144:147], v[212:215], v[4:7]
	v_mfma_f32_16x16x32_f16 v[40:43], v[156:159], v[180:183], v[40:43]
	v_mfma_f32_16x16x32_f16 v[48:51], v[148:151], v[180:183], v[48:51]
	v_mfma_f32_16x16x32_f16 v[24:27], v[156:159], v[194:197], v[24:27]
	v_mfma_f32_16x16x32_f16 v[32:35], v[148:151], v[194:197], v[32:35]
	v_mfma_f32_16x16x32_f16 v[8:11], v[156:159], v[208:211], v[8:11]
	v_mfma_f32_16x16x32_f16 v[16:19], v[148:151], v[208:211], v[16:19]
	v_mfma_f32_16x16x32_f16 v[0:3], v[156:159], v[216:219], v[0:3]
	v_mfma_f32_16x16x32_f16 v[4:7], v[148:151], v[216:219], v[4:7]
	s_barrier
; #define PG8_STAGE(bufoff, gbase, voff) do { _Pragma("unroll") for (int _i = 0; _i < 2; ++_i) \
;         __builtin_amdgcn_global_load_lds((const unsigned*)((const char*)(gbase) + (voff)[_i]), (PG8_LAS unsigned*)(lds + (bufoff) + ldsw + _i * 8192), 16, 0, 0); } while (0)
; #define PG8_LDA(dst, b, h) do { _Pragma("unroll") for (int m = 0; m < 4; ++m) _Pragma("unroll") for (int k = 0; k < 2; ++k) dst[m][k] = *(const PG8_LAS bf16x8*)(lds + PG8_SA(b, h) + aoff + m * 2048 + k * 1024); } while (0)
; #define PG8_LDB(dst, b, h) do { _Pragma("unroll") for (int n = 0; n < 2; ++n) _Pragma("unroll") for (int k = 0; k < 2; ++k) dst[n][k] = *(const PG8_LAS bf16x8*)(lds + PG8_SB(b, h) + boff + n * 2048 + k * 1024); } while (0)
; #define PG8_MMA(ai, bj, At, Bt) do { __builtin_amdgcn_s_setprio(1); _Pragma("unroll") for (int m = 0; m < 4; ++m) _Pragma("unroll") for (int n = 0; n < 2; ++n) _Pragma("unroll") for (int k = 0; k < 2; ++k) \
;         acc[ai][bj][m][n] = __builtin_amdgcn_mfma_f32_16x16x32_f16(Bt[n][k], At[m][k], acc[ai][bj][m][n], 0, 0, 0); __builtin_amdgcn_s_setprio(0); } while (0)
; #define PG8_WAIT_V(n) asm volatile("s_waitcnt vmcnt(" #n ")" ::: "memory")
; #define PG8_WAIT_L(n) asm volatile("s_waitcnt lgkmcnt(" #n ")" ::: "memory")
; #define PG8_BAR __builtin_amdgcn_s_barrier()
; #define PG8_SCHED __builtin_amdgcn_sched_barrier(0)
; template <class Epi, class Sched, bool ALIGN_EPI = false, bool SP2 = false>
; __device__ __forceinline__ void gemm_phase(PG8_LAS unsigned char* lds, const Gemm g, const Sched& S, const Epi& E) {
;     ...
;             PG8_LDB(B0, 1, 0); PG8_LDB(B1, 1, 1); PG8_SCHED; PG8_LDA(At, 1, 0); PG8_STAGE(PG8_SA(0, 1), a2 + hstep, voffA);
;             PG8_WAIT_V(8); PG8_WAIT_L(0); PG8_BAR; PG8_MMA(0, 0, At, B0); PG8_MMA(0, 1, At, B1); PG8_BAR; PG8_SCHED;
;             PG8_LDA(At, 1, 1); PG8_STAGE(PG8_SB(1, 0), b3, voffB); PG8_STAGE(PG8_SB(1, 1), b3 + hstep, voffB); PG8_STAGE(PG8_SA(1, 0), a3, voffA);
;             PG8_WAIT_V(8); PG8_WAIT_L(0); PG8_BAR; PG8_MMA(1, 0, At, B0); PG8_MMA(1, 1, At, B1); PG8_BAR; PG8_SCHED;
;     ...
;         if constexpr (ALIGN_EPI) { if (wr == 0) PG8_BAR; }
	s_add_i32 s91, 0, 0x18000
	s_add_i32 s92, 0, 0x1c000
	v_add_u32_e32 v140, s91, v189
	v_add_u32_e32 v156, s92, v189
	ds_read_b128 v[128:131], v140
	ds_read_b128 v[132:135], v140 offset:1024
	ds_read_b128 v[136:139], v140 offset:2048
	ds_read_b128 v[140:143], v140 offset:3072
	ds_read_b128 v[144:147], v156
	ds_read_b128 v[148:151], v156 offset:1024
	ds_read_b128 v[152:155], v156 offset:2048
	ds_read_b128 v[156:159], v156 offset:3072
	s_add_u32 s50, s50, 0x80000
	s_addc_u32 s51, s51, 0
	s_mov_b32 m0, s63
	ds_read_b128 v[176:179], v193 offset:32768
	ds_read_b128 v[180:183], v193 offset:33792
	ds_read_b128 v[184:187], v193 offset:34816
	ds_read_b128 v[194:197], v193 offset:35840
	ds_read_b128 v[198:201], v193 offset:36864
	ds_read_b128 v[208:211], v193 offset:37888
	ds_read_b128 v[212:215], v193 offset:38912
	ds_read_b128 v[216:219], v193 offset:39936
	global_load_lds_dwordx4 v160, s[50:51]
	s_mov_b32 m0, s64
	s_nop 0
	global_load_lds_dwordx4 v164, s[50:51]
	s_waitcnt vmcnt(8)
	s_waitcnt lgkmcnt(0)
	s_barrier
	v_mfma_f32_16x16x32_f16 v[120:123], v[136:139], v[176:179], v[120:123]
	v_mfma_f32_16x16x32_f16 v[124:127], v[128:131], v[176:179], v[124:127]
	v_mfma_f32_16x16x32_f16 v[104:107], v[136:139], v[184:187], v[104:107]
	v_mfma_f32_16x16x32_f16 v[112:115], v[128:131], v[184:187], v[112:115]
	v_mfma_f32_16x16x32_f16 v[88:91], v[136:139], v[198:201], v[88:91]
	v_mfma_f32_16x16x32_f16 v[96:99], v[128:131], v[198:201], v[96:99]
	v_mfma_f32_16x16x32_f16 v[72:75], v[136:139], v[212:215], v[72:75]
	v_mfma_f32_16x16x32_f16 v[80:83], v[128:131], v[212:215], v[80:83]
	v_mfma_f32_16x16x32_f16 v[120:123], v[140:143], v[180:183], v[120:123]
	v_mfma_f32_16x16x32_f16 v[124:127], v[132:135], v[180:183], v[124:127]
	v_mfma_f32_16x16x32_f16 v[104:107], v[140:143], v[194:197], v[104:107]
	v_mfma_f32_16x16x32_f16 v[112:115], v[132:135], v[194:197], v[112:115]
	v_mfma_f32_16x16x32_f16 v[88:91], v[140:143], v[208:211], v[88:91]
	v_mfma_f32_16x16x32_f16 v[96:99], v[132:135], v[208:211], v[96:99]
	v_mfma_f32_16x16x32_f16 v[72:75], v[140:143], v[216:219], v[72:75]
	v_mfma_f32_16x16x32_f16 v[80:83], v[132:135], v[216:219], v[80:83]
	v_mfma_f32_16x16x32_f16 v[108:111], v[152:155], v[176:179], v[108:111]
	v_mfma_f32_16x16x32_f16 v[116:119], v[144:147], v[176:179], v[116:119]
	v_mfma_f32_16x16x32_f16 v[92:95], v[152:155], v[184:187], v[92:95]
	v_mfma_f32_16x16x32_f16 v[100:103], v[144:147], v[184:187], v[100:103]
	v_mfma_f32_16x16x32_f16 v[76:79], v[152:155], v[198:201], v[76:79]
	v_mfma_f32_16x16x32_f16 v[84:87], v[144:147], v[198:201], v[84:87]
	v_mfma_f32_16x16x32_f16 v[64:67], v[152:155], v[212:215], v[64:67]
	v_mfma_f32_16x16x32_f16 v[68:71], v[144:147], v[212:215], v[68:71]
	v_mfma_f32_16x16x32_f16 v[108:111], v[156:159], v[180:183], v[108:111]
	v_mfma_f32_16x16x32_f16 v[116:119], v[148:151], v[180:183], v[116:119]
	v_mfma_f32_16x16x32_f16 v[92:95], v[156:159], v[194:197], v[92:95]
	v_mfma_f32_16x16x32_f16 v[100:103], v[148:151], v[194:197], v[100:103]
	v_mfma_f32_16x16x32_f16 v[76:79], v[156:159], v[208:211], v[76:79]
	v_mfma_f32_16x16x32_f16 v[84:87], v[148:151], v[208:211], v[84:87]
	v_mfma_f32_16x16x32_f16 v[64:67], v[156:159], v[216:219], v[64:67]
	v_mfma_f32_16x16x32_f16 v[68:71], v[148:151], v[216:219], v[68:71]
	s_barrier
	s_add_i32 s50, s91, s61
	s_mov_b32 m0, s50
	ds_read_b128 v[176:179], v193 offset:49152
	ds_read_b128 v[180:183], v193 offset:50176
	ds_read_b128 v[184:187], v193 offset:51200
	ds_read_b128 v[194:197], v193 offset:52224
	ds_read_b128 v[198:201], v193 offset:53248
	ds_read_b128 v[208:211], v193 offset:54272
	ds_read_b128 v[212:215], v193 offset:55296
	ds_read_b128 v[216:219], v193 offset:56320
	global_load_lds_dwordx4 v162, s[98:99]
	s_add_i32 m0, s50, 0x2000
	s_add_u32 s48, s48, 0x80080
	s_addc_u32 s49, s49, 0
	s_add_i32 s50, s92, s61
	global_load_lds_dwordx4 v166, s[98:99]
	s_mov_b32 m0, s50
	s_nop 0
	global_load_lds_dwordx4 v162, s[48:49]
	s_add_i32 m0, s50, 0x2000
	s_nop 0
	global_load_lds_dwordx4 v166, s[48:49]
	s_mov_b32 m0, s66
	s_nop 0
	global_load_lds_dwordx4 v160, s[100:101]
	s_mov_b32 m0, s67
	s_nop 0
	global_load_lds_dwordx4 v164, s[100:101]
	s_waitcnt vmcnt(8)
	s_waitcnt lgkmcnt(0)
	s_barrier
	v_mfma_f32_16x16x32_f16 v[56:59], v[136:139], v[176:179], v[56:59]
	v_mfma_f32_16x16x32_f16 v[60:63], v[128:131], v[176:179], v[60:63]
	v_mfma_f32_16x16x32_f16 v[44:47], v[136:139], v[184:187], v[44:47]
	v_mfma_f32_16x16x32_f16 v[52:55], v[128:131], v[184:187], v[52:55]
	v_mfma_f32_16x16x32_f16 v[28:31], v[136:139], v[198:201], v[28:31]
	v_mfma_f32_16x16x32_f16 v[36:39], v[128:131], v[198:201], v[36:39]
	v_mfma_f32_16x16x32_f16 v[12:15], v[136:139], v[212:215], v[12:15]
	v_mfma_f32_16x16x32_f16 v[20:23], v[128:131], v[212:215], v[20:23]
	v_mfma_f32_16x16x32_f16 v[56:59], v[140:143], v[180:183], v[56:59]
	v_mfma_f32_16x16x32_f16 v[60:63], v[132:135], v[180:183], v[60:63]
	v_mfma_f32_16x16x32_f16 v[44:47], v[140:143], v[194:197], v[44:47]
	v_mfma_f32_16x16x32_f16 v[52:55], v[132:135], v[194:197], v[52:55]
	v_mfma_f32_16x16x32_f16 v[28:31], v[140:143], v[208:211], v[28:31]
	v_mfma_f32_16x16x32_f16 v[36:39], v[132:135], v[208:211], v[36:39]
	v_mfma_f32_16x16x32_f16 v[12:15], v[140:143], v[216:219], v[12:15]
	v_mfma_f32_16x16x32_f16 v[20:23], v[132:135], v[216:219], v[20:23]
	v_mfma_f32_16x16x32_f16 v[40:43], v[152:155], v[176:179], v[40:43]
	v_mfma_f32_16x16x32_f16 v[48:51], v[144:147], v[176:179], v[48:51]
	v_mfma_f32_16x16x32_f16 v[24:27], v[152:155], v[184:187], v[24:27]
	v_mfma_f32_16x16x32_f16 v[32:35], v[144:147], v[184:187], v[32:35]
	v_mfma_f32_16x16x32_f16 v[8:11], v[152:155], v[198:201], v[8:11]
	v_mfma_f32_16x16x32_f16 v[16:19], v[144:147], v[198:201], v[16:19]
	v_mfma_f32_16x16x32_f16 v[0:3], v[152:155], v[212:215], v[0:3]
	v_mfma_f32_16x16x32_f16 v[4:7], v[144:147], v[212:215], v[4:7]
	v_mfma_f32_16x16x32_f16 v[40:43], v[156:159], v[180:183], v[40:43]
	v_mfma_f32_16x16x32_f16 v[48:51], v[148:151], v[180:183], v[48:51]
	v_mfma_f32_16x16x32_f16 v[24:27], v[156:159], v[194:197], v[24:27]
	v_mfma_f32_16x16x32_f16 v[32:35], v[148:151], v[194:197], v[32:35]
	v_mfma_f32_16x16x32_f16 v[8:11], v[156:159], v[208:211], v[8:11]
	v_mfma_f32_16x16x32_f16 v[16:19], v[148:151], v[208:211], v[16:19]
	v_mfma_f32_16x16x32_f16 v[0:3], v[156:159], v[216:219], v[0:3]
	v_mfma_f32_16x16x32_f16 v[4:7], v[148:151], v[216:219], v[4:7]
	s_barrier
	s_add_i32 s90, s90, 2
	s_add_u32 s88, s88, 0x100
	s_addc_u32 s89, s89, 0
	s_add_u32 s44, s44, 0x100
	s_addc_u32 s45, s45, 0
	s_cmp_gt_u32 s90, 29
	s_cbranch_scc0 .LBB0_747
	s_and_b64 vcc, exec, s[20:21]
	s_cbranch_vccz .LBB0_750
	s_barrier

; #define PG8_STAGE(bufoff, gbase, voff) do { _Pragma("unroll") for (int _i = 0; _i < 2; ++_i) \
;         __builtin_amdgcn_global_load_lds((const unsigned*)((const char*)(gbase) + (voff)[_i]), (PG8_LAS unsigned*)(lds + (bufoff) + ldsw + _i * 8192), 16, 0, 0); } while (0)
; #define PG8_LDA(dst, b, h) do { _Pragma("unroll") for (int m = 0; m < 4; ++m) _Pragma("unroll") for (int k = 0; k < 2; ++k) dst[m][k] = *(const PG8_LAS bf16x8*)(lds + PG8_SA(b, h) + aoff + m * 2048 + k * 1024); } while (0)
; #define PG8_LDB(dst, b, h) do { _Pragma("unroll") for (int n = 0; n < 2; ++n) _Pragma("unroll") for (int k = 0; k < 2; ++k) dst[n][k] = *(const PG8_LAS bf16x8*)(lds + PG8_SB(b, h) + boff + n * 2048 + k * 1024); } while (0)
; #define PG8_MMA(ai, bj, At, Bt) do { __builtin_amdgcn_s_setprio(1); _Pragma("unroll") for (int m = 0; m < 4; ++m) _Pragma("unroll") for (int n = 0; n < 2; ++n) _Pragma("unroll") for (int k = 0; k < 2; ++k) \
;         acc[ai][bj][m][n] = __builtin_amdgcn_mfma_f32_16x16x32_f16(Bt[n][k], At[m][k], acc[ai][bj][m][n], 0, 0, 0); __builtin_amdgcn_s_setprio(0); } while (0)
; #define PG8_WAIT_V(n) asm volatile("s_waitcnt vmcnt(" #n ")" ::: "memory")
; #define PG8_WAIT_L(n) asm volatile("s_waitcnt lgkmcnt(" #n ")" ::: "memory")
; #define PG8_BAR __builtin_amdgcn_s_barrier()
; #define PG8_SCHED __builtin_amdgcn_sched_barrier(0)
; template <class Epi, class Sched, bool ALIGN_EPI = false, bool SP2 = false>
; __device__ __forceinline__ void gemm_phase(PG8_LAS unsigned char* lds, const Gemm g, const Sched& S, const Epi& E) {
;     ...
;             PG8_LDB(B0, 0, 0); PG8_LDB(B1, 0, 1); PG8_SCHED; PG8_LDA(At, 0, 0); PG8_STAGE(PG8_SA(1, 1), a1 + hstep, voffA);
;             PG8_WAIT_V(8); PG8_WAIT_L(0); PG8_BAR; PG8_MMA(0, 0, At, B0); PG8_MMA(0, 1, At, B1); PG8_BAR; PG8_SCHED;
;             PG8_LDA(At, 0, 1); PG8_STAGE(PG8_SB(0, 0), b2, voffB); PG8_STAGE(PG8_SB(0, 1), b2 + hstep, voffB); PG8_STAGE(PG8_SA(0, 0), a2, voffA);
;             PG8_WAIT_V(8); PG8_WAIT_L(0); PG8_BAR; PG8_MMA(1, 0, At, B0); PG8_MMA(1, 1, At, B1); PG8_BAR; PG8_SCHED;
.LBB0_872:
	ds_read_b128 v[128:131], v187
	ds_read_b128 v[132:135], v187 offset:1024
	ds_read_b128 v[136:139], v187 offset:2048
	ds_read_b128 v[140:143], v187 offset:3072
	ds_read_b128 v[144:147], v188
	ds_read_b128 v[148:151], v188 offset:1024
	ds_read_b128 v[152:155], v188 offset:2048
	ds_read_b128 v[156:159], v188 offset:3072
	s_add_u32 s28, s26, 0xfffe0080
	s_addc_u32 s29, s27, -1
	s_cmp_eq_u32 s65, 4
	s_cselect_b32 s31, s21, s29
	s_cselect_b32 s30, s61, s28
	s_cselect_b32 s29, s19, s64
	s_cselect_b32 s28, s62, s63
	s_add_i32 m0, s39, 0xc000
	ds_read_b128 v[160:163], v189
	ds_read_b128 v[164:167], v189 offset:1024
	ds_read_b128 v[192:195], v189 offset:2048
	ds_read_b128 v[196:199], v189 offset:3072
	ds_read_b128 v[200:203], v189 offset:4096
	ds_read_b128 v[208:211], v189 offset:5120
	ds_read_b128 v[212:215], v189 offset:6144
	ds_read_b128 v[216:219], v189 offset:7168
	global_load_lds_dwordx4 v178, s[26:27]
	s_add_i32 m0, s39, 0xe000
	s_nop 0
	global_load_lds_dwordx4 v176, s[26:27]
	s_waitcnt vmcnt(8)
	s_waitcnt lgkmcnt(0)
	s_barrier
	v_mfma_f32_16x16x32_f16 v[120:123], v[136:139], v[160:163], v[120:123]
	v_mfma_f32_16x16x32_f16 v[124:127], v[128:131], v[160:163], v[124:127]
	v_mfma_f32_16x16x32_f16 v[104:107], v[136:139], v[192:195], v[104:107]
	v_mfma_f32_16x16x32_f16 v[108:111], v[128:131], v[192:195], v[108:111]
	v_mfma_f32_16x16x32_f16 v[88:91], v[136:139], v[200:203], v[88:91]
	v_mfma_f32_16x16x32_f16 v[92:95], v[128:131], v[200:203], v[92:95]
	v_mfma_f32_16x16x32_f16 v[72:75], v[136:139], v[212:215], v[72:75]
	v_mfma_f32_16x16x32_f16 v[76:79], v[128:131], v[212:215], v[76:79]
	v_mfma_f32_16x16x32_f16 v[120:123], v[140:143], v[164:167], v[120:123]
	v_mfma_f32_16x16x32_f16 v[124:127], v[132:135], v[164:167], v[124:127]
	v_mfma_f32_16x16x32_f16 v[104:107], v[140:143], v[196:199], v[104:107]
	v_mfma_f32_16x16x32_f16 v[108:111], v[132:135], v[196:199], v[108:111]
	v_mfma_f32_16x16x32_f16 v[88:91], v[140:143], v[208:211], v[88:91]
	v_mfma_f32_16x16x32_f16 v[92:95], v[132:135], v[208:211], v[92:95]
	v_mfma_f32_16x16x32_f16 v[72:75], v[140:143], v[216:219], v[72:75]
	v_mfma_f32_16x16x32_f16 v[76:79], v[132:135], v[216:219], v[76:79]
	v_mfma_f32_16x16x32_f16 v[112:115], v[152:155], v[160:163], v[112:115]
	v_mfma_f32_16x16x32_f16 v[116:119], v[144:147], v[160:163], v[116:119]
	v_mfma_f32_16x16x32_f16 v[96:99], v[152:155], v[192:195], v[96:99]
	v_mfma_f32_16x16x32_f16 v[100:103], v[144:147], v[192:195], v[100:103]
	v_mfma_f32_16x16x32_f16 v[80:83], v[152:155], v[200:203], v[80:83]
	v_mfma_f32_16x16x32_f16 v[84:87], v[144:147], v[200:203], v[84:87]
	v_mfma_f32_16x16x32_f16 v[64:67], v[152:155], v[212:215], v[64:67]
	v_mfma_f32_16x16x32_f16 v[68:71], v[144:147], v[212:215], v[68:71]
	v_mfma_f32_16x16x32_f16 v[112:115], v[156:159], v[164:167], v[112:115]
	v_mfma_f32_16x16x32_f16 v[116:119], v[148:151], v[164:167], v[116:119]
	v_mfma_f32_16x16x32_f16 v[96:99], v[156:159], v[196:199], v[96:99]
	v_mfma_f32_16x16x32_f16 v[100:103], v[148:151], v[196:199], v[100:103]
	v_mfma_f32_16x16x32_f16 v[80:83], v[156:159], v[208:211], v[80:83]
	v_mfma_f32_16x16x32_f16 v[84:87], v[148:151], v[208:211], v[84:87]
	v_mfma_f32_16x16x32_f16 v[64:67], v[156:159], v[216:219], v[64:67]
	v_mfma_f32_16x16x32_f16 v[68:71], v[148:151], v[216:219], v[68:71]
	s_barrier
	s_add_i32 s66, s49, s37
	s_add_u32 s98, s28, s14
	s_addc_u32 s99, s29, s15
	s_mov_b32 m0, s66
	ds_read_b128 v[160:163], v189 offset:16384
	ds_read_b128 v[164:167], v189 offset:17408
	ds_read_b128 v[192:195], v189 offset:18432
	ds_read_b128 v[196:199], v189 offset:19456
	ds_read_b128 v[200:203], v189 offset:20480
	ds_read_b128 v[208:211], v189 offset:21504
	ds_read_b128 v[212:215], v189 offset:22528
	ds_read_b128 v[216:219], v189 offset:23552
	global_load_lds_dwordx4 v170, s[28:29]
	s_add_i32 m0, s66, 0x2000
	s_add_u32 s66, s28, 0x20000
	s_addc_u32 s67, s29, 0
	s_add_i32 s68, s50, s37
	global_load_lds_dwordx4 v168, s[28:29]
	s_mov_b32 m0, s68
	s_nop 0
	global_load_lds_dwordx4 v170, s[66:67]
	s_add_i32 m0, s68, 0x2000
	s_nop 0
	global_load_lds_dwordx4 v168, s[66:67]
	s_add_u32 s100, s30, s14
	s_addc_u32 s101, s31, s15
	s_mov_b32 m0, s39
	s_nop 0
	global_load_lds_dwordx4 v170, s[30:31]
	s_mov_b32 m0, s40
	s_nop 0
	global_load_lds_dwordx4 v168, s[30:31]
	s_waitcnt vmcnt(8)
	s_waitcnt lgkmcnt(0)
	s_barrier
	v_mfma_f32_16x16x32_f16 v[56:59], v[136:139], v[160:163], v[56:59]
	v_mfma_f32_16x16x32_f16 v[60:63], v[128:131], v[160:163], v[60:63]
	v_mfma_f32_16x16x32_f16 v[40:43], v[136:139], v[192:195], v[40:43]
	v_mfma_f32_16x16x32_f16 v[44:47], v[128:131], v[192:195], v[44:47]
	v_mfma_f32_16x16x32_f16 v[24:27], v[136:139], v[200:203], v[24:27]
	v_mfma_f32_16x16x32_f16 v[28:31], v[128:131], v[200:203], v[28:31]
	v_mfma_f32_16x16x32_f16 v[8:11], v[136:139], v[212:215], v[8:11]
	v_mfma_f32_16x16x32_f16 v[12:15], v[128:131], v[212:215], v[12:15]
	v_mfma_f32_16x16x32_f16 v[56:59], v[140:143], v[164:167], v[56:59]
	v_mfma_f32_16x16x32_f16 v[60:63], v[132:135], v[164:167], v[60:63]
	v_mfma_f32_16x16x32_f16 v[40:43], v[140:143], v[196:199], v[40:43]
	v_mfma_f32_16x16x32_f16 v[44:47], v[132:135], v[196:199], v[44:47]
	v_mfma_f32_16x16x32_f16 v[24:27], v[140:143], v[208:211], v[24:27]
	v_mfma_f32_16x16x32_f16 v[28:31], v[132:135], v[208:211], v[28:31]
	v_mfma_f32_16x16x32_f16 v[8:11], v[140:143], v[216:219], v[8:11]
	v_mfma_f32_16x16x32_f16 v[12:15], v[132:135], v[216:219], v[12:15]
	v_mfma_f32_16x16x32_f16 v[48:51], v[152:155], v[160:163], v[48:51]
	v_mfma_f32_16x16x32_f16 v[52:55], v[144:147], v[160:163], v[52:55]
	v_mfma_f32_16x16x32_f16 v[32:35], v[152:155], v[192:195], v[32:35]
	v_mfma_f32_16x16x32_f16 v[36:39], v[144:147], v[192:195], v[36:39]
	v_mfma_f32_16x16x32_f16 v[16:19], v[152:155], v[200:203], v[16:19]
	v_mfma_f32_16x16x32_f16 v[20:23], v[144:147], v[200:203], v[20:23]
	v_mfma_f32_16x16x32_f16 v[0:3], v[152:155], v[212:215], v[0:3]
	v_mfma_f32_16x16x32_f16 v[4:7], v[144:147], v[212:215], v[4:7]
	v_mfma_f32_16x16x32_f16 v[48:51], v[156:159], v[164:167], v[48:51]
	v_mfma_f32_16x16x32_f16 v[52:55], v[148:151], v[164:167], v[52:55]
	v_mfma_f32_16x16x32_f16 v[32:35], v[156:159], v[196:199], v[32:35]
	v_mfma_f32_16x16x32_f16 v[36:39], v[148:151], v[196:199], v[36:39]
	v_mfma_f32_16x16x32_f16 v[16:19], v[156:159], v[208:211], v[16:19]
	v_mfma_f32_16x16x32_f16 v[20:23], v[148:151], v[208:211], v[20:23]
	v_mfma_f32_16x16x32_f16 v[0:3], v[156:159], v[216:219], v[0:3]
	v_mfma_f32_16x16x32_f16 v[4:7], v[148:151], v[216:219], v[4:7]
	s_barrier
; #define PG8_STAGE(bufoff, gbase, voff) do { _Pragma("unroll") for (int _i = 0; _i < 2; ++_i) \
;         __builtin_amdgcn_global_load_lds((const unsigned*)((const char*)(gbase) + (voff)[_i]), (PG8_LAS unsigned*)(lds + (bufoff) + ldsw + _i * 8192), 16, 0, 0); } while (0)
; #define PG8_LDA(dst, b, h) do { _Pragma("unroll") for (int m = 0; m < 4; ++m) _Pragma("unroll") for (int k = 0; k < 2; ++k) dst[m][k] = *(const PG8_LAS bf16x8*)(lds + PG8_SA(b, h) + aoff + m * 2048 + k * 1024); } while (0)
; #define PG8_LDB(dst, b, h) do { _Pragma("unroll") for (int n = 0; n < 2; ++n) _Pragma("unroll") for (int k = 0; k < 2; ++k) dst[n][k] = *(const PG8_LAS bf16x8*)(lds + PG8_SB(b, h) + boff + n * 2048 + k * 1024); } while (0)
; #define PG8_MMA(ai, bj, At, Bt) do { __builtin_amdgcn_s_setprio(1); _Pragma("unroll") for (int m = 0; m < 4; ++m) _Pragma("unroll") for (int n = 0; n < 2; ++n) _Pragma("unroll") for (int k = 0; k < 2; ++k) \
;         acc[ai][bj][m][n] = __builtin_amdgcn_mfma_f32_16x16x32_f16(Bt[n][k], At[m][k], acc[ai][bj][m][n], 0, 0, 0); __builtin_amdgcn_s_setprio(0); } while (0)
; #define PG8_WAIT_V(n) asm volatile("s_waitcnt vmcnt(" #n ")" ::: "memory")
; #define PG8_WAIT_L(n) asm volatile("s_waitcnt lgkmcnt(" #n ")" ::: "memory")
; #define PG8_BAR __builtin_amdgcn_s_barrier()
; #define PG8_SCHED __builtin_amdgcn_sched_barrier(0)
; template <class Epi, class Sched, bool ALIGN_EPI = false, bool SP2 = false>
; __device__ __forceinline__ void gemm_phase(PG8_LAS unsigned char* lds, const Gemm g, const Sched& S, const Epi& E) {
;     ...
;             PG8_LDB(B0, 1, 0); PG8_LDB(B1, 1, 1); PG8_SCHED; PG8_LDA(At, 1, 0); PG8_STAGE(PG8_SA(0, 1), a2 + hstep, voffA);
;             PG8_WAIT_V(8); PG8_WAIT_L(0); PG8_BAR; PG8_MMA(0, 0, At, B0); PG8_MMA(0, 1, At, B1); PG8_BAR; PG8_SCHED;
;             PG8_LDA(At, 1, 1); PG8_STAGE(PG8_SB(1, 0), b3, voffB); PG8_STAGE(PG8_SB(1, 1), b3 + hstep, voffB); PG8_STAGE(PG8_SA(1, 0), a3, voffA);
;             PG8_WAIT_V(8); PG8_WAIT_L(0); PG8_BAR; PG8_MMA(1, 0, At, B0); PG8_MMA(1, 1, At, B1); PG8_BAR; PG8_SCHED;
;     ...
;         if constexpr (ALIGN_EPI) { if (wr == 0) PG8_BAR; }
	s_add_i32 s66, 0, 0x18000
	s_add_i32 s67, 0, 0x1c000
	v_add_u32_e32 v140, s66, v186
	v_add_u32_e32 v156, s67, v186
	ds_read_b128 v[128:131], v140
	ds_read_b128 v[132:135], v140 offset:1024
	ds_read_b128 v[136:139], v140 offset:2048
	ds_read_b128 v[140:143], v140 offset:3072
	ds_read_b128 v[144:147], v156
	ds_read_b128 v[148:151], v156 offset:1024
	ds_read_b128 v[152:155], v156 offset:2048
	ds_read_b128 v[156:159], v156 offset:3072
	s_add_u32 s30, s30, 0x20000
	s_addc_u32 s31, s31, 0
	s_mov_b32 m0, s41
	ds_read_b128 v[160:163], v189 offset:32768
	ds_read_b128 v[164:167], v189 offset:33792
	ds_read_b128 v[192:195], v189 offset:34816
	ds_read_b128 v[196:199], v189 offset:35840
	ds_read_b128 v[200:203], v189 offset:36864
	ds_read_b128 v[208:211], v189 offset:37888
	ds_read_b128 v[212:215], v189 offset:38912
	ds_read_b128 v[216:219], v189 offset:39936
	global_load_lds_dwordx4 v170, s[30:31]
	s_mov_b32 m0, s42
	s_nop 0
	global_load_lds_dwordx4 v168, s[30:31]
	s_waitcnt vmcnt(8)
	s_waitcnt lgkmcnt(0)
	s_barrier
	v_mfma_f32_16x16x32_f16 v[120:123], v[136:139], v[160:163], v[120:123]
	v_mfma_f32_16x16x32_f16 v[124:127], v[128:131], v[160:163], v[124:127]
	v_mfma_f32_16x16x32_f16 v[104:107], v[136:139], v[192:195], v[104:107]
	v_mfma_f32_16x16x32_f16 v[108:111], v[128:131], v[192:195], v[108:111]
	v_mfma_f32_16x16x32_f16 v[88:91], v[136:139], v[200:203], v[88:91]
	v_mfma_f32_16x16x32_f16 v[92:95], v[128:131], v[200:203], v[92:95]
	v_mfma_f32_16x16x32_f16 v[72:75], v[136:139], v[212:215], v[72:75]
	v_mfma_f32_16x16x32_f16 v[76:79], v[128:131], v[212:215], v[76:79]
	v_mfma_f32_16x16x32_f16 v[120:123], v[140:143], v[164:167], v[120:123]
	v_mfma_f32_16x16x32_f16 v[124:127], v[132:135], v[164:167], v[124:127]
	v_mfma_f32_16x16x32_f16 v[104:107], v[140:143], v[196:199], v[104:107]
	v_mfma_f32_16x16x32_f16 v[108:111], v[132:135], v[196:199], v[108:111]
	v_mfma_f32_16x16x32_f16 v[88:91], v[140:143], v[208:211], v[88:91]
	v_mfma_f32_16x16x32_f16 v[92:95], v[132:135], v[208:211], v[92:95]
	v_mfma_f32_16x16x32_f16 v[72:75], v[140:143], v[216:219], v[72:75]
	v_mfma_f32_16x16x32_f16 v[76:79], v[132:135], v[216:219], v[76:79]
	v_mfma_f32_16x16x32_f16 v[112:115], v[152:155], v[160:163], v[112:115]
	v_mfma_f32_16x16x32_f16 v[116:119], v[144:147], v[160:163], v[116:119]
	v_mfma_f32_16x16x32_f16 v[96:99], v[152:155], v[192:195], v[96:99]
	v_mfma_f32_16x16x32_f16 v[100:103], v[144:147], v[192:195], v[100:103]
	v_mfma_f32_16x16x32_f16 v[80:83], v[152:155], v[200:203], v[80:83]
	v_mfma_f32_16x16x32_f16 v[84:87], v[144:147], v[200:203], v[84:87]
	v_mfma_f32_16x16x32_f16 v[64:67], v[152:155], v[212:215], v[64:67]
	v_mfma_f32_16x16x32_f16 v[68:71], v[144:147], v[212:215], v[68:71]
	v_mfma_f32_16x16x32_f16 v[112:115], v[156:159], v[164:167], v[112:115]
	v_mfma_f32_16x16x32_f16 v[116:119], v[148:151], v[164:167], v[116:119]
	v_mfma_f32_16x16x32_f16 v[96:99], v[156:159], v[196:199], v[96:99]
	v_mfma_f32_16x16x32_f16 v[100:103], v[148:151], v[196:199], v[100:103]
	v_mfma_f32_16x16x32_f16 v[80:83], v[156:159], v[208:211], v[80:83]
	v_mfma_f32_16x16x32_f16 v[84:87], v[148:151], v[208:211], v[84:87]
	v_mfma_f32_16x16x32_f16 v[64:67], v[156:159], v[216:219], v[64:67]
	v_mfma_f32_16x16x32_f16 v[68:71], v[148:151], v[216:219], v[68:71]
	s_barrier
	s_add_i32 s30, s66, s37
	s_mov_b32 m0, s30
	ds_read_b128 v[160:163], v189 offset:49152
	ds_read_b128 v[164:167], v189 offset:50176
	ds_read_b128 v[192:195], v189 offset:51200
	ds_read_b128 v[196:199], v189 offset:52224
	ds_read_b128 v[200:203], v189 offset:53248
	ds_read_b128 v[208:211], v189 offset:54272
	ds_read_b128 v[212:215], v189 offset:55296
	ds_read_b128 v[216:219], v189 offset:56320
	global_load_lds_dwordx4 v170, s[98:99]
	s_add_i32 m0, s30, 0x2000
	s_add_u32 s28, s28, 0x20080
	s_addc_u32 s29, s29, 0
	s_add_i32 s30, s67, s37
	global_load_lds_dwordx4 v168, s[98:99]
	s_mov_b32 m0, s30
	s_nop 0
	global_load_lds_dwordx4 v170, s[28:29]
	s_add_i32 m0, s30, 0x2000
	s_nop 0
	global_load_lds_dwordx4 v168, s[28:29]
	s_mov_b32 m0, s45
	s_nop 0
	global_load_lds_dwordx4 v170, s[100:101]
	s_mov_b32 m0, s48
	s_nop 0
	global_load_lds_dwordx4 v168, s[100:101]
	s_waitcnt vmcnt(8)
	s_waitcnt lgkmcnt(0)
	s_barrier
	v_mfma_f32_16x16x32_f16 v[56:59], v[136:139], v[160:163], v[56:59]
	v_mfma_f32_16x16x32_f16 v[60:63], v[128:131], v[160:163], v[60:63]
	v_mfma_f32_16x16x32_f16 v[40:43], v[136:139], v[192:195], v[40:43]
	v_mfma_f32_16x16x32_f16 v[44:47], v[128:131], v[192:195], v[44:47]
	v_mfma_f32_16x16x32_f16 v[24:27], v[136:139], v[200:203], v[24:27]
	v_mfma_f32_16x16x32_f16 v[28:31], v[128:131], v[200:203], v[28:31]
	v_mfma_f32_16x16x32_f16 v[8:11], v[136:139], v[212:215], v[8:11]
	v_mfma_f32_16x16x32_f16 v[12:15], v[128:131], v[212:215], v[12:15]
	v_mfma_f32_16x16x32_f16 v[56:59], v[140:143], v[164:167], v[56:59]
	v_mfma_f32_16x16x32_f16 v[60:63], v[132:135], v[164:167], v[60:63]
	v_mfma_f32_16x16x32_f16 v[40:43], v[140:143], v[196:199], v[40:43]
	v_mfma_f32_16x16x32_f16 v[44:47], v[132:135], v[196:199], v[44:47]
	v_mfma_f32_16x16x32_f16 v[24:27], v[140:143], v[208:211], v[24:27]
	v_mfma_f32_16x16x32_f16 v[28:31], v[132:135], v[208:211], v[28:31]
	v_mfma_f32_16x16x32_f16 v[8:11], v[140:143], v[216:219], v[8:11]
	v_mfma_f32_16x16x32_f16 v[12:15], v[132:135], v[216:219], v[12:15]
	v_mfma_f32_16x16x32_f16 v[48:51], v[152:155], v[160:163], v[48:51]
	v_mfma_f32_16x16x32_f16 v[52:55], v[144:147], v[160:163], v[52:55]
	v_mfma_f32_16x16x32_f16 v[32:35], v[152:155], v[192:195], v[32:35]
	v_mfma_f32_16x16x32_f16 v[36:39], v[144:147], v[192:195], v[36:39]
	v_mfma_f32_16x16x32_f16 v[16:19], v[152:155], v[200:203], v[16:19]
	v_mfma_f32_16x16x32_f16 v[20:23], v[144:147], v[200:203], v[20:23]
	v_mfma_f32_16x16x32_f16 v[0:3], v[152:155], v[212:215], v[0:3]
	v_mfma_f32_16x16x32_f16 v[4:7], v[144:147], v[212:215], v[4:7]
	v_mfma_f32_16x16x32_f16 v[48:51], v[156:159], v[164:167], v[48:51]
	v_mfma_f32_16x16x32_f16 v[52:55], v[148:151], v[164:167], v[52:55]
	v_mfma_f32_16x16x32_f16 v[32:35], v[156:159], v[196:199], v[32:35]
	v_mfma_f32_16x16x32_f16 v[36:39], v[148:151], v[196:199], v[36:39]
	v_mfma_f32_16x16x32_f16 v[16:19], v[156:159], v[208:211], v[16:19]
	v_mfma_f32_16x16x32_f16 v[20:23], v[148:151], v[208:211], v[20:23]
	v_mfma_f32_16x16x32_f16 v[0:3], v[156:159], v[216:219], v[0:3]
	v_mfma_f32_16x16x32_f16 v[4:7], v[148:151], v[216:219], v[4:7]
	s_barrier
	s_add_i32 s65, s65, 2
	s_add_u32 s63, s63, 0x100
	s_addc_u32 s64, s64, 0
	s_add_u32 s26, s26, 0x100
	s_addc_u32 s27, s27, 0
	s_cmp_gt_u32 s65, 5
	s_cbranch_scc0 .LBB0_872
	s_and_b64 vcc, exec, s[16:17]
	s_cbranch_vccz .LBB0_875
	s_barrier

; #define PG8_STAGE(bufoff, gbase, voff) do { _Pragma("unroll") for (int _i = 0; _i < 2; ++_i) \
;         __builtin_amdgcn_global_load_lds((const unsigned*)((const char*)(gbase) + (voff)[_i]), (PG8_LAS unsigned*)(lds + (bufoff) + ldsw + _i * 8192), 16, 0, 0); } while (0)
; #define PG8_LDA(dst, b, h) do { _Pragma("unroll") for (int m = 0; m < 4; ++m) _Pragma("unroll") for (int k = 0; k < 2; ++k) dst[m][k] = *(const PG8_LAS bf16x8*)(lds + PG8_SA(b, h) + aoff + m * 2048 + k * 1024); } while (0)
; #define PG8_LDB(dst, b, h) do { _Pragma("unroll") for (int n = 0; n < 2; ++n) _Pragma("unroll") for (int k = 0; k < 2; ++k) dst[n][k] = *(const PG8_LAS bf16x8*)(lds + PG8_SB(b, h) + boff + n * 2048 + k * 1024); } while (0)
; #define PG8_MMA(ai, bj, At, Bt) do { __builtin_amdgcn_s_setprio(1); _Pragma("unroll") for (int m = 0; m < 4; ++m) _Pragma("unroll") for (int n = 0; n < 2; ++n) _Pragma("unroll") for (int k = 0; k < 2; ++k) \
;         acc[ai][bj][m][n] = __builtin_amdgcn_mfma_f32_16x16x32_f16(Bt[n][k], At[m][k], acc[ai][bj][m][n], 0, 0, 0); __builtin_amdgcn_s_setprio(0); } while (0)
; #define PG8_WAIT_V(n) asm volatile("s_waitcnt vmcnt(" #n ")" ::: "memory")
; #define PG8_WAIT_L(n) asm volatile("s_waitcnt lgkmcnt(" #n ")" ::: "memory")
; #define PG8_BAR __builtin_amdgcn_s_barrier()
; #define PG8_SCHED __builtin_amdgcn_sched_barrier(0)
; template <class Epi, class Sched, bool ALIGN_EPI = false, bool SP2 = false>
; __device__ __forceinline__ void gemm_phase(PG8_LAS unsigned char* lds, const Gemm g, const Sched& S, const Epi& E) {
;     ...
;             PG8_LDB(B0, 0, 0); PG8_LDB(B1, 0, 1); PG8_SCHED; PG8_LDA(At, 0, 0); PG8_STAGE(PG8_SA(1, 1), a1 + hstep, voffA);
;             PG8_WAIT_V(8); PG8_WAIT_L(0); PG8_BAR; PG8_MMA(0, 0, At, B0); PG8_MMA(0, 1, At, B1); PG8_BAR; PG8_SCHED;
;             PG8_LDA(At, 0, 1); PG8_STAGE(PG8_SB(0, 0), b2, voffB); PG8_STAGE(PG8_SB(0, 1), b2 + hstep, voffB); PG8_STAGE(PG8_SA(0, 0), a2, voffA);
;             PG8_WAIT_V(8); PG8_WAIT_L(0); PG8_BAR; PG8_MMA(1, 0, At, B0); PG8_MMA(1, 1, At, B1); PG8_BAR; PG8_SCHED;
.LBB0_1075:
	ds_read_b128 v[128:131], v211
	ds_read_b128 v[132:135], v211 offset:1024
	ds_read_b128 v[136:139], v211 offset:2048
	ds_read_b128 v[140:143], v211 offset:3072
	ds_read_b128 v[144:147], v212
	ds_read_b128 v[148:151], v212 offset:1024
	ds_read_b128 v[152:155], v212 offset:2048
	ds_read_b128 v[156:159], v212 offset:3072
	s_add_u32 s42, s40, 0xfff80080
	s_addc_u32 s43, s41, -1
	s_cmp_eq_u32 s70, 28
	s_cselect_b32 s45, s29, s43
	s_cselect_b32 s44, s37, s42
	s_cselect_b32 s43, s27, s69
	s_cselect_b32 s42, s67, s68
	s_add_i32 m0, s39, 0xc000
	ds_read_b128 v[160:163], v213
	ds_read_b128 v[164:167], v213 offset:1024
	ds_read_b128 v[184:187], v213 offset:2048
	ds_read_b128 v[188:191], v213 offset:3072
	ds_read_b128 v[192:195], v213 offset:4096
	ds_read_b128 v[196:199], v213 offset:5120
	ds_read_b128 v[200:203], v213 offset:6144
	ds_read_b128 v[214:217], v213 offset:7168
	global_load_lds_dwordx4 v178, s[40:41]
	s_add_i32 m0, s39, 0xe000
	s_nop 0
	global_load_lds_dwordx4 v176, s[40:41]
	s_waitcnt vmcnt(8)
	s_waitcnt lgkmcnt(0)
	s_barrier
	v_mfma_f32_16x16x32_f16 v[120:123], v[136:139], v[160:163], v[120:123]
	v_mfma_f32_16x16x32_f16 v[124:127], v[128:131], v[160:163], v[124:127]
	v_mfma_f32_16x16x32_f16 v[104:107], v[136:139], v[184:187], v[104:107]
	v_mfma_f32_16x16x32_f16 v[108:111], v[128:131], v[184:187], v[108:111]
	v_mfma_f32_16x16x32_f16 v[88:91], v[136:139], v[192:195], v[88:91]
	v_mfma_f32_16x16x32_f16 v[92:95], v[128:131], v[192:195], v[92:95]
	v_mfma_f32_16x16x32_f16 v[72:75], v[136:139], v[200:203], v[72:75]
	v_mfma_f32_16x16x32_f16 v[76:79], v[128:131], v[200:203], v[76:79]
	v_mfma_f32_16x16x32_f16 v[120:123], v[140:143], v[164:167], v[120:123]
	v_mfma_f32_16x16x32_f16 v[124:127], v[132:135], v[164:167], v[124:127]
	v_mfma_f32_16x16x32_f16 v[104:107], v[140:143], v[188:191], v[104:107]
	v_mfma_f32_16x16x32_f16 v[108:111], v[132:135], v[188:191], v[108:111]
	v_mfma_f32_16x16x32_f16 v[88:91], v[140:143], v[196:199], v[88:91]
	v_mfma_f32_16x16x32_f16 v[92:95], v[132:135], v[196:199], v[92:95]
	v_mfma_f32_16x16x32_f16 v[72:75], v[140:143], v[214:217], v[72:75]
	v_mfma_f32_16x16x32_f16 v[76:79], v[132:135], v[214:217], v[76:79]
	v_mfma_f32_16x16x32_f16 v[112:115], v[152:155], v[160:163], v[112:115]
	v_mfma_f32_16x16x32_f16 v[116:119], v[144:147], v[160:163], v[116:119]
	v_mfma_f32_16x16x32_f16 v[96:99], v[152:155], v[184:187], v[96:99]
	v_mfma_f32_16x16x32_f16 v[100:103], v[144:147], v[184:187], v[100:103]
	v_mfma_f32_16x16x32_f16 v[80:83], v[152:155], v[192:195], v[80:83]
	v_mfma_f32_16x16x32_f16 v[84:87], v[144:147], v[192:195], v[84:87]
	v_mfma_f32_16x16x32_f16 v[64:67], v[152:155], v[200:203], v[64:67]
	v_mfma_f32_16x16x32_f16 v[68:71], v[144:147], v[200:203], v[68:71]
	v_mfma_f32_16x16x32_f16 v[112:115], v[156:159], v[164:167], v[112:115]
	v_mfma_f32_16x16x32_f16 v[116:119], v[148:151], v[164:167], v[116:119]
	v_mfma_f32_16x16x32_f16 v[96:99], v[156:159], v[188:191], v[96:99]
	v_mfma_f32_16x16x32_f16 v[100:103], v[148:151], v[188:191], v[100:103]
	v_mfma_f32_16x16x32_f16 v[80:83], v[156:159], v[196:199], v[80:83]
	v_mfma_f32_16x16x32_f16 v[84:87], v[148:151], v[196:199], v[84:87]
	v_mfma_f32_16x16x32_f16 v[64:67], v[156:159], v[214:217], v[64:67]
	v_mfma_f32_16x16x32_f16 v[68:71], v[148:151], v[214:217], v[68:71]
	s_barrier
	s_add_i32 s71, s64, s48
	s_add_u32 s98, s42, s18
	s_addc_u32 s99, s43, s19
	s_mov_b32 m0, s71
	ds_read_b128 v[160:163], v213 offset:16384
	ds_read_b128 v[164:167], v213 offset:17408
	ds_read_b128 v[184:187], v213 offset:18432
	ds_read_b128 v[188:191], v213 offset:19456
	ds_read_b128 v[192:195], v213 offset:20480
	ds_read_b128 v[196:199], v213 offset:21504
	ds_read_b128 v[200:203], v213 offset:22528
	ds_read_b128 v[214:217], v213 offset:23552
	global_load_lds_dwordx4 v170, s[42:43]
	s_add_i32 m0, s71, 0x2000
	s_add_u32 s72, s42, 0x80000
	s_addc_u32 s73, s43, 0
	s_add_i32 s71, s65, s48
	global_load_lds_dwordx4 v174, s[42:43]
	s_mov_b32 m0, s71
	s_nop 0
	global_load_lds_dwordx4 v170, s[72:73]
	s_add_i32 m0, s71, 0x2000
	s_nop 0
	global_load_lds_dwordx4 v174, s[72:73]
	s_add_u32 s100, s44, s18
	s_addc_u32 s101, s45, s19
	s_mov_b32 m0, s39
	s_nop 0
	global_load_lds_dwordx4 v168, s[44:45]
	s_mov_b32 m0, s49
	s_nop 0
	global_load_lds_dwordx4 v172, s[44:45]
	s_waitcnt vmcnt(8)
	s_waitcnt lgkmcnt(0)
	s_barrier
	v_mfma_f32_16x16x32_f16 v[56:59], v[136:139], v[160:163], v[56:59]
	v_mfma_f32_16x16x32_f16 v[60:63], v[128:131], v[160:163], v[60:63]
	v_mfma_f32_16x16x32_f16 v[40:43], v[136:139], v[184:187], v[40:43]
	v_mfma_f32_16x16x32_f16 v[44:47], v[128:131], v[184:187], v[44:47]
	v_mfma_f32_16x16x32_f16 v[24:27], v[136:139], v[192:195], v[24:27]
	v_mfma_f32_16x16x32_f16 v[28:31], v[128:131], v[192:195], v[28:31]
	v_mfma_f32_16x16x32_f16 v[8:11], v[136:139], v[200:203], v[8:11]
	v_mfma_f32_16x16x32_f16 v[12:15], v[128:131], v[200:203], v[12:15]
	v_mfma_f32_16x16x32_f16 v[56:59], v[140:143], v[164:167], v[56:59]
	v_mfma_f32_16x16x32_f16 v[60:63], v[132:135], v[164:167], v[60:63]
	v_mfma_f32_16x16x32_f16 v[40:43], v[140:143], v[188:191], v[40:43]
	v_mfma_f32_16x16x32_f16 v[44:47], v[132:135], v[188:191], v[44:47]
	v_mfma_f32_16x16x32_f16 v[24:27], v[140:143], v[196:199], v[24:27]
	v_mfma_f32_16x16x32_f16 v[28:31], v[132:135], v[196:199], v[28:31]
	v_mfma_f32_16x16x32_f16 v[8:11], v[140:143], v[214:217], v[8:11]
	v_mfma_f32_16x16x32_f16 v[12:15], v[132:135], v[214:217], v[12:15]
	v_mfma_f32_16x16x32_f16 v[48:51], v[152:155], v[160:163], v[48:51]
	v_mfma_f32_16x16x32_f16 v[52:55], v[144:147], v[160:163], v[52:55]
	v_mfma_f32_16x16x32_f16 v[32:35], v[152:155], v[184:187], v[32:35]
	v_mfma_f32_16x16x32_f16 v[36:39], v[144:147], v[184:187], v[36:39]
	v_mfma_f32_16x16x32_f16 v[16:19], v[152:155], v[192:195], v[16:19]
	v_mfma_f32_16x16x32_f16 v[20:23], v[144:147], v[192:195], v[20:23]
	v_mfma_f32_16x16x32_f16 v[0:3], v[152:155], v[200:203], v[0:3]
	v_mfma_f32_16x16x32_f16 v[4:7], v[144:147], v[200:203], v[4:7]
	v_mfma_f32_16x16x32_f16 v[48:51], v[156:159], v[164:167], v[48:51]
	v_mfma_f32_16x16x32_f16 v[52:55], v[148:151], v[164:167], v[52:55]
	v_mfma_f32_16x16x32_f16 v[32:35], v[156:159], v[188:191], v[32:35]
	v_mfma_f32_16x16x32_f16 v[36:39], v[148:151], v[188:191], v[36:39]
	v_mfma_f32_16x16x32_f16 v[16:19], v[156:159], v[196:199], v[16:19]
	v_mfma_f32_16x16x32_f16 v[20:23], v[148:151], v[196:199], v[20:23]
	v_mfma_f32_16x16x32_f16 v[0:3], v[156:159], v[214:217], v[0:3]
	v_mfma_f32_16x16x32_f16 v[4:7], v[148:151], v[214:217], v[4:7]
	s_barrier
; #define PG8_STAGE(bufoff, gbase, voff) do { _Pragma("unroll") for (int _i = 0; _i < 2; ++_i) \
;         __builtin_amdgcn_global_load_lds((const unsigned*)((const char*)(gbase) + (voff)[_i]), (PG8_LAS unsigned*)(lds + (bufoff) + ldsw + _i * 8192), 16, 0, 0); } while (0)
; #define PG8_LDA(dst, b, h) do { _Pragma("unroll") for (int m = 0; m < 4; ++m) _Pragma("unroll") for (int k = 0; k < 2; ++k) dst[m][k] = *(const PG8_LAS bf16x8*)(lds + PG8_SA(b, h) + aoff + m * 2048 + k * 1024); } while (0)
; #define PG8_LDB(dst, b, h) do { _Pragma("unroll") for (int n = 0; n < 2; ++n) _Pragma("unroll") for (int k = 0; k < 2; ++k) dst[n][k] = *(const PG8_LAS bf16x8*)(lds + PG8_SB(b, h) + boff + n * 2048 + k * 1024); } while (0)
; #define PG8_MMA(ai, bj, At, Bt) do { __builtin_amdgcn_s_setprio(1); _Pragma("unroll") for (int m = 0; m < 4; ++m) _Pragma("unroll") for (int n = 0; n < 2; ++n) _Pragma("unroll") for (int k = 0; k < 2; ++k) \
;         acc[ai][bj][m][n] = __builtin_amdgcn_mfma_f32_16x16x32_f16(Bt[n][k], At[m][k], acc[ai][bj][m][n], 0, 0, 0); __builtin_amdgcn_s_setprio(0); } while (0)
; #define PG8_WAIT_V(n) asm volatile("s_waitcnt vmcnt(" #n ")" ::: "memory")
; #define PG8_WAIT_L(n) asm volatile("s_waitcnt lgkmcnt(" #n ")" ::: "memory")
; #define PG8_BAR __builtin_amdgcn_s_barrier()
; #define PG8_SCHED __builtin_amdgcn_sched_barrier(0)
; template <class Epi, class Sched, bool ALIGN_EPI = false, bool SP2 = false>
; __device__ __forceinline__ void gemm_phase(PG8_LAS unsigned char* lds, const Gemm g, const Sched& S, const Epi& E) {
;     ...
;             PG8_LDB(B0, 1, 0); PG8_LDB(B1, 1, 1); PG8_SCHED; PG8_LDA(At, 1, 0); PG8_STAGE(PG8_SA(0, 1), a2 + hstep, voffA);
;             PG8_WAIT_V(8); PG8_WAIT_L(0); PG8_BAR; PG8_MMA(0, 0, At, B0); PG8_MMA(0, 1, At, B1); PG8_BAR; PG8_SCHED;
;             PG8_LDA(At, 1, 1); PG8_STAGE(PG8_SB(1, 0), b3, voffB); PG8_STAGE(PG8_SB(1, 1), b3 + hstep, voffB); PG8_STAGE(PG8_SA(1, 0), a3, voffA);
;             PG8_WAIT_V(8); PG8_WAIT_L(0); PG8_BAR; PG8_MMA(1, 0, At, B0); PG8_MMA(1, 1, At, B1); PG8_BAR; PG8_SCHED;
;     ...
;         if constexpr (ALIGN_EPI) { if (wr == 0) PG8_BAR; }
	s_add_i32 s71, 0, 0x18000
	s_add_i32 s72, 0, 0x1c000
	v_add_u32_e32 v140, s71, v209
	v_add_u32_e32 v156, s72, v209
	ds_read_b128 v[128:131], v140
	ds_read_b128 v[132:135], v140 offset:1024
	ds_read_b128 v[136:139], v140 offset:2048
	ds_read_b128 v[140:143], v140 offset:3072
	ds_read_b128 v[144:147], v156
	ds_read_b128 v[148:151], v156 offset:1024
	ds_read_b128 v[152:155], v156 offset:2048
	ds_read_b128 v[156:159], v156 offset:3072
	s_add_u32 s44, s44, 0x80000
	s_addc_u32 s45, s45, 0
	s_mov_b32 m0, s50
	ds_read_b128 v[160:163], v213 offset:32768
	ds_read_b128 v[164:167], v213 offset:33792
	ds_read_b128 v[184:187], v213 offset:34816
	ds_read_b128 v[188:191], v213 offset:35840
	ds_read_b128 v[192:195], v213 offset:36864
	ds_read_b128 v[196:199], v213 offset:37888
	ds_read_b128 v[200:203], v213 offset:38912
	ds_read_b128 v[214:217], v213 offset:39936
	global_load_lds_dwordx4 v168, s[44:45]
	s_mov_b32 m0, s51
	s_nop 0
	global_load_lds_dwordx4 v172, s[44:45]
	s_waitcnt vmcnt(8)
	s_waitcnt lgkmcnt(0)
	s_barrier
	v_mfma_f32_16x16x32_f16 v[120:123], v[136:139], v[160:163], v[120:123]
	v_mfma_f32_16x16x32_f16 v[124:127], v[128:131], v[160:163], v[124:127]
	v_mfma_f32_16x16x32_f16 v[104:107], v[136:139], v[184:187], v[104:107]
	v_mfma_f32_16x16x32_f16 v[108:111], v[128:131], v[184:187], v[108:111]
	v_mfma_f32_16x16x32_f16 v[88:91], v[136:139], v[192:195], v[88:91]
	v_mfma_f32_16x16x32_f16 v[92:95], v[128:131], v[192:195], v[92:95]
	v_mfma_f32_16x16x32_f16 v[72:75], v[136:139], v[200:203], v[72:75]
	v_mfma_f32_16x16x32_f16 v[76:79], v[128:131], v[200:203], v[76:79]
	v_mfma_f32_16x16x32_f16 v[120:123], v[140:143], v[164:167], v[120:123]
	v_mfma_f32_16x16x32_f16 v[124:127], v[132:135], v[164:167], v[124:127]
	v_mfma_f32_16x16x32_f16 v[104:107], v[140:143], v[188:191], v[104:107]
	v_mfma_f32_16x16x32_f16 v[108:111], v[132:135], v[188:191], v[108:111]
	v_mfma_f32_16x16x32_f16 v[88:91], v[140:143], v[196:199], v[88:91]
	v_mfma_f32_16x16x32_f16 v[92:95], v[132:135], v[196:199], v[92:95]
	v_mfma_f32_16x16x32_f16 v[72:75], v[140:143], v[214:217], v[72:75]
	v_mfma_f32_16x16x32_f16 v[76:79], v[132:135], v[214:217], v[76:79]
	v_mfma_f32_16x16x32_f16 v[112:115], v[152:155], v[160:163], v[112:115]
	v_mfma_f32_16x16x32_f16 v[116:119], v[144:147], v[160:163], v[116:119]
	v_mfma_f32_16x16x32_f16 v[96:99], v[152:155], v[184:187], v[96:99]
	v_mfma_f32_16x16x32_f16 v[100:103], v[144:147], v[184:187], v[100:103]
	v_mfma_f32_16x16x32_f16 v[80:83], v[152:155], v[192:195], v[80:83]
	v_mfma_f32_16x16x32_f16 v[84:87], v[144:147], v[192:195], v[84:87]
	v_mfma_f32_16x16x32_f16 v[64:67], v[152:155], v[200:203], v[64:67]
	v_mfma_f32_16x16x32_f16 v[68:71], v[144:147], v[200:203], v[68:71]
	v_mfma_f32_16x16x32_f16 v[112:115], v[156:159], v[164:167], v[112:115]
	v_mfma_f32_16x16x32_f16 v[116:119], v[148:151], v[164:167], v[116:119]
	v_mfma_f32_16x16x32_f16 v[96:99], v[156:159], v[188:191], v[96:99]
	v_mfma_f32_16x16x32_f16 v[100:103], v[148:151], v[188:191], v[100:103]
	v_mfma_f32_16x16x32_f16 v[80:83], v[156:159], v[196:199], v[80:83]
	v_mfma_f32_16x16x32_f16 v[84:87], v[148:151], v[196:199], v[84:87]
	v_mfma_f32_16x16x32_f16 v[64:67], v[156:159], v[214:217], v[64:67]
	v_mfma_f32_16x16x32_f16 v[68:71], v[148:151], v[214:217], v[68:71]
	s_barrier
	s_add_i32 s44, s71, s48
	s_mov_b32 m0, s44
	ds_read_b128 v[160:163], v213 offset:49152
	ds_read_b128 v[164:167], v213 offset:50176
	ds_read_b128 v[184:187], v213 offset:51200
	ds_read_b128 v[188:191], v213 offset:52224
	ds_read_b128 v[192:195], v213 offset:53248
	ds_read_b128 v[196:199], v213 offset:54272
	ds_read_b128 v[200:203], v213 offset:55296
	ds_read_b128 v[214:217], v213 offset:56320
	global_load_lds_dwordx4 v170, s[98:99]
	s_add_i32 m0, s44, 0x2000
	s_add_u32 s42, s42, 0x80080
	s_addc_u32 s43, s43, 0
	s_add_i32 s44, s72, s48
	global_load_lds_dwordx4 v174, s[98:99]
	s_mov_b32 m0, s44
	s_nop 0
	global_load_lds_dwordx4 v170, s[42:43]
	s_add_i32 m0, s44, 0x2000
	s_nop 0
	global_load_lds_dwordx4 v174, s[42:43]
	s_mov_b32 m0, s61
	s_nop 0
	global_load_lds_dwordx4 v168, s[100:101]
	s_mov_b32 m0, s62
	s_nop 0
	global_load_lds_dwordx4 v172, s[100:101]
	s_waitcnt vmcnt(8)
	s_waitcnt lgkmcnt(0)
	s_barrier
	v_mfma_f32_16x16x32_f16 v[56:59], v[136:139], v[160:163], v[56:59]
	v_mfma_f32_16x16x32_f16 v[60:63], v[128:131], v[160:163], v[60:63]
	v_mfma_f32_16x16x32_f16 v[40:43], v[136:139], v[184:187], v[40:43]
	v_mfma_f32_16x16x32_f16 v[44:47], v[128:131], v[184:187], v[44:47]
	v_mfma_f32_16x16x32_f16 v[24:27], v[136:139], v[192:195], v[24:27]
	v_mfma_f32_16x16x32_f16 v[28:31], v[128:131], v[192:195], v[28:31]
	v_mfma_f32_16x16x32_f16 v[8:11], v[136:139], v[200:203], v[8:11]
	v_mfma_f32_16x16x32_f16 v[12:15], v[128:131], v[200:203], v[12:15]
	v_mfma_f32_16x16x32_f16 v[56:59], v[140:143], v[164:167], v[56:59]
	v_mfma_f32_16x16x32_f16 v[60:63], v[132:135], v[164:167], v[60:63]
	v_mfma_f32_16x16x32_f16 v[40:43], v[140:143], v[188:191], v[40:43]
	v_mfma_f32_16x16x32_f16 v[44:47], v[132:135], v[188:191], v[44:47]
	v_mfma_f32_16x16x32_f16 v[24:27], v[140:143], v[196:199], v[24:27]
	v_mfma_f32_16x16x32_f16 v[28:31], v[132:135], v[196:199], v[28:31]
	v_mfma_f32_16x16x32_f16 v[8:11], v[140:143], v[214:217], v[8:11]
	v_mfma_f32_16x16x32_f16 v[12:15], v[132:135], v[214:217], v[12:15]
	v_mfma_f32_16x16x32_f16 v[48:51], v[152:155], v[160:163], v[48:51]
	v_mfma_f32_16x16x32_f16 v[52:55], v[144:147], v[160:163], v[52:55]
	v_mfma_f32_16x16x32_f16 v[32:35], v[152:155], v[184:187], v[32:35]
	v_mfma_f32_16x16x32_f16 v[36:39], v[144:147], v[184:187], v[36:39]
	v_mfma_f32_16x16x32_f16 v[16:19], v[152:155], v[192:195], v[16:19]
	v_mfma_f32_16x16x32_f16 v[20:23], v[144:147], v[192:195], v[20:23]
	v_mfma_f32_16x16x32_f16 v[0:3], v[152:155], v[200:203], v[0:3]
	v_mfma_f32_16x16x32_f16 v[4:7], v[144:147], v[200:203], v[4:7]
	v_mfma_f32_16x16x32_f16 v[48:51], v[156:159], v[164:167], v[48:51]
	v_mfma_f32_16x16x32_f16 v[52:55], v[148:151], v[164:167], v[52:55]
	v_mfma_f32_16x16x32_f16 v[32:35], v[156:159], v[188:191], v[32:35]
	v_mfma_f32_16x16x32_f16 v[36:39], v[148:151], v[188:191], v[36:39]
	v_mfma_f32_16x16x32_f16 v[16:19], v[156:159], v[196:199], v[16:19]
	v_mfma_f32_16x16x32_f16 v[20:23], v[148:151], v[196:199], v[20:23]
	v_mfma_f32_16x16x32_f16 v[0:3], v[156:159], v[214:217], v[0:3]
	v_mfma_f32_16x16x32_f16 v[4:7], v[148:151], v[214:217], v[4:7]
	s_barrier
	s_add_i32 s70, s70, 2
	s_add_u32 s68, s68, 0x100
	s_addc_u32 s69, s69, 0
	s_add_u32 s40, s40, 0x100
	s_addc_u32 s41, s41, 0
	s_cmp_gt_u32 s70, 29
	s_cbranch_scc0 .LBB0_1075
	s_and_b64 vcc, exec, s[20:21]
	s_cbranch_vccz .LBB0_1078
	s_barrier

; #define PG8_STAGE(bufoff, gbase, voff) do { _Pragma("unroll") for (int _i = 0; _i < 2; ++_i) \
;         __builtin_amdgcn_global_load_lds((const unsigned*)((const char*)(gbase) + (voff)[_i]), (PG8_LAS unsigned*)(lds + (bufoff) + ldsw + _i * 8192), 16, 0, 0); } while (0)
; #define PG8_LDA(dst, b, h) do { _Pragma("unroll") for (int m = 0; m < 4; ++m) _Pragma("unroll") for (int k = 0; k < 2; ++k) dst[m][k] = *(const PG8_LAS bf16x8*)(lds + PG8_SA(b, h) + aoff + m * 2048 + k * 1024); } while (0)
; #define PG8_LDB(dst, b, h) do { _Pragma("unroll") for (int n = 0; n < 2; ++n) _Pragma("unroll") for (int k = 0; k < 2; ++k) dst[n][k] = *(const PG8_LAS bf16x8*)(lds + PG8_SB(b, h) + boff + n * 2048 + k * 1024); } while (0)
; #define PG8_MMA(ai, bj, At, Bt) do { __builtin_amdgcn_s_setprio(1); _Pragma("unroll") for (int m = 0; m < 4; ++m) _Pragma("unroll") for (int n = 0; n < 2; ++n) _Pragma("unroll") for (int k = 0; k < 2; ++k) \
;         acc[ai][bj][m][n] = __builtin_amdgcn_mfma_f32_16x16x32_f16(Bt[n][k], At[m][k], acc[ai][bj][m][n], 0, 0, 0); __builtin_amdgcn_s_setprio(0); } while (0)
; #define PG8_WAIT_V(n) asm volatile("s_waitcnt vmcnt(" #n ")" ::: "memory")
; #define PG8_WAIT_L(n) asm volatile("s_waitcnt lgkmcnt(" #n ")" ::: "memory")
; #define PG8_BAR __builtin_amdgcn_s_barrier()
; #define PG8_SCHED __builtin_amdgcn_sched_barrier(0)
; template <class Epi, class Sched, bool ALIGN_EPI = false, bool SP2 = false>
; __device__ __forceinline__ void gemm_phase(PG8_LAS unsigned char* lds, const Gemm g, const Sched& S, const Epi& E) {
;     ...
;             PG8_LDB(B0, 0, 0); PG8_LDB(B1, 0, 1); PG8_SCHED; PG8_LDA(At, 0, 0); PG8_STAGE(PG8_SA(1, 1), a1 + hstep, voffA);
;             PG8_WAIT_V(8); PG8_WAIT_L(0); PG8_BAR; PG8_MMA(0, 0, At, B0); PG8_MMA(0, 1, At, B1); PG8_BAR; PG8_SCHED;
;             PG8_LDA(At, 0, 1); PG8_STAGE(PG8_SB(0, 0), b2, voffB); PG8_STAGE(PG8_SB(0, 1), b2 + hstep, voffB); PG8_STAGE(PG8_SA(0, 0), a2, voffA);
;             PG8_WAIT_V(8); PG8_WAIT_L(0); PG8_BAR; PG8_MMA(1, 0, At, B0); PG8_MMA(1, 1, At, B1); PG8_BAR; PG8_SCHED;
.LBB0_1167:
	ds_read_b128 v[128:131], v198
	ds_read_b128 v[132:135], v198 offset:1024
	ds_read_b128 v[136:139], v198 offset:2048
	ds_read_b128 v[140:143], v198 offset:3072
	ds_read_b128 v[144:147], v199
	ds_read_b128 v[148:151], v199 offset:1024
	ds_read_b128 v[152:155], v199 offset:2048
	ds_read_b128 v[156:159], v199 offset:3072
	s_add_u32 s44, s42, 0xfff80080
	s_addc_u32 s45, s43, -1
	s_cmp_eq_u32 s81, 28
	s_cselect_b32 s49, s35, s45
	s_cselect_b32 s48, s72, s44
	s_cselect_b32 s45, s31, s75
	s_cselect_b32 s44, s73, s74
	s_add_i32 m0, s41, 0xc000
	ds_read_b128 v[176:179], v200
	ds_read_b128 v[180:183], v200 offset:1024
	ds_read_b128 v[184:187], v200 offset:2048
	ds_read_b128 v[188:191], v200 offset:3072
	ds_read_b128 v[208:211], v200 offset:4096
	ds_read_b128 v[212:215], v200 offset:5120
	ds_read_b128 v[216:219], v200 offset:6144
	ds_read_b128 v[220:223], v200 offset:7168
	global_load_lds_dwordx4 v170, s[42:43]
	s_add_i32 m0, s41, 0xe000
	s_nop 0
	global_load_lds_dwordx4 v168, s[42:43]
	s_waitcnt vmcnt(8)
	s_waitcnt lgkmcnt(0)
	s_barrier
	v_mfma_f32_16x16x32_f16 v[120:123], v[136:139], v[176:179], v[120:123]
	v_mfma_f32_16x16x32_f16 v[124:127], v[128:131], v[176:179], v[124:127]
	v_mfma_f32_16x16x32_f16 v[104:107], v[136:139], v[184:187], v[104:107]
	v_mfma_f32_16x16x32_f16 v[108:111], v[128:131], v[184:187], v[108:111]
	v_mfma_f32_16x16x32_f16 v[88:91], v[136:139], v[208:211], v[88:91]
	v_mfma_f32_16x16x32_f16 v[92:95], v[128:131], v[208:211], v[92:95]
	v_mfma_f32_16x16x32_f16 v[72:75], v[136:139], v[216:219], v[72:75]
	v_mfma_f32_16x16x32_f16 v[76:79], v[128:131], v[216:219], v[76:79]
	v_mfma_f32_16x16x32_f16 v[120:123], v[140:143], v[180:183], v[120:123]
	v_mfma_f32_16x16x32_f16 v[124:127], v[132:135], v[180:183], v[124:127]
	v_mfma_f32_16x16x32_f16 v[104:107], v[140:143], v[188:191], v[104:107]
	v_mfma_f32_16x16x32_f16 v[108:111], v[132:135], v[188:191], v[108:111]
	v_mfma_f32_16x16x32_f16 v[88:91], v[140:143], v[212:215], v[88:91]
	v_mfma_f32_16x16x32_f16 v[92:95], v[132:135], v[212:215], v[92:95]
	v_mfma_f32_16x16x32_f16 v[72:75], v[140:143], v[220:223], v[72:75]
	v_mfma_f32_16x16x32_f16 v[76:79], v[132:135], v[220:223], v[76:79]
	v_mfma_f32_16x16x32_f16 v[112:115], v[152:155], v[176:179], v[112:115]
	v_mfma_f32_16x16x32_f16 v[116:119], v[144:147], v[176:179], v[116:119]
	v_mfma_f32_16x16x32_f16 v[96:99], v[152:155], v[184:187], v[96:99]
	v_mfma_f32_16x16x32_f16 v[100:103], v[144:147], v[184:187], v[100:103]
	v_mfma_f32_16x16x32_f16 v[80:83], v[152:155], v[208:211], v[80:83]
	v_mfma_f32_16x16x32_f16 v[84:87], v[144:147], v[208:211], v[84:87]
	v_mfma_f32_16x16x32_f16 v[64:67], v[152:155], v[216:219], v[64:67]
	v_mfma_f32_16x16x32_f16 v[68:71], v[144:147], v[216:219], v[68:71]
	v_mfma_f32_16x16x32_f16 v[112:115], v[156:159], v[180:183], v[112:115]
	v_mfma_f32_16x16x32_f16 v[116:119], v[148:151], v[180:183], v[116:119]
	v_mfma_f32_16x16x32_f16 v[96:99], v[156:159], v[188:191], v[96:99]
	v_mfma_f32_16x16x32_f16 v[100:103], v[148:151], v[188:191], v[100:103]
	v_mfma_f32_16x16x32_f16 v[80:83], v[156:159], v[212:215], v[80:83]
	v_mfma_f32_16x16x32_f16 v[84:87], v[148:151], v[212:215], v[84:87]
	v_mfma_f32_16x16x32_f16 v[64:67], v[156:159], v[220:223], v[64:67]
	v_mfma_f32_16x16x32_f16 v[68:71], v[148:151], v[220:223], v[68:71]
	s_barrier
	s_add_i32 s82, s65, s52
	s_add_u32 s98, s44, s16
	s_addc_u32 s99, s45, s17
	s_mov_b32 m0, s82
	ds_read_b128 v[176:179], v200 offset:16384
	ds_read_b128 v[180:183], v200 offset:17408
	ds_read_b128 v[184:187], v200 offset:18432
	ds_read_b128 v[188:191], v200 offset:19456
	ds_read_b128 v[208:211], v200 offset:20480
	ds_read_b128 v[212:215], v200 offset:21504
	ds_read_b128 v[216:219], v200 offset:22528
	ds_read_b128 v[220:223], v200 offset:23552
	global_load_lds_dwordx4 v162, s[44:45]
	s_add_i32 m0, s82, 0x2000
	s_add_u32 s82, s44, 0x80000
	s_addc_u32 s83, s45, 0
	s_add_i32 s86, s66, s52
	global_load_lds_dwordx4 v166, s[44:45]
	s_mov_b32 m0, s86
	s_nop 0
	global_load_lds_dwordx4 v162, s[82:83]
	s_add_i32 m0, s86, 0x2000
	s_nop 0
	global_load_lds_dwordx4 v166, s[82:83]
	s_add_u32 s100, s48, s16
	s_addc_u32 s101, s49, s17
	s_mov_b32 m0, s41
	s_nop 0
	global_load_lds_dwordx4 v160, s[48:49]
	s_mov_b32 m0, s53
	s_nop 0
	global_load_lds_dwordx4 v164, s[48:49]
	s_waitcnt vmcnt(8)
	s_waitcnt lgkmcnt(0)
	s_barrier
	v_mfma_f32_16x16x32_f16 v[56:59], v[136:139], v[176:179], v[56:59]
	v_mfma_f32_16x16x32_f16 v[60:63], v[128:131], v[176:179], v[60:63]
	v_mfma_f32_16x16x32_f16 v[40:43], v[136:139], v[184:187], v[40:43]
	v_mfma_f32_16x16x32_f16 v[44:47], v[128:131], v[184:187], v[44:47]
	v_mfma_f32_16x16x32_f16 v[24:27], v[136:139], v[208:211], v[24:27]
	v_mfma_f32_16x16x32_f16 v[28:31], v[128:131], v[208:211], v[28:31]
	v_mfma_f32_16x16x32_f16 v[8:11], v[136:139], v[216:219], v[8:11]
	v_mfma_f32_16x16x32_f16 v[12:15], v[128:131], v[216:219], v[12:15]
	v_mfma_f32_16x16x32_f16 v[56:59], v[140:143], v[180:183], v[56:59]
	v_mfma_f32_16x16x32_f16 v[60:63], v[132:135], v[180:183], v[60:63]
	v_mfma_f32_16x16x32_f16 v[40:43], v[140:143], v[188:191], v[40:43]
	v_mfma_f32_16x16x32_f16 v[44:47], v[132:135], v[188:191], v[44:47]
	v_mfma_f32_16x16x32_f16 v[24:27], v[140:143], v[212:215], v[24:27]
	v_mfma_f32_16x16x32_f16 v[28:31], v[132:135], v[212:215], v[28:31]
	v_mfma_f32_16x16x32_f16 v[8:11], v[140:143], v[220:223], v[8:11]
	v_mfma_f32_16x16x32_f16 v[12:15], v[132:135], v[220:223], v[12:15]
	v_mfma_f32_16x16x32_f16 v[48:51], v[152:155], v[176:179], v[48:51]
	v_mfma_f32_16x16x32_f16 v[52:55], v[144:147], v[176:179], v[52:55]
	v_mfma_f32_16x16x32_f16 v[32:35], v[152:155], v[184:187], v[32:35]
	v_mfma_f32_16x16x32_f16 v[36:39], v[144:147], v[184:187], v[36:39]
	v_mfma_f32_16x16x32_f16 v[16:19], v[152:155], v[208:211], v[16:19]
	v_mfma_f32_16x16x32_f16 v[20:23], v[144:147], v[208:211], v[20:23]
	v_mfma_f32_16x16x32_f16 v[0:3], v[152:155], v[216:219], v[0:3]
	v_mfma_f32_16x16x32_f16 v[4:7], v[144:147], v[216:219], v[4:7]
	v_mfma_f32_16x16x32_f16 v[48:51], v[156:159], v[180:183], v[48:51]
	v_mfma_f32_16x16x32_f16 v[52:55], v[148:151], v[180:183], v[52:55]
	v_mfma_f32_16x16x32_f16 v[32:35], v[156:159], v[188:191], v[32:35]
	v_mfma_f32_16x16x32_f16 v[36:39], v[148:151], v[188:191], v[36:39]
	v_mfma_f32_16x16x32_f16 v[16:19], v[156:159], v[212:215], v[16:19]
	v_mfma_f32_16x16x32_f16 v[20:23], v[148:151], v[212:215], v[20:23]
	v_mfma_f32_16x16x32_f16 v[0:3], v[156:159], v[220:223], v[0:3]
	v_mfma_f32_16x16x32_f16 v[4:7], v[148:151], v[220:223], v[4:7]
	s_barrier
; #define PG8_STAGE(bufoff, gbase, voff) do { _Pragma("unroll") for (int _i = 0; _i < 2; ++_i) \
;         __builtin_amdgcn_global_load_lds((const unsigned*)((const char*)(gbase) + (voff)[_i]), (PG8_LAS unsigned*)(lds + (bufoff) + ldsw + _i * 8192), 16, 0, 0); } while (0)
; #define PG8_LDA(dst, b, h) do { _Pragma("unroll") for (int m = 0; m < 4; ++m) _Pragma("unroll") for (int k = 0; k < 2; ++k) dst[m][k] = *(const PG8_LAS bf16x8*)(lds + PG8_SA(b, h) + aoff + m * 2048 + k * 1024); } while (0)
; #define PG8_LDB(dst, b, h) do { _Pragma("unroll") for (int n = 0; n < 2; ++n) _Pragma("unroll") for (int k = 0; k < 2; ++k) dst[n][k] = *(const PG8_LAS bf16x8*)(lds + PG8_SB(b, h) + boff + n * 2048 + k * 1024); } while (0)
; #define PG8_MMA(ai, bj, At, Bt) do { __builtin_amdgcn_s_setprio(1); _Pragma("unroll") for (int m = 0; m < 4; ++m) _Pragma("unroll") for (int n = 0; n < 2; ++n) _Pragma("unroll") for (int k = 0; k < 2; ++k) \
;         acc[ai][bj][m][n] = __builtin_amdgcn_mfma_f32_16x16x32_f16(Bt[n][k], At[m][k], acc[ai][bj][m][n], 0, 0, 0); __builtin_amdgcn_s_setprio(0); } while (0)
; #define PG8_WAIT_V(n) asm volatile("s_waitcnt vmcnt(" #n ")" ::: "memory")
; #define PG8_WAIT_L(n) asm volatile("s_waitcnt lgkmcnt(" #n ")" ::: "memory")
; #define PG8_BAR __builtin_amdgcn_s_barrier()
; #define PG8_SCHED __builtin_amdgcn_sched_barrier(0)
; template <class Epi, class Sched, bool ALIGN_EPI = false, bool SP2 = false>
; __device__ __forceinline__ void gemm_phase(PG8_LAS unsigned char* lds, const Gemm g, const Sched& S, const Epi& E) {
;     ...
;             PG8_LDB(B0, 1, 0); PG8_LDB(B1, 1, 1); PG8_SCHED; PG8_LDA(At, 1, 0); PG8_STAGE(PG8_SA(0, 1), a2 + hstep, voffA);
;             PG8_WAIT_V(8); PG8_WAIT_L(0); PG8_BAR; PG8_MMA(0, 0, At, B0); PG8_MMA(0, 1, At, B1); PG8_BAR; PG8_SCHED;
;             PG8_LDA(At, 1, 1); PG8_STAGE(PG8_SB(1, 0), b3, voffB); PG8_STAGE(PG8_SB(1, 1), b3 + hstep, voffB); PG8_STAGE(PG8_SA(1, 0), a3, voffA);
;             PG8_WAIT_V(8); PG8_WAIT_L(0); PG8_BAR; PG8_MMA(1, 0, At, B0); PG8_MMA(1, 1, At, B1); PG8_BAR; PG8_SCHED;
;     ...
;         if constexpr (ALIGN_EPI) { if (wr == 0) PG8_BAR; }
	s_add_i32 s82, 0, 0x18000
	s_add_i32 s83, 0, 0x1c000
	v_add_u32_e32 v140, s82, v196
	v_add_u32_e32 v156, s83, v196
	ds_read_b128 v[128:131], v140
	ds_read_b128 v[132:135], v140 offset:1024
	ds_read_b128 v[136:139], v140 offset:2048
	ds_read_b128 v[140:143], v140 offset:3072
	ds_read_b128 v[144:147], v156
	ds_read_b128 v[148:151], v156 offset:1024
	ds_read_b128 v[152:155], v156 offset:2048
	ds_read_b128 v[156:159], v156 offset:3072
	s_add_u32 s48, s48, 0x80000
	s_addc_u32 s49, s49, 0
	s_mov_b32 m0, s60
	ds_read_b128 v[176:179], v200 offset:32768
	ds_read_b128 v[180:183], v200 offset:33792
	ds_read_b128 v[184:187], v200 offset:34816
	ds_read_b128 v[188:191], v200 offset:35840
	ds_read_b128 v[208:211], v200 offset:36864
	ds_read_b128 v[212:215], v200 offset:37888
	ds_read_b128 v[216:219], v200 offset:38912
	ds_read_b128 v[220:223], v200 offset:39936
	global_load_lds_dwordx4 v160, s[48:49]
	s_mov_b32 m0, s61
	s_nop 0
	global_load_lds_dwordx4 v164, s[48:49]
	s_waitcnt vmcnt(8)
	s_waitcnt lgkmcnt(0)
	s_barrier
	v_mfma_f32_16x16x32_f16 v[120:123], v[136:139], v[176:179], v[120:123]
	v_mfma_f32_16x16x32_f16 v[124:127], v[128:131], v[176:179], v[124:127]
	v_mfma_f32_16x16x32_f16 v[104:107], v[136:139], v[184:187], v[104:107]
	v_mfma_f32_16x16x32_f16 v[108:111], v[128:131], v[184:187], v[108:111]
	v_mfma_f32_16x16x32_f16 v[88:91], v[136:139], v[208:211], v[88:91]
	v_mfma_f32_16x16x32_f16 v[92:95], v[128:131], v[208:211], v[92:95]
	v_mfma_f32_16x16x32_f16 v[72:75], v[136:139], v[216:219], v[72:75]
	v_mfma_f32_16x16x32_f16 v[76:79], v[128:131], v[216:219], v[76:79]
	v_mfma_f32_16x16x32_f16 v[120:123], v[140:143], v[180:183], v[120:123]
	v_mfma_f32_16x16x32_f16 v[124:127], v[132:135], v[180:183], v[124:127]
	v_mfma_f32_16x16x32_f16 v[104:107], v[140:143], v[188:191], v[104:107]
	v_mfma_f32_16x16x32_f16 v[108:111], v[132:135], v[188:191], v[108:111]
	v_mfma_f32_16x16x32_f16 v[88:91], v[140:143], v[212:215], v[88:91]
	v_mfma_f32_16x16x32_f16 v[92:95], v[132:135], v[212:215], v[92:95]
	v_mfma_f32_16x16x32_f16 v[72:75], v[140:143], v[220:223], v[72:75]
	v_mfma_f32_16x16x32_f16 v[76:79], v[132:135], v[220:223], v[76:79]
	v_mfma_f32_16x16x32_f16 v[112:115], v[152:155], v[176:179], v[112:115]
	v_mfma_f32_16x16x32_f16 v[116:119], v[144:147], v[176:179], v[116:119]
	v_mfma_f32_16x16x32_f16 v[96:99], v[152:155], v[184:187], v[96:99]
	v_mfma_f32_16x16x32_f16 v[100:103], v[144:147], v[184:187], v[100:103]
	v_mfma_f32_16x16x32_f16 v[80:83], v[152:155], v[208:211], v[80:83]
	v_mfma_f32_16x16x32_f16 v[84:87], v[144:147], v[208:211], v[84:87]
	v_mfma_f32_16x16x32_f16 v[64:67], v[152:155], v[216:219], v[64:67]
	v_mfma_f32_16x16x32_f16 v[68:71], v[144:147], v[216:219], v[68:71]
	v_mfma_f32_16x16x32_f16 v[112:115], v[156:159], v[180:183], v[112:115]
	v_mfma_f32_16x16x32_f16 v[116:119], v[148:151], v[180:183], v[116:119]
	v_mfma_f32_16x16x32_f16 v[96:99], v[156:159], v[188:191], v[96:99]
	v_mfma_f32_16x16x32_f16 v[100:103], v[148:151], v[188:191], v[100:103]
	v_mfma_f32_16x16x32_f16 v[80:83], v[156:159], v[212:215], v[80:83]
	v_mfma_f32_16x16x32_f16 v[84:87], v[148:151], v[212:215], v[84:87]
	v_mfma_f32_16x16x32_f16 v[64:67], v[156:159], v[220:223], v[64:67]
	v_mfma_f32_16x16x32_f16 v[68:71], v[148:151], v[220:223], v[68:71]
	s_barrier
	s_add_i32 s48, s82, s52
	s_mov_b32 m0, s48
	ds_read_b128 v[176:179], v200 offset:49152
	ds_read_b128 v[180:183], v200 offset:50176
	ds_read_b128 v[184:187], v200 offset:51200
	ds_read_b128 v[188:191], v200 offset:52224
	ds_read_b128 v[208:211], v200 offset:53248
	ds_read_b128 v[212:215], v200 offset:54272
	ds_read_b128 v[216:219], v200 offset:55296
	ds_read_b128 v[220:223], v200 offset:56320
	global_load_lds_dwordx4 v162, s[98:99]
	s_add_i32 m0, s48, 0x2000
	s_add_u32 s44, s44, 0x80080
	s_addc_u32 s45, s45, 0
	s_add_i32 s48, s83, s52
	global_load_lds_dwordx4 v166, s[98:99]
	s_mov_b32 m0, s48
	s_nop 0
	global_load_lds_dwordx4 v162, s[44:45]
	s_add_i32 m0, s48, 0x2000
	s_nop 0
	global_load_lds_dwordx4 v166, s[44:45]
	s_mov_b32 m0, s63
	s_nop 0
	global_load_lds_dwordx4 v160, s[100:101]
	s_mov_b32 m0, s64
	s_nop 0
	global_load_lds_dwordx4 v164, s[100:101]
	s_waitcnt vmcnt(8)
	s_waitcnt lgkmcnt(0)
	s_barrier
	v_mfma_f32_16x16x32_f16 v[56:59], v[136:139], v[176:179], v[56:59]
	v_mfma_f32_16x16x32_f16 v[60:63], v[128:131], v[176:179], v[60:63]
	v_mfma_f32_16x16x32_f16 v[40:43], v[136:139], v[184:187], v[40:43]
	v_mfma_f32_16x16x32_f16 v[44:47], v[128:131], v[184:187], v[44:47]
	v_mfma_f32_16x16x32_f16 v[24:27], v[136:139], v[208:211], v[24:27]
	v_mfma_f32_16x16x32_f16 v[28:31], v[128:131], v[208:211], v[28:31]
	v_mfma_f32_16x16x32_f16 v[8:11], v[136:139], v[216:219], v[8:11]
	v_mfma_f32_16x16x32_f16 v[12:15], v[128:131], v[216:219], v[12:15]
	v_mfma_f32_16x16x32_f16 v[56:59], v[140:143], v[180:183], v[56:59]
	v_mfma_f32_16x16x32_f16 v[60:63], v[132:135], v[180:183], v[60:63]
	v_mfma_f32_16x16x32_f16 v[40:43], v[140:143], v[188:191], v[40:43]
	v_mfma_f32_16x16x32_f16 v[44:47], v[132:135], v[188:191], v[44:47]
	v_mfma_f32_16x16x32_f16 v[24:27], v[140:143], v[212:215], v[24:27]
	v_mfma_f32_16x16x32_f16 v[28:31], v[132:135], v[212:215], v[28:31]
	v_mfma_f32_16x16x32_f16 v[8:11], v[140:143], v[220:223], v[8:11]
	v_mfma_f32_16x16x32_f16 v[12:15], v[132:135], v[220:223], v[12:15]
	v_mfma_f32_16x16x32_f16 v[48:51], v[152:155], v[176:179], v[48:51]
	v_mfma_f32_16x16x32_f16 v[52:55], v[144:147], v[176:179], v[52:55]
	v_mfma_f32_16x16x32_f16 v[32:35], v[152:155], v[184:187], v[32:35]
	v_mfma_f32_16x16x32_f16 v[36:39], v[144:147], v[184:187], v[36:39]
	v_mfma_f32_16x16x32_f16 v[16:19], v[152:155], v[208:211], v[16:19]
	v_mfma_f32_16x16x32_f16 v[20:23], v[144:147], v[208:211], v[20:23]
	v_mfma_f32_16x16x32_f16 v[0:3], v[152:155], v[216:219], v[0:3]
	v_mfma_f32_16x16x32_f16 v[4:7], v[144:147], v[216:219], v[4:7]
	v_mfma_f32_16x16x32_f16 v[48:51], v[156:159], v[180:183], v[48:51]
	v_mfma_f32_16x16x32_f16 v[52:55], v[148:151], v[180:183], v[52:55]
	v_mfma_f32_16x16x32_f16 v[32:35], v[156:159], v[188:191], v[32:35]
	v_mfma_f32_16x16x32_f16 v[36:39], v[148:151], v[188:191], v[36:39]
	v_mfma_f32_16x16x32_f16 v[16:19], v[156:159], v[212:215], v[16:19]
	v_mfma_f32_16x16x32_f16 v[20:23], v[148:151], v[212:215], v[20:23]
	v_mfma_f32_16x16x32_f16 v[0:3], v[156:159], v[220:223], v[0:3]
	v_mfma_f32_16x16x32_f16 v[4:7], v[148:151], v[220:223], v[4:7]
	s_barrier
	s_add_i32 s81, s81, 2
	s_add_u32 s74, s74, 0x100
	s_addc_u32 s75, s75, 0
	s_add_u32 s42, s42, 0x100
	s_addc_u32 s43, s43, 0
	s_cmp_gt_u32 s81, 29
	s_cbranch_scc0 .LBB0_1167
	s_and_b64 vcc, exec, s[18:19]
	s_cbranch_vccz .LBB0_1170
	s_barrier

; #define PG8_STAGE(bufoff, gbase, voff) do { _Pragma("unroll") for (int _i = 0; _i < 2; ++_i) \
;         __builtin_amdgcn_global_load_lds((const unsigned*)((const char*)(gbase) + (voff)[_i]), (PG8_LAS unsigned*)(lds + (bufoff) + ldsw + _i * 8192), 16, 0, 0); } while (0)
; #define PG8_LDA(dst, b, h) do { _Pragma("unroll") for (int m = 0; m < 4; ++m) _Pragma("unroll") for (int k = 0; k < 2; ++k) dst[m][k] = *(const PG8_LAS bf16x8*)(lds + PG8_SA(b, h) + aoff + m * 2048 + k * 1024); } while (0)
; #define PG8_LDB(dst, b, h) do { _Pragma("unroll") for (int n = 0; n < 2; ++n) _Pragma("unroll") for (int k = 0; k < 2; ++k) dst[n][k] = *(const PG8_LAS bf16x8*)(lds + PG8_SB(b, h) + boff + n * 2048 + k * 1024); } while (0)
; #define PG8_MMA(ai, bj, At, Bt) do { __builtin_amdgcn_s_setprio(1); _Pragma("unroll") for (int m = 0; m < 4; ++m) _Pragma("unroll") for (int n = 0; n < 2; ++n) _Pragma("unroll") for (int k = 0; k < 2; ++k) \
;         acc[ai][bj][m][n] = __builtin_amdgcn_mfma_f32_16x16x32_f16(Bt[n][k], At[m][k], acc[ai][bj][m][n], 0, 0, 0); __builtin_amdgcn_s_setprio(0); } while (0)
; #define PG8_WAIT_V(n) asm volatile("s_waitcnt vmcnt(" #n ")" ::: "memory")
; #define PG8_WAIT_L(n) asm volatile("s_waitcnt lgkmcnt(" #n ")" ::: "memory")
; #define PG8_BAR __builtin_amdgcn_s_barrier()
; #define PG8_SCHED __builtin_amdgcn_sched_barrier(0)
; template <class Epi, class Sched, bool ALIGN_EPI = false, bool SP2 = false>
; __device__ __forceinline__ void gemm_phase(PG8_LAS unsigned char* lds, const Gemm g, const Sched& S, const Epi& E) {
;     ...
;             PG8_LDB(B0, 0, 0); PG8_LDB(B1, 0, 1); PG8_SCHED; PG8_LDA(At, 0, 0); PG8_STAGE(PG8_SA(1, 1), a1 + hstep, voffA);
;             PG8_WAIT_V(8); PG8_WAIT_L(0); PG8_BAR; PG8_MMA(0, 0, At, B0); PG8_MMA(0, 1, At, B1); PG8_BAR; PG8_SCHED;
;             PG8_LDA(At, 0, 1); PG8_STAGE(PG8_SB(0, 0), b2, voffB); PG8_STAGE(PG8_SB(0, 1), b2 + hstep, voffB); PG8_STAGE(PG8_SA(0, 0), a2, voffA);
;             PG8_WAIT_V(8); PG8_WAIT_L(0); PG8_BAR; PG8_MMA(1, 0, At, B0); PG8_MMA(1, 1, At, B1); PG8_BAR; PG8_SCHED;
.LBB0_1243:
	ds_read_b128 v[128:131], v189
	ds_read_b128 v[132:135], v189 offset:1024
	ds_read_b128 v[136:139], v189 offset:2048
	ds_read_b128 v[140:143], v189 offset:3072
	ds_read_b128 v[144:147], v190
	ds_read_b128 v[148:151], v190 offset:1024
	ds_read_b128 v[152:155], v190 offset:2048
	ds_read_b128 v[156:159], v190 offset:3072
	s_add_u32 s34, s30, 0xffe00080
	s_addc_u32 s35, s31, -1
	s_cmpk_eq_i32 s61, 0x7c
	s_cselect_b32 s37, s23, s35
	s_cselect_b32 s36, s51, s34
	s_cselect_b32 s35, s21, s60
	s_cselect_b32 s34, s52, s53
	s_add_i32 m0, s29, 0xc000
	ds_read_b128 v[176:179], v191
	ds_read_b128 v[180:183], v191 offset:1024
	ds_read_b128 v[192:195], v191 offset:2048
	ds_read_b128 v[196:199], v191 offset:3072
	ds_read_b128 v[200:203], v191 offset:4096
	ds_read_b128 v[208:211], v191 offset:5120
	ds_read_b128 v[212:215], v191 offset:6144
	ds_read_b128 v[216:219], v191 offset:7168
	global_load_lds_dwordx4 v170, s[30:31]
	s_add_i32 m0, s29, 0xe000
	s_nop 0
	global_load_lds_dwordx4 v168, s[30:31]
	s_waitcnt vmcnt(8)
	s_waitcnt lgkmcnt(0)
	s_barrier
	v_mfma_f32_16x16x32_f16 v[120:123], v[136:139], v[176:179], v[120:123]
	v_mfma_f32_16x16x32_f16 v[124:127], v[128:131], v[176:179], v[124:127]
	v_mfma_f32_16x16x32_f16 v[104:107], v[136:139], v[192:195], v[104:107]
	v_mfma_f32_16x16x32_f16 v[108:111], v[128:131], v[192:195], v[108:111]
	v_mfma_f32_16x16x32_f16 v[88:91], v[136:139], v[200:203], v[88:91]
	v_mfma_f32_16x16x32_f16 v[92:95], v[128:131], v[200:203], v[92:95]
	v_mfma_f32_16x16x32_f16 v[72:75], v[136:139], v[212:215], v[72:75]
	v_mfma_f32_16x16x32_f16 v[76:79], v[128:131], v[212:215], v[76:79]
	v_mfma_f32_16x16x32_f16 v[120:123], v[140:143], v[180:183], v[120:123]
	v_mfma_f32_16x16x32_f16 v[124:127], v[132:135], v[180:183], v[124:127]
	v_mfma_f32_16x16x32_f16 v[104:107], v[140:143], v[196:199], v[104:107]
	v_mfma_f32_16x16x32_f16 v[108:111], v[132:135], v[196:199], v[108:111]
	v_mfma_f32_16x16x32_f16 v[88:91], v[140:143], v[208:211], v[88:91]
	v_mfma_f32_16x16x32_f16 v[92:95], v[132:135], v[208:211], v[92:95]
	v_mfma_f32_16x16x32_f16 v[72:75], v[140:143], v[216:219], v[72:75]
	v_mfma_f32_16x16x32_f16 v[76:79], v[132:135], v[216:219], v[76:79]
	v_mfma_f32_16x16x32_f16 v[112:115], v[152:155], v[176:179], v[112:115]
	v_mfma_f32_16x16x32_f16 v[116:119], v[144:147], v[176:179], v[116:119]
	v_mfma_f32_16x16x32_f16 v[96:99], v[152:155], v[192:195], v[96:99]
	v_mfma_f32_16x16x32_f16 v[100:103], v[144:147], v[192:195], v[100:103]
	v_mfma_f32_16x16x32_f16 v[80:83], v[152:155], v[200:203], v[80:83]
	v_mfma_f32_16x16x32_f16 v[84:87], v[144:147], v[200:203], v[84:87]
	v_mfma_f32_16x16x32_f16 v[64:67], v[152:155], v[212:215], v[64:67]
	v_mfma_f32_16x16x32_f16 v[68:71], v[144:147], v[212:215], v[68:71]
	v_mfma_f32_16x16x32_f16 v[112:115], v[156:159], v[180:183], v[112:115]
	v_mfma_f32_16x16x32_f16 v[116:119], v[148:151], v[180:183], v[116:119]
	v_mfma_f32_16x16x32_f16 v[96:99], v[156:159], v[196:199], v[96:99]
	v_mfma_f32_16x16x32_f16 v[100:103], v[148:151], v[196:199], v[100:103]
	v_mfma_f32_16x16x32_f16 v[80:83], v[156:159], v[208:211], v[80:83]
	v_mfma_f32_16x16x32_f16 v[84:87], v[148:151], v[208:211], v[84:87]
	v_mfma_f32_16x16x32_f16 v[64:67], v[156:159], v[216:219], v[64:67]
	v_mfma_f32_16x16x32_f16 v[68:71], v[148:151], v[216:219], v[68:71]
	s_barrier
	s_add_i32 s62, s48, s39
	s_add_u32 s98, s34, s12
	s_addc_u32 s99, s35, s13
	s_mov_b32 m0, s62
	ds_read_b128 v[176:179], v191 offset:16384
	ds_read_b128 v[180:183], v191 offset:17408
	ds_read_b128 v[192:195], v191 offset:18432
	ds_read_b128 v[196:199], v191 offset:19456
	ds_read_b128 v[200:203], v191 offset:20480
	ds_read_b128 v[208:211], v191 offset:21504
	ds_read_b128 v[212:215], v191 offset:22528
	ds_read_b128 v[216:219], v191 offset:23552
	global_load_lds_dwordx4 v162, s[34:35]
	s_add_i32 m0, s62, 0x2000
	s_add_u32 s62, s34, 0x200000
	s_addc_u32 s63, s35, 0
	s_add_i32 s64, s49, s39
	global_load_lds_dwordx4 v166, s[34:35]
	s_mov_b32 m0, s64
	s_nop 0
	global_load_lds_dwordx4 v162, s[62:63]
	s_add_i32 m0, s64, 0x2000
	s_nop 0
	global_load_lds_dwordx4 v166, s[62:63]
	s_add_u32 s100, s36, s12
	s_addc_u32 s101, s37, s13
	s_mov_b32 m0, s29
	s_nop 0
	global_load_lds_dwordx4 v160, s[36:37]
	s_mov_b32 m0, s40
	s_nop 0
	global_load_lds_dwordx4 v164, s[36:37]
	s_waitcnt vmcnt(8)
	s_waitcnt lgkmcnt(0)
	s_barrier
	v_mfma_f32_16x16x32_f16 v[56:59], v[136:139], v[176:179], v[56:59]
	v_mfma_f32_16x16x32_f16 v[60:63], v[128:131], v[176:179], v[60:63]
	v_mfma_f32_16x16x32_f16 v[40:43], v[136:139], v[192:195], v[40:43]
	v_mfma_f32_16x16x32_f16 v[44:47], v[128:131], v[192:195], v[44:47]
	v_mfma_f32_16x16x32_f16 v[24:27], v[136:139], v[200:203], v[24:27]
	v_mfma_f32_16x16x32_f16 v[28:31], v[128:131], v[200:203], v[28:31]
	v_mfma_f32_16x16x32_f16 v[8:11], v[136:139], v[212:215], v[8:11]
	v_mfma_f32_16x16x32_f16 v[12:15], v[128:131], v[212:215], v[12:15]
	v_mfma_f32_16x16x32_f16 v[56:59], v[140:143], v[180:183], v[56:59]
	v_mfma_f32_16x16x32_f16 v[60:63], v[132:135], v[180:183], v[60:63]
	v_mfma_f32_16x16x32_f16 v[40:43], v[140:143], v[196:199], v[40:43]
	v_mfma_f32_16x16x32_f16 v[44:47], v[132:135], v[196:199], v[44:47]
	v_mfma_f32_16x16x32_f16 v[24:27], v[140:143], v[208:211], v[24:27]
	v_mfma_f32_16x16x32_f16 v[28:31], v[132:135], v[208:211], v[28:31]
	v_mfma_f32_16x16x32_f16 v[8:11], v[140:143], v[216:219], v[8:11]
	v_mfma_f32_16x16x32_f16 v[12:15], v[132:135], v[216:219], v[12:15]
	v_mfma_f32_16x16x32_f16 v[48:51], v[152:155], v[176:179], v[48:51]
	v_mfma_f32_16x16x32_f16 v[52:55], v[144:147], v[176:179], v[52:55]
	v_mfma_f32_16x16x32_f16 v[32:35], v[152:155], v[192:195], v[32:35]
	v_mfma_f32_16x16x32_f16 v[36:39], v[144:147], v[192:195], v[36:39]
	v_mfma_f32_16x16x32_f16 v[16:19], v[152:155], v[200:203], v[16:19]
	v_mfma_f32_16x16x32_f16 v[20:23], v[144:147], v[200:203], v[20:23]
	v_mfma_f32_16x16x32_f16 v[0:3], v[152:155], v[212:215], v[0:3]
	v_mfma_f32_16x16x32_f16 v[4:7], v[144:147], v[212:215], v[4:7]
	v_mfma_f32_16x16x32_f16 v[48:51], v[156:159], v[180:183], v[48:51]
	v_mfma_f32_16x16x32_f16 v[52:55], v[148:151], v[180:183], v[52:55]
	v_mfma_f32_16x16x32_f16 v[32:35], v[156:159], v[196:199], v[32:35]
	v_mfma_f32_16x16x32_f16 v[36:39], v[148:151], v[196:199], v[36:39]
	v_mfma_f32_16x16x32_f16 v[16:19], v[156:159], v[208:211], v[16:19]
	v_mfma_f32_16x16x32_f16 v[20:23], v[148:151], v[208:211], v[20:23]
	v_mfma_f32_16x16x32_f16 v[0:3], v[156:159], v[216:219], v[0:3]
	v_mfma_f32_16x16x32_f16 v[4:7], v[148:151], v[216:219], v[4:7]
	s_barrier
; #define PG8_STAGE(bufoff, gbase, voff) do { _Pragma("unroll") for (int _i = 0; _i < 2; ++_i) \
;         __builtin_amdgcn_global_load_lds((const unsigned*)((const char*)(gbase) + (voff)[_i]), (PG8_LAS unsigned*)(lds + (bufoff) + ldsw + _i * 8192), 16, 0, 0); } while (0)
; #define PG8_LDA(dst, b, h) do { _Pragma("unroll") for (int m = 0; m < 4; ++m) _Pragma("unroll") for (int k = 0; k < 2; ++k) dst[m][k] = *(const PG8_LAS bf16x8*)(lds + PG8_SA(b, h) + aoff + m * 2048 + k * 1024); } while (0)
; #define PG8_LDB(dst, b, h) do { _Pragma("unroll") for (int n = 0; n < 2; ++n) _Pragma("unroll") for (int k = 0; k < 2; ++k) dst[n][k] = *(const PG8_LAS bf16x8*)(lds + PG8_SB(b, h) + boff + n * 2048 + k * 1024); } while (0)
; #define PG8_MMA(ai, bj, At, Bt) do { __builtin_amdgcn_s_setprio(1); _Pragma("unroll") for (int m = 0; m < 4; ++m) _Pragma("unroll") for (int n = 0; n < 2; ++n) _Pragma("unroll") for (int k = 0; k < 2; ++k) \
;         acc[ai][bj][m][n] = __builtin_amdgcn_mfma_f32_16x16x32_f16(Bt[n][k], At[m][k], acc[ai][bj][m][n], 0, 0, 0); __builtin_amdgcn_s_setprio(0); } while (0)
; #define PG8_WAIT_V(n) asm volatile("s_waitcnt vmcnt(" #n ")" ::: "memory")
; #define PG8_WAIT_L(n) asm volatile("s_waitcnt lgkmcnt(" #n ")" ::: "memory")
; #define PG8_BAR __builtin_amdgcn_s_barrier()
; #define PG8_SCHED __builtin_amdgcn_sched_barrier(0)
; template <class Epi, class Sched, bool ALIGN_EPI = false, bool SP2 = false>
; __device__ __forceinline__ void gemm_phase(PG8_LAS unsigned char* lds, const Gemm g, const Sched& S, const Epi& E) {
;     ...
;             PG8_LDB(B0, 1, 0); PG8_LDB(B1, 1, 1); PG8_SCHED; PG8_LDA(At, 1, 0); PG8_STAGE(PG8_SA(0, 1), a2 + hstep, voffA);
;             PG8_WAIT_V(8); PG8_WAIT_L(0); PG8_BAR; PG8_MMA(0, 0, At, B0); PG8_MMA(0, 1, At, B1); PG8_BAR; PG8_SCHED;
;             PG8_LDA(At, 1, 1); PG8_STAGE(PG8_SB(1, 0), b3, voffB); PG8_STAGE(PG8_SB(1, 1), b3 + hstep, voffB); PG8_STAGE(PG8_SA(1, 0), a3, voffA);
;             PG8_WAIT_V(8); PG8_WAIT_L(0); PG8_BAR; PG8_MMA(1, 0, At, B0); PG8_MMA(1, 1, At, B1); PG8_BAR; PG8_SCHED;
	s_add_i32 s62, 0, 0x18000
	s_add_i32 s63, 0, 0x1c000
	v_add_u32_e32 v140, s62, v187
	v_add_u32_e32 v156, s63, v187
	ds_read_b128 v[128:131], v140
	ds_read_b128 v[132:135], v140 offset:1024
	ds_read_b128 v[136:139], v140 offset:2048
	ds_read_b128 v[140:143], v140 offset:3072
	ds_read_b128 v[144:147], v156
	ds_read_b128 v[148:151], v156 offset:1024
	ds_read_b128 v[152:155], v156 offset:2048
	ds_read_b128 v[156:159], v156 offset:3072
	s_add_u32 s36, s36, 0x200000
	s_addc_u32 s37, s37, 0
	s_mov_b32 m0, s41
	ds_read_b128 v[176:179], v191 offset:32768
	ds_read_b128 v[180:183], v191 offset:33792
	ds_read_b128 v[192:195], v191 offset:34816
	ds_read_b128 v[196:199], v191 offset:35840
	ds_read_b128 v[200:203], v191 offset:36864
	ds_read_b128 v[208:211], v191 offset:37888
	ds_read_b128 v[212:215], v191 offset:38912
	ds_read_b128 v[216:219], v191 offset:39936
	global_load_lds_dwordx4 v160, s[36:37]
	s_mov_b32 m0, s42
	s_nop 0
	global_load_lds_dwordx4 v164, s[36:37]
	s_waitcnt vmcnt(8)
	s_waitcnt lgkmcnt(0)
	s_barrier
	v_mfma_f32_16x16x32_f16 v[120:123], v[136:139], v[176:179], v[120:123]
	v_mfma_f32_16x16x32_f16 v[124:127], v[128:131], v[176:179], v[124:127]
	v_mfma_f32_16x16x32_f16 v[104:107], v[136:139], v[192:195], v[104:107]
	v_mfma_f32_16x16x32_f16 v[108:111], v[128:131], v[192:195], v[108:111]
	v_mfma_f32_16x16x32_f16 v[88:91], v[136:139], v[200:203], v[88:91]
	v_mfma_f32_16x16x32_f16 v[92:95], v[128:131], v[200:203], v[92:95]
	v_mfma_f32_16x16x32_f16 v[72:75], v[136:139], v[212:215], v[72:75]
	v_mfma_f32_16x16x32_f16 v[76:79], v[128:131], v[212:215], v[76:79]
	v_mfma_f32_16x16x32_f16 v[120:123], v[140:143], v[180:183], v[120:123]
	v_mfma_f32_16x16x32_f16 v[124:127], v[132:135], v[180:183], v[124:127]
	v_mfma_f32_16x16x32_f16 v[104:107], v[140:143], v[196:199], v[104:107]
	v_mfma_f32_16x16x32_f16 v[108:111], v[132:135], v[196:199], v[108:111]
	v_mfma_f32_16x16x32_f16 v[88:91], v[140:143], v[208:211], v[88:91]
	v_mfma_f32_16x16x32_f16 v[92:95], v[132:135], v[208:211], v[92:95]
	v_mfma_f32_16x16x32_f16 v[72:75], v[140:143], v[216:219], v[72:75]
	v_mfma_f32_16x16x32_f16 v[76:79], v[132:135], v[216:219], v[76:79]
	v_mfma_f32_16x16x32_f16 v[112:115], v[152:155], v[176:179], v[112:115]
	v_mfma_f32_16x16x32_f16 v[116:119], v[144:147], v[176:179], v[116:119]
	v_mfma_f32_16x16x32_f16 v[96:99], v[152:155], v[192:195], v[96:99]
	v_mfma_f32_16x16x32_f16 v[100:103], v[144:147], v[192:195], v[100:103]
	v_mfma_f32_16x16x32_f16 v[80:83], v[152:155], v[200:203], v[80:83]
	v_mfma_f32_16x16x32_f16 v[84:87], v[144:147], v[200:203], v[84:87]
	v_mfma_f32_16x16x32_f16 v[64:67], v[152:155], v[212:215], v[64:67]
	v_mfma_f32_16x16x32_f16 v[68:71], v[144:147], v[212:215], v[68:71]
	v_mfma_f32_16x16x32_f16 v[112:115], v[156:159], v[180:183], v[112:115]
	v_mfma_f32_16x16x32_f16 v[116:119], v[148:151], v[180:183], v[116:119]
	v_mfma_f32_16x16x32_f16 v[96:99], v[156:159], v[196:199], v[96:99]
	v_mfma_f32_16x16x32_f16 v[100:103], v[148:151], v[196:199], v[100:103]
	v_mfma_f32_16x16x32_f16 v[80:83], v[156:159], v[208:211], v[80:83]
	v_mfma_f32_16x16x32_f16 v[84:87], v[148:151], v[208:211], v[84:87]
	v_mfma_f32_16x16x32_f16 v[64:67], v[156:159], v[216:219], v[64:67]
	v_mfma_f32_16x16x32_f16 v[68:71], v[148:151], v[216:219], v[68:71]
	s_barrier
	s_add_i32 s36, s62, s39
	s_mov_b32 m0, s36
	ds_read_b128 v[176:179], v191 offset:49152
	ds_read_b128 v[180:183], v191 offset:50176
	ds_read_b128 v[192:195], v191 offset:51200
	ds_read_b128 v[196:199], v191 offset:52224
	ds_read_b128 v[200:203], v191 offset:53248
	ds_read_b128 v[208:211], v191 offset:54272
	ds_read_b128 v[212:215], v191 offset:55296
	ds_read_b128 v[216:219], v191 offset:56320
	global_load_lds_dwordx4 v162, s[98:99]
	s_add_i32 m0, s36, 0x2000
	s_add_u32 s34, s34, 0x200080
	s_addc_u32 s35, s35, 0
	s_add_i32 s36, s63, s39
	global_load_lds_dwordx4 v166, s[98:99]
	s_mov_b32 m0, s36
	s_nop 0
	global_load_lds_dwordx4 v162, s[34:35]
	s_add_i32 m0, s36, 0x2000
	s_nop 0
	global_load_lds_dwordx4 v166, s[34:35]
	s_mov_b32 m0, s44
	s_nop 0
	global_load_lds_dwordx4 v160, s[100:101]
	s_mov_b32 m0, s45
	s_nop 0
	global_load_lds_dwordx4 v164, s[100:101]
	s_waitcnt vmcnt(8)
	s_waitcnt lgkmcnt(0)
	s_barrier
	v_mfma_f32_16x16x32_f16 v[56:59], v[136:139], v[176:179], v[56:59]
	v_mfma_f32_16x16x32_f16 v[60:63], v[128:131], v[176:179], v[60:63]
	v_mfma_f32_16x16x32_f16 v[40:43], v[136:139], v[192:195], v[40:43]
	v_mfma_f32_16x16x32_f16 v[44:47], v[128:131], v[192:195], v[44:47]
	v_mfma_f32_16x16x32_f16 v[24:27], v[136:139], v[200:203], v[24:27]
	v_mfma_f32_16x16x32_f16 v[28:31], v[128:131], v[200:203], v[28:31]
	v_mfma_f32_16x16x32_f16 v[8:11], v[136:139], v[212:215], v[8:11]
	v_mfma_f32_16x16x32_f16 v[12:15], v[128:131], v[212:215], v[12:15]
	v_mfma_f32_16x16x32_f16 v[56:59], v[140:143], v[180:183], v[56:59]
	v_mfma_f32_16x16x32_f16 v[60:63], v[132:135], v[180:183], v[60:63]
	v_mfma_f32_16x16x32_f16 v[40:43], v[140:143], v[196:199], v[40:43]
	v_mfma_f32_16x16x32_f16 v[44:47], v[132:135], v[196:199], v[44:47]
	v_mfma_f32_16x16x32_f16 v[24:27], v[140:143], v[208:211], v[24:27]
	v_mfma_f32_16x16x32_f16 v[28:31], v[132:135], v[208:211], v[28:31]
	v_mfma_f32_16x16x32_f16 v[8:11], v[140:143], v[216:219], v[8:11]
	v_mfma_f32_16x16x32_f16 v[12:15], v[132:135], v[216:219], v[12:15]
	v_mfma_f32_16x16x32_f16 v[48:51], v[152:155], v[176:179], v[48:51]
	v_mfma_f32_16x16x32_f16 v[52:55], v[144:147], v[176:179], v[52:55]
	v_mfma_f32_16x16x32_f16 v[32:35], v[152:155], v[192:195], v[32:35]
	v_mfma_f32_16x16x32_f16 v[36:39], v[144:147], v[192:195], v[36:39]
	v_mfma_f32_16x16x32_f16 v[16:19], v[152:155], v[200:203], v[16:19]
	v_mfma_f32_16x16x32_f16 v[20:23], v[144:147], v[200:203], v[20:23]
	v_mfma_f32_16x16x32_f16 v[0:3], v[152:155], v[212:215], v[0:3]
	v_mfma_f32_16x16x32_f16 v[4:7], v[144:147], v[212:215], v[4:7]
	v_mfma_f32_16x16x32_f16 v[48:51], v[156:159], v[180:183], v[48:51]
	v_mfma_f32_16x16x32_f16 v[52:55], v[148:151], v[180:183], v[52:55]
	v_mfma_f32_16x16x32_f16 v[32:35], v[156:159], v[196:199], v[32:35]
	v_mfma_f32_16x16x32_f16 v[36:39], v[148:151], v[196:199], v[36:39]
	v_mfma_f32_16x16x32_f16 v[16:19], v[156:159], v[208:211], v[16:19]
	v_mfma_f32_16x16x32_f16 v[20:23], v[148:151], v[208:211], v[20:23]
	v_mfma_f32_16x16x32_f16 v[0:3], v[156:159], v[216:219], v[0:3]
	v_mfma_f32_16x16x32_f16 v[4:7], v[148:151], v[216:219], v[4:7]
	s_barrier
	s_add_i32 s61, s61, 2
	s_add_u32 s53, s53, 0x100
	s_addc_u32 s60, s60, 0
	s_add_u32 s30, s30, 0x100
	s_addc_u32 s31, s31, 0
	s_cmpk_gt_u32 s61, 0x7d
	s_cbranch_scc0 .LBB0_1243
	s_and_b64 vcc, exec, s[14:15]
	s_cbranch_vccz .LBB0_1246
	s_barrier
